# K-loops: the 32 no-op s_setprio 0 / s_setprio 1 pairs in the middle of the MFMA blocks deleted (asm guide 6.3), on top of v45
# baseline (speedup 1.0000x reference)
; #define PG8_STAGE(bufoff, gbase, voff) do { _Pragma("unroll") for (int _i = 0; _i < 2; ++_i) \
;         __builtin_amdgcn_global_load_lds((const unsigned*)((const char*)(gbase) + (voff)[_i]), (PG8_LAS unsigned*)(lds + (bufoff) + ldsw + _i * 8192), 16, 0, 0); } while (0)
; #define PG8_LDA(dst, b, h) do { _Pragma("unroll") for (int m = 0; m < 4; ++m) _Pragma("unroll") for (int k = 0; k < 2; ++k) dst[m][k] = *(const PG8_LAS bf16x8*)(lds + PG8_SA(b, h) + aoff + m * 2048 + k * 1024); } while (0)
; #define PG8_LDB(dst, b, h) do { _Pragma("unroll") for (int n = 0; n < 2; ++n) _Pragma("unroll") for (int k = 0; k < 2; ++k) dst[n][k] = *(const PG8_LAS bf16x8*)(lds + PG8_SB(b, h) + boff + n * 2048 + k * 1024); } while (0)
; #define PG8_MMA(ai, bj, At, Bt) do { __builtin_amdgcn_s_setprio(1); _Pragma("unroll") for (int m = 0; m < 4; ++m) _Pragma("unroll") for (int n = 0; n < 2; ++n) _Pragma("unroll") for (int k = 0; k < 2; ++k) \
;         acc[ai][bj][m][n] = __builtin_amdgcn_mfma_f32_16x16x32_bf16(Bt[n][k], At[m][k], acc[ai][bj][m][n], 0, 0, 0); __builtin_amdgcn_s_setprio(0); } while (0)
; #define PG8_WAIT_V(n) asm volatile("s_waitcnt vmcnt(" #n ")" ::: "memory")
; #define PG8_WAIT_L(n) asm volatile("s_waitcnt lgkmcnt(" #n ")" ::: "memory")
; #define PG8_BAR __builtin_amdgcn_s_barrier()
; template <class Epi, class Sched, bool ALIGN_EPI = false, bool SP2 = false>
; __device__ __forceinline__ void gemm_phase(PG8_LAS unsigned char* lds, const Gemm g, const Sched& S, const Epi& E) {
;     ...
;         const bool has_next = S.next(ui + 1, nxt);
;         const char* nA = has_next ? (const char*)g.A + (size_t)nxt.pm * tstep : cA; const char* nB = has_next ? (const char*)g.Bt + (size_t)nxt.pn * tstep : cB;
;         for (int t = 0; t < nt; t += 2) {
;             const bool last = (t == nt - 2);
;             const char* a1 = cA + (size_t)(t + 1) * kstep;
;             const char* a2 = last ? nA : cA + (size_t)(t + 2) * kstep; const char* b2 = last ? nB : cB + (size_t)(t + 2) * kstep;
;             const char* a3 = a2 + kstep; const char* b3 = b2 + kstep;
;             if (last && has_next) S.a_ready(nxt);
;             if constexpr (SP2) {
;             PG8_LDB(B0, 0, 0); PG8_LDB(B1, 0, 1); PG8_SCHED; PG8_LDA(At, 0, 0); PG8_STAGE(PG8_SA(1, 1), a1 + hstep, voffA);
;             PG8_WAIT_V(8); PG8_WAIT_L(0); PG8_BAR; PG8_MMA(0, 0, At, B0); PG8_MMA(0, 1, At, B1); PG8_BAR; PG8_SCHED;
.LBB0_151:
	s_ashr_i32 s83, s82, 31
	s_lshl_b64 s[10:11], s[82:83], 19
	s_add_u32 s84, s0, s10
	s_addc_u32 s85, s1, s11
	s_and_b64 s[10:11], s[4:5], exec
	s_cselect_b32 s10, s85, s7
	s_cselect_b32 s11, s84, s6
	s_ashr_i32 s81, s80, 31
	s_lshl_b64 s[14:15], s[80:81], 19
	s_add_u32 s86, s48, s14
	s_addc_u32 s87, s49, s15
	s_and_b64 s[14:15], s[4:5], exec
	s_cselect_b32 s13, s87, s9
	s_cselect_b32 s14, s86, s8
	s_add_u32 s6, s6, 0x44000
	s_addc_u32 s7, s7, 0
	s_add_u32 s8, s8, 0x8000
	s_addc_u32 s9, s9, 0
	s_mov_b32 s15, -2
	s_waitcnt lgkmcnt(0)
	ds_read_b128 v[130:133], v177
	ds_read_b128 v[134:137], v177 offset:1024
	ds_read_b128 v[138:141], v177 offset:2048
	ds_read_b128 v[142:145], v177 offset:3072
	ds_read_b128 v[146:149], v178
	ds_read_b128 v[150:153], v178 offset:1024
	ds_read_b128 v[166:169], v178 offset:2048
	ds_read_b128 v[170:173], v178 offset:3072
	s_add_u32 s36, s6, 0xfffc4000
	s_addc_u32 s37, s7, -1
	s_cmp_eq_u32 s15, 12
	s_cselect_b32 s37, s10, s37
	s_cselect_b32 s36, s11, s36
	s_cselect_b32 s39, s13, s9
	s_cselect_b32 s38, s14, s8
	v_lshl_add_u64 v[174:175], s[6:7], 0, v[154:155]
	s_add_i32 m0, s68, 0xc000
	ds_read_b128 v[184:187], v179
	ds_read_b128 v[188:191], v179 offset:1024
	ds_read_b128 v[192:195], v179 offset:2048
	ds_read_b128 v[196:199], v179 offset:3072
	ds_read_b128 v[202:205], v179 offset:4096
	ds_read_b128 v[206:209], v179 offset:5120
	ds_read_b128 v[210:213], v179 offset:6144
	ds_read_b128 v[214:217], v179 offset:7168
	global_load_lds_dwordx4 v[174:175], off
	v_lshl_add_u64 v[174:175], v[174:175], 0, s[34:35]
	s_add_i32 m0, s68, 0xe000
	s_nop 0
	global_load_lds_dwordx4 v[174:175], off
	s_waitcnt vmcnt(8)
	s_waitcnt lgkmcnt(0)
	s_barrier
	s_setprio 1
	s_waitcnt lgkmcnt(0)
	v_mfma_f32_16x16x32_bf16 v[126:129], v[130:133], v[184:187], 0
	v_mfma_f32_16x16x32_bf16 v[122:125], v[138:141], v[184:187], 0
	v_mfma_f32_16x16x32_bf16 v[110:113], v[130:133], v[192:195], 0
	v_mfma_f32_16x16x32_bf16 v[106:109], v[138:141], v[192:195], 0
	v_mfma_f32_16x16x32_bf16 v[94:97], v[130:133], v[202:205], 0
	v_mfma_f32_16x16x32_bf16 v[90:93], v[138:141], v[202:205], 0
	v_mfma_f32_16x16x32_bf16 v[78:81], v[130:133], v[210:213], 0
	v_mfma_f32_16x16x32_bf16 v[74:77], v[138:141], v[210:213], 0
	v_mfma_f32_16x16x32_bf16 v[126:129], v[134:137], v[188:191], v[126:129]
	v_mfma_f32_16x16x32_bf16 v[122:125], v[142:145], v[188:191], v[122:125]
	v_mfma_f32_16x16x32_bf16 v[110:113], v[134:137], v[196:199], v[110:113]
	v_mfma_f32_16x16x32_bf16 v[106:109], v[142:145], v[196:199], v[106:109]
	v_mfma_f32_16x16x32_bf16 v[94:97], v[134:137], v[206:209], v[94:97]
	v_mfma_f32_16x16x32_bf16 v[90:93], v[142:145], v[206:209], v[90:93]
	v_mfma_f32_16x16x32_bf16 v[78:81], v[134:137], v[214:217], v[78:81]
	v_mfma_f32_16x16x32_bf16 v[74:77], v[142:145], v[214:217], v[74:77]
	v_mfma_f32_16x16x32_bf16 v[118:121], v[146:149], v[184:187], 0
	v_mfma_f32_16x16x32_bf16 v[114:117], v[166:169], v[184:187], 0
	v_mfma_f32_16x16x32_bf16 v[102:105], v[146:149], v[192:195], 0
	v_mfma_f32_16x16x32_bf16 v[98:101], v[166:169], v[192:195], 0
	v_mfma_f32_16x16x32_bf16 v[86:89], v[146:149], v[202:205], 0
	v_mfma_f32_16x16x32_bf16 v[82:85], v[166:169], v[202:205], 0
	v_mfma_f32_16x16x32_bf16 v[70:73], v[146:149], v[210:213], 0
	v_mfma_f32_16x16x32_bf16 v[66:69], v[166:169], v[210:213], 0
	v_mfma_f32_16x16x32_bf16 v[118:121], v[150:153], v[188:191], v[118:121]
	v_mfma_f32_16x16x32_bf16 v[114:117], v[170:173], v[188:191], v[114:117]
	v_mfma_f32_16x16x32_bf16 v[102:105], v[150:153], v[196:199], v[102:105]
	v_mfma_f32_16x16x32_bf16 v[98:101], v[170:173], v[196:199], v[98:101]
	v_mfma_f32_16x16x32_bf16 v[86:89], v[150:153], v[206:209], v[86:89]
	v_mfma_f32_16x16x32_bf16 v[82:85], v[170:173], v[206:209], v[82:85]
	v_mfma_f32_16x16x32_bf16 v[70:73], v[150:153], v[214:217], v[70:73]
	v_mfma_f32_16x16x32_bf16 v[66:69], v[170:173], v[214:217], v[66:69]
	s_setprio 0
	s_barrier
	v_lshl_add_u64 v[174:175], s[38:39], 0, v[154:155]
	s_add_i32 s38, s93, s33
	s_mov_b32 m0, s38
	ds_read_b128 v[184:187], v179 offset:16384
	ds_read_b128 v[188:191], v179 offset:17408
	ds_read_b128 v[192:195], v179 offset:18432
	ds_read_b128 v[196:199], v179 offset:19456
	ds_read_b128 v[202:205], v179 offset:20480
	ds_read_b128 v[206:209], v179 offset:21504
	ds_read_b128 v[210:213], v179 offset:22528
	ds_read_b128 v[214:217], v179 offset:23552
	global_load_lds_dwordx4 v[174:175], off
	v_lshl_add_u64 v[218:219], v[174:175], 0, s[34:35]
	s_add_i32 m0, s38, 0x2000
	s_add_i32 s38, s94, s33
	global_load_lds_dwordx4 v[218:219], off
	v_lshl_add_u64 v[218:219], v[174:175], 0, s[52:53]
	s_mov_b32 m0, s38
	s_nop 0
	global_load_lds_dwordx4 v[218:219], off
	v_lshl_add_u64 v[218:219], v[174:175], 0, s[54:55]
	s_add_i32 m0, s38, 0x2000
	s_nop 0
	global_load_lds_dwordx4 v[218:219], off
	v_lshl_add_u64 v[218:219], s[36:37], 0, v[154:155]
	s_mov_b32 m0, s68
	v_lshl_add_u64 v[220:221], v[218:219], 0, s[34:35]
	global_load_lds_dwordx4 v[218:219], off
	s_mov_b32 m0, s69
	s_nop 0
	global_load_lds_dwordx4 v[220:221], off
	s_waitcnt vmcnt(8)
	s_waitcnt lgkmcnt(0)
	s_barrier
; #define PG8_STAGE(bufoff, gbase, voff) do { _Pragma("unroll") for (int _i = 0; _i < 2; ++_i) \
;         __builtin_amdgcn_global_load_lds((const unsigned*)((const char*)(gbase) + (voff)[_i]), (PG8_LAS unsigned*)(lds + (bufoff) + ldsw + _i * 8192), 16, 0, 0); } while (0)
; #define PG8_LDA(dst, b, h) do { _Pragma("unroll") for (int m = 0; m < 4; ++m) _Pragma("unroll") for (int k = 0; k < 2; ++k) dst[m][k] = *(const PG8_LAS bf16x8*)(lds + PG8_SA(b, h) + aoff + m * 2048 + k * 1024); } while (0)
; #define PG8_LDB(dst, b, h) do { _Pragma("unroll") for (int n = 0; n < 2; ++n) _Pragma("unroll") for (int k = 0; k < 2; ++k) dst[n][k] = *(const PG8_LAS bf16x8*)(lds + PG8_SB(b, h) + boff + n * 2048 + k * 1024); } while (0)
; #define PG8_MMA(ai, bj, At, Bt) do { __builtin_amdgcn_s_setprio(1); _Pragma("unroll") for (int m = 0; m < 4; ++m) _Pragma("unroll") for (int n = 0; n < 2; ++n) _Pragma("unroll") for (int k = 0; k < 2; ++k) \
;         acc[ai][bj][m][n] = __builtin_amdgcn_mfma_f32_16x16x32_bf16(Bt[n][k], At[m][k], acc[ai][bj][m][n], 0, 0, 0); __builtin_amdgcn_s_setprio(0); } while (0)
; #define PG8_WAIT_V(n) asm volatile("s_waitcnt vmcnt(" #n ")" ::: "memory")
; #define PG8_WAIT_L(n) asm volatile("s_waitcnt lgkmcnt(" #n ")" ::: "memory")
; #define PG8_BAR __builtin_amdgcn_s_barrier()
; #define PG8_SCHED __builtin_amdgcn_sched_barrier(0)
; template <class Epi, class Sched, bool ALIGN_EPI = false, bool SP2 = false>
; __device__ __forceinline__ void gemm_phase(PG8_LAS unsigned char* lds, const Gemm g, const Sched& S, const Epi& E) {
;     ...
;             PG8_LDA(At, 0, 1); PG8_STAGE(PG8_SB(0, 0), b2, voffB); PG8_STAGE(PG8_SB(0, 1), b2 + hstep, voffB); PG8_STAGE(PG8_SA(0, 0), a2, voffA);
;             PG8_WAIT_V(8); PG8_WAIT_L(0); PG8_BAR; PG8_MMA(1, 0, At, B0); PG8_MMA(1, 1, At, B1); PG8_BAR; PG8_SCHED;
;             PG8_LDB(B0, 1, 0); PG8_LDB(B1, 1, 1); PG8_SCHED; PG8_LDA(At, 1, 0); PG8_STAGE(PG8_SA(0, 1), a2 + hstep, voffA);
;             PG8_WAIT_V(8); PG8_WAIT_L(0); PG8_BAR; PG8_MMA(0, 0, At, B0); PG8_MMA(0, 1, At, B1); PG8_BAR; PG8_SCHED;
	s_setprio 1
	s_waitcnt lgkmcnt(0)
	v_mfma_f32_16x16x32_bf16 v[62:65], v[130:133], v[184:187], 0
	v_mfma_f32_16x16x32_bf16 v[58:61], v[138:141], v[184:187], 0
	v_mfma_f32_16x16x32_bf16 v[46:49], v[130:133], v[192:195], 0
	v_mfma_f32_16x16x32_bf16 v[42:45], v[138:141], v[192:195], 0
	v_mfma_f32_16x16x32_bf16 v[30:33], v[130:133], v[202:205], 0
	v_mfma_f32_16x16x32_bf16 v[26:29], v[138:141], v[202:205], 0
	v_mfma_f32_16x16x32_bf16 v[14:17], v[130:133], v[210:213], 0
	v_mfma_f32_16x16x32_bf16 v[10:13], v[138:141], v[210:213], 0
	v_mfma_f32_16x16x32_bf16 v[62:65], v[134:137], v[188:191], v[62:65]
	v_mfma_f32_16x16x32_bf16 v[58:61], v[142:145], v[188:191], v[58:61]
	v_mfma_f32_16x16x32_bf16 v[46:49], v[134:137], v[196:199], v[46:49]
	v_mfma_f32_16x16x32_bf16 v[42:45], v[142:145], v[196:199], v[42:45]
	v_mfma_f32_16x16x32_bf16 v[30:33], v[134:137], v[206:209], v[30:33]
	v_mfma_f32_16x16x32_bf16 v[26:29], v[142:145], v[206:209], v[26:29]
	v_mfma_f32_16x16x32_bf16 v[14:17], v[134:137], v[214:217], v[14:17]
	v_mfma_f32_16x16x32_bf16 v[10:13], v[142:145], v[214:217], v[10:13]
	v_mfma_f32_16x16x32_bf16 v[54:57], v[146:149], v[184:187], 0
	v_mfma_f32_16x16x32_bf16 v[50:53], v[166:169], v[184:187], 0
	v_mfma_f32_16x16x32_bf16 v[38:41], v[146:149], v[192:195], 0
	v_mfma_f32_16x16x32_bf16 v[34:37], v[166:169], v[192:195], 0
	v_mfma_f32_16x16x32_bf16 v[22:25], v[146:149], v[202:205], 0
	v_mfma_f32_16x16x32_bf16 v[18:21], v[166:169], v[202:205], 0
	v_mfma_f32_16x16x32_bf16 v[6:9], v[146:149], v[210:213], 0
	v_mfma_f32_16x16x32_bf16 v[2:5], v[166:169], v[210:213], 0
	v_mfma_f32_16x16x32_bf16 v[54:57], v[150:153], v[188:191], v[54:57]
	v_mfma_f32_16x16x32_bf16 v[50:53], v[170:173], v[188:191], v[50:53]
	v_mfma_f32_16x16x32_bf16 v[38:41], v[150:153], v[196:199], v[38:41]
	v_mfma_f32_16x16x32_bf16 v[34:37], v[170:173], v[196:199], v[34:37]
	v_mfma_f32_16x16x32_bf16 v[22:25], v[150:153], v[206:209], v[22:25]
	v_mfma_f32_16x16x32_bf16 v[18:21], v[170:173], v[206:209], v[18:21]
	v_mfma_f32_16x16x32_bf16 v[6:9], v[150:153], v[214:217], v[6:9]
	v_mfma_f32_16x16x32_bf16 v[2:5], v[170:173], v[214:217], v[2:5]
	s_setprio 0
	s_barrier
	s_add_i32 s36, 0, 0x18000
	s_add_i32 s37, 0, 0x1c000
	v_add_u32_e32 v142, s36, v159
	v_add_u32_e32 v156, s37, v159
	ds_read_b128 v[130:133], v142
	ds_read_b128 v[134:137], v142 offset:1024
	ds_read_b128 v[138:141], v142 offset:2048
	ds_read_b128 v[142:145], v142 offset:3072
	ds_read_b128 v[146:149], v156
	ds_read_b128 v[150:153], v156 offset:1024
	ds_read_b128 v[166:169], v156 offset:2048
	ds_read_b128 v[170:173], v156 offset:3072
	s_mov_b32 m0, s70
	v_lshl_add_u64 v[220:221], v[218:219], 0, s[52:53]
	ds_read_b128 v[184:187], v179 offset:32768
	ds_read_b128 v[188:191], v179 offset:33792
	ds_read_b128 v[192:195], v179 offset:34816
	ds_read_b128 v[196:199], v179 offset:35840
	ds_read_b128 v[202:205], v179 offset:36864
	ds_read_b128 v[206:209], v179 offset:37888
	ds_read_b128 v[210:213], v179 offset:38912
	ds_read_b128 v[214:217], v179 offset:39936
	global_load_lds_dwordx4 v[220:221], off
	v_lshl_add_u64 v[220:221], v[218:219], 0, s[54:55]
	s_mov_b32 m0, s71
	s_nop 0
	global_load_lds_dwordx4 v[220:221], off
	s_waitcnt vmcnt(8)
	s_waitcnt lgkmcnt(0)
	s_barrier
	s_setprio 1
	s_waitcnt lgkmcnt(0)
	v_mfma_f32_16x16x32_bf16 v[126:129], v[130:133], v[184:187], v[126:129]
	v_mfma_f32_16x16x32_bf16 v[122:125], v[138:141], v[184:187], v[122:125]
	v_mfma_f32_16x16x32_bf16 v[110:113], v[130:133], v[192:195], v[110:113]
	v_mfma_f32_16x16x32_bf16 v[106:109], v[138:141], v[192:195], v[106:109]
	v_mfma_f32_16x16x32_bf16 v[94:97], v[130:133], v[202:205], v[94:97]
	v_mfma_f32_16x16x32_bf16 v[90:93], v[138:141], v[202:205], v[90:93]
	v_mfma_f32_16x16x32_bf16 v[78:81], v[130:133], v[210:213], v[78:81]
	v_mfma_f32_16x16x32_bf16 v[74:77], v[138:141], v[210:213], v[74:77]
	v_mfma_f32_16x16x32_bf16 v[126:129], v[134:137], v[188:191], v[126:129]
	v_mfma_f32_16x16x32_bf16 v[122:125], v[142:145], v[188:191], v[122:125]
	v_mfma_f32_16x16x32_bf16 v[110:113], v[134:137], v[196:199], v[110:113]
	v_mfma_f32_16x16x32_bf16 v[106:109], v[142:145], v[196:199], v[106:109]
	v_mfma_f32_16x16x32_bf16 v[94:97], v[134:137], v[206:209], v[94:97]
	v_mfma_f32_16x16x32_bf16 v[90:93], v[142:145], v[206:209], v[90:93]
	v_mfma_f32_16x16x32_bf16 v[78:81], v[134:137], v[214:217], v[78:81]
	v_mfma_f32_16x16x32_bf16 v[74:77], v[142:145], v[214:217], v[74:77]
	v_mfma_f32_16x16x32_bf16 v[118:121], v[146:149], v[184:187], v[118:121]
	v_mfma_f32_16x16x32_bf16 v[114:117], v[166:169], v[184:187], v[114:117]
	v_mfma_f32_16x16x32_bf16 v[102:105], v[146:149], v[192:195], v[102:105]
	v_mfma_f32_16x16x32_bf16 v[98:101], v[166:169], v[192:195], v[98:101]
	v_mfma_f32_16x16x32_bf16 v[86:89], v[146:149], v[202:205], v[86:89]
	v_mfma_f32_16x16x32_bf16 v[82:85], v[166:169], v[202:205], v[82:85]
	v_mfma_f32_16x16x32_bf16 v[70:73], v[146:149], v[210:213], v[70:73]
	v_mfma_f32_16x16x32_bf16 v[66:69], v[166:169], v[210:213], v[66:69]
	v_mfma_f32_16x16x32_bf16 v[118:121], v[150:153], v[188:191], v[118:121]
	v_mfma_f32_16x16x32_bf16 v[114:117], v[170:173], v[188:191], v[114:117]
	v_mfma_f32_16x16x32_bf16 v[102:105], v[150:153], v[196:199], v[102:105]
	v_mfma_f32_16x16x32_bf16 v[98:101], v[170:173], v[196:199], v[98:101]
	v_mfma_f32_16x16x32_bf16 v[86:89], v[150:153], v[206:209], v[86:89]
	v_mfma_f32_16x16x32_bf16 v[82:85], v[170:173], v[206:209], v[82:85]
	v_mfma_f32_16x16x32_bf16 v[70:73], v[150:153], v[214:217], v[70:73]
	v_mfma_f32_16x16x32_bf16 v[66:69], v[170:173], v[214:217], v[66:69]
	s_setprio 0
	s_barrier
; #define PG8_STAGE(bufoff, gbase, voff) do { _Pragma("unroll") for (int _i = 0; _i < 2; ++_i) \
;         __builtin_amdgcn_global_load_lds((const unsigned*)((const char*)(gbase) + (voff)[_i]), (PG8_LAS unsigned*)(lds + (bufoff) + ldsw + _i * 8192), 16, 0, 0); } while (0)
; #define PG8_LDA(dst, b, h) do { _Pragma("unroll") for (int m = 0; m < 4; ++m) _Pragma("unroll") for (int k = 0; k < 2; ++k) dst[m][k] = *(const PG8_LAS bf16x8*)(lds + PG8_SA(b, h) + aoff + m * 2048 + k * 1024); } while (0)
; #define PG8_LDB(dst, b, h) do { _Pragma("unroll") for (int n = 0; n < 2; ++n) _Pragma("unroll") for (int k = 0; k < 2; ++k) dst[n][k] = *(const PG8_LAS bf16x8*)(lds + PG8_SB(b, h) + boff + n * 2048 + k * 1024); } while (0)
; #define PG8_MMA(ai, bj, At, Bt) do { __builtin_amdgcn_s_setprio(1); _Pragma("unroll") for (int m = 0; m < 4; ++m) _Pragma("unroll") for (int n = 0; n < 2; ++n) _Pragma("unroll") for (int k = 0; k < 2; ++k) \
;         acc[ai][bj][m][n] = __builtin_amdgcn_mfma_f32_16x16x32_bf16(Bt[n][k], At[m][k], acc[ai][bj][m][n], 0, 0, 0); __builtin_amdgcn_s_setprio(0); } while (0)
; #define PG8_WAIT_V(n) asm volatile("s_waitcnt vmcnt(" #n ")" ::: "memory")
; #define PG8_WAIT_L(n) asm volatile("s_waitcnt lgkmcnt(" #n ")" ::: "memory")
; #define PG8_BAR __builtin_amdgcn_s_barrier()
; #define PG8_SCHED __builtin_amdgcn_sched_barrier(0)
; template <class Epi, class Sched, bool ALIGN_EPI = false, bool SP2 = false>
; __device__ __forceinline__ void gemm_phase(PG8_LAS unsigned char* lds, const Gemm g, const Sched& S, const Epi& E) {
;     ...
;             PG8_LDB(B0, 0, 0); PG8_LDB(B1, 0, 1); PG8_SCHED; PG8_LDA(At, 0, 0); PG8_STAGE(PG8_SA(1, 1), a1 + hstep, voffA);
;     ...
;             PG8_LDA(At, 1, 1); PG8_STAGE(PG8_SB(1, 0), b3, voffB); PG8_STAGE(PG8_SB(1, 1), b3 + hstep, voffB); PG8_STAGE(PG8_SA(1, 0), a3, voffA);
;             PG8_WAIT_V(8); PG8_WAIT_L(0); PG8_BAR; PG8_MMA(1, 0, At, B0); PG8_MMA(1, 1, At, B1); PG8_BAR; PG8_SCHED;
	s_add_i32 s36, s36, s33
	v_lshl_add_u64 v[220:221], v[174:175], 0, s[58:59]
	s_mov_b32 m0, s36
	ds_read_b128 v[184:187], v179 offset:49152
	ds_read_b128 v[188:191], v179 offset:50176
	ds_read_b128 v[192:195], v179 offset:51200
	ds_read_b128 v[196:199], v179 offset:52224
	ds_read_b128 v[202:205], v179 offset:53248
	ds_read_b128 v[206:209], v179 offset:54272
	ds_read_b128 v[210:213], v179 offset:55296
	ds_read_b128 v[214:217], v179 offset:56320
	global_load_lds_dwordx4 v[220:221], off
	v_lshl_add_u64 v[220:221], v[174:175], 0, s[60:61]
	s_add_i32 m0, s36, 0x2000
	s_add_i32 s36, s37, s33
	global_load_lds_dwordx4 v[220:221], off
	v_lshl_add_u64 v[220:221], v[174:175], 0, s[62:63]
	s_mov_b32 m0, s36
	v_lshl_add_u64 v[174:175], v[174:175], 0, s[64:65]
	global_load_lds_dwordx4 v[220:221], off
	s_add_i32 m0, s36, 0x2000
	s_nop 0
	global_load_lds_dwordx4 v[174:175], off
	v_lshl_add_u64 v[174:175], v[218:219], 0, s[58:59]
	s_mov_b32 m0, s73
	s_nop 0
	global_load_lds_dwordx4 v[174:175], off
	v_lshl_add_u64 v[174:175], v[218:219], 0, s[60:61]
	s_mov_b32 m0, s74
	s_nop 0
	global_load_lds_dwordx4 v[174:175], off
	s_waitcnt vmcnt(8)
	s_waitcnt lgkmcnt(0)
	s_barrier
	s_setprio 1
	s_waitcnt lgkmcnt(0)
	v_mfma_f32_16x16x32_bf16 v[62:65], v[130:133], v[184:187], v[62:65]
	v_mfma_f32_16x16x32_bf16 v[58:61], v[138:141], v[184:187], v[58:61]
	v_mfma_f32_16x16x32_bf16 v[46:49], v[130:133], v[192:195], v[46:49]
	v_mfma_f32_16x16x32_bf16 v[42:45], v[138:141], v[192:195], v[42:45]
	v_mfma_f32_16x16x32_bf16 v[30:33], v[130:133], v[202:205], v[30:33]
	v_mfma_f32_16x16x32_bf16 v[26:29], v[138:141], v[202:205], v[26:29]
	v_mfma_f32_16x16x32_bf16 v[14:17], v[130:133], v[210:213], v[14:17]
	v_mfma_f32_16x16x32_bf16 v[10:13], v[138:141], v[210:213], v[10:13]
	v_mfma_f32_16x16x32_bf16 v[62:65], v[134:137], v[188:191], v[62:65]
	v_mfma_f32_16x16x32_bf16 v[58:61], v[142:145], v[188:191], v[58:61]
	v_mfma_f32_16x16x32_bf16 v[46:49], v[134:137], v[196:199], v[46:49]
	v_mfma_f32_16x16x32_bf16 v[42:45], v[142:145], v[196:199], v[42:45]
	v_mfma_f32_16x16x32_bf16 v[30:33], v[134:137], v[206:209], v[30:33]
	v_mfma_f32_16x16x32_bf16 v[26:29], v[142:145], v[206:209], v[26:29]
	v_mfma_f32_16x16x32_bf16 v[14:17], v[134:137], v[214:217], v[14:17]
	v_mfma_f32_16x16x32_bf16 v[10:13], v[142:145], v[214:217], v[10:13]
	v_mfma_f32_16x16x32_bf16 v[54:57], v[146:149], v[184:187], v[54:57]
	v_mfma_f32_16x16x32_bf16 v[50:53], v[166:169], v[184:187], v[50:53]
	v_mfma_f32_16x16x32_bf16 v[38:41], v[146:149], v[192:195], v[38:41]
	v_mfma_f32_16x16x32_bf16 v[34:37], v[166:169], v[192:195], v[34:37]
	v_mfma_f32_16x16x32_bf16 v[22:25], v[146:149], v[202:205], v[22:25]
	v_mfma_f32_16x16x32_bf16 v[18:21], v[166:169], v[202:205], v[18:21]
	v_mfma_f32_16x16x32_bf16 v[6:9], v[146:149], v[210:213], v[6:9]
	v_mfma_f32_16x16x32_bf16 v[2:5], v[166:169], v[210:213], v[2:5]
	v_mfma_f32_16x16x32_bf16 v[54:57], v[150:153], v[188:191], v[54:57]
	v_mfma_f32_16x16x32_bf16 v[50:53], v[170:173], v[188:191], v[50:53]
	v_mfma_f32_16x16x32_bf16 v[38:41], v[150:153], v[196:199], v[38:41]
	v_mfma_f32_16x16x32_bf16 v[34:37], v[170:173], v[196:199], v[34:37]
	v_mfma_f32_16x16x32_bf16 v[22:25], v[150:153], v[206:209], v[22:25]
	v_mfma_f32_16x16x32_bf16 v[18:21], v[170:173], v[206:209], v[18:21]
	v_mfma_f32_16x16x32_bf16 v[6:9], v[150:153], v[214:217], v[6:9]
	v_mfma_f32_16x16x32_bf16 v[2:5], v[170:173], v[214:217], v[2:5]
	s_setprio 0
	s_barrier
	s_add_i32 s15, s15, 2
	s_add_u32 s6, s6, 0x8000
	s_addc_u32 s7, s7, 0
	s_add_u32 s8, s8, 0x8000
	s_addc_u32 s9, s9, 0
	s_cmp_gt_u32 s15, 13
	s_cbranch_scc0 .LBB0_152
.LBB0_152:
	ds_read_b128 v[130:133], v177
	ds_read_b128 v[134:137], v177 offset:1024
	ds_read_b128 v[138:141], v177 offset:2048
	ds_read_b128 v[142:145], v177 offset:3072
	ds_read_b128 v[146:149], v178
	ds_read_b128 v[150:153], v178 offset:1024
	ds_read_b128 v[166:169], v178 offset:2048
	ds_read_b128 v[170:173], v178 offset:3072
	s_add_u32 s36, s6, 0xfffc4000
	s_addc_u32 s37, s7, -1
	s_cmp_eq_u32 s15, 12
	s_cselect_b32 s37, s10, s37
	s_cselect_b32 s36, s11, s36
	s_cselect_b32 s39, s13, s9
	s_cselect_b32 s38, s14, s8
	v_lshl_add_u64 v[174:175], s[6:7], 0, v[154:155]
	s_add_i32 m0, s68, 0xc000
	ds_read_b128 v[184:187], v179
	ds_read_b128 v[188:191], v179 offset:1024
	ds_read_b128 v[192:195], v179 offset:2048
	ds_read_b128 v[196:199], v179 offset:3072
	ds_read_b128 v[202:205], v179 offset:4096
	ds_read_b128 v[206:209], v179 offset:5120
	ds_read_b128 v[210:213], v179 offset:6144
	ds_read_b128 v[214:217], v179 offset:7168
	global_load_lds_dwordx4 v[174:175], off
	v_lshl_add_u64 v[174:175], v[174:175], 0, s[34:35]
	s_add_i32 m0, s68, 0xe000
	s_nop 0
	global_load_lds_dwordx4 v[174:175], off
	s_waitcnt vmcnt(8)
	s_waitcnt lgkmcnt(0)
	s_barrier
; #define PG8_STAGE(bufoff, gbase, voff) do { _Pragma("unroll") for (int _i = 0; _i < 2; ++_i) \
;         __builtin_amdgcn_global_load_lds((const unsigned*)((const char*)(gbase) + (voff)[_i]), (PG8_LAS unsigned*)(lds + (bufoff) + ldsw + _i * 8192), 16, 0, 0); } while (0)
; #define PG8_LDA(dst, b, h) do { _Pragma("unroll") for (int m = 0; m < 4; ++m) _Pragma("unroll") for (int k = 0; k < 2; ++k) dst[m][k] = *(const PG8_LAS bf16x8*)(lds + PG8_SA(b, h) + aoff + m * 2048 + k * 1024); } while (0)
; #define PG8_MMA(ai, bj, At, Bt) do { __builtin_amdgcn_s_setprio(1); _Pragma("unroll") for (int m = 0; m < 4; ++m) _Pragma("unroll") for (int n = 0; n < 2; ++n) _Pragma("unroll") for (int k = 0; k < 2; ++k) \
;         acc[ai][bj][m][n] = __builtin_amdgcn_mfma_f32_16x16x32_bf16(Bt[n][k], At[m][k], acc[ai][bj][m][n], 0, 0, 0); __builtin_amdgcn_s_setprio(0); } while (0)
; #define PG8_WAIT_V(n) asm volatile("s_waitcnt vmcnt(" #n ")" ::: "memory")
; #define PG8_WAIT_L(n) asm volatile("s_waitcnt lgkmcnt(" #n ")" ::: "memory")
; #define PG8_BAR __builtin_amdgcn_s_barrier()
; #define PG8_SCHED __builtin_amdgcn_sched_barrier(0)
; template <class Epi, class Sched, bool ALIGN_EPI = false, bool SP2 = false>
; __device__ __forceinline__ void gemm_phase(PG8_LAS unsigned char* lds, const Gemm g, const Sched& S, const Epi& E) {
;     ...
;             PG8_WAIT_V(8); PG8_WAIT_L(0); PG8_BAR; PG8_MMA(0, 0, At, B0); PG8_MMA(0, 1, At, B1); PG8_BAR; PG8_SCHED;
;             PG8_LDA(At, 0, 1); PG8_STAGE(PG8_SB(0, 0), b2, voffB); PG8_STAGE(PG8_SB(0, 1), b2 + hstep, voffB); PG8_STAGE(PG8_SA(0, 0), a2, voffA);
;             PG8_WAIT_V(8); PG8_WAIT_L(0); PG8_BAR; PG8_MMA(1, 0, At, B0); PG8_MMA(1, 1, At, B1); PG8_BAR; PG8_SCHED;
	s_setprio 1
	s_waitcnt lgkmcnt(0)
	v_mfma_f32_16x16x32_bf16 v[126:129], v[130:133], v[184:187], v[126:129]
	v_mfma_f32_16x16x32_bf16 v[122:125], v[138:141], v[184:187], v[122:125]
	v_mfma_f32_16x16x32_bf16 v[110:113], v[130:133], v[192:195], v[110:113]
	v_mfma_f32_16x16x32_bf16 v[106:109], v[138:141], v[192:195], v[106:109]
	v_mfma_f32_16x16x32_bf16 v[94:97], v[130:133], v[202:205], v[94:97]
	v_mfma_f32_16x16x32_bf16 v[90:93], v[138:141], v[202:205], v[90:93]
	v_mfma_f32_16x16x32_bf16 v[78:81], v[130:133], v[210:213], v[78:81]
	v_mfma_f32_16x16x32_bf16 v[74:77], v[138:141], v[210:213], v[74:77]
	v_mfma_f32_16x16x32_bf16 v[126:129], v[134:137], v[188:191], v[126:129]
	v_mfma_f32_16x16x32_bf16 v[122:125], v[142:145], v[188:191], v[122:125]
	v_mfma_f32_16x16x32_bf16 v[110:113], v[134:137], v[196:199], v[110:113]
	v_mfma_f32_16x16x32_bf16 v[106:109], v[142:145], v[196:199], v[106:109]
	v_mfma_f32_16x16x32_bf16 v[94:97], v[134:137], v[206:209], v[94:97]
	v_mfma_f32_16x16x32_bf16 v[90:93], v[142:145], v[206:209], v[90:93]
	v_mfma_f32_16x16x32_bf16 v[78:81], v[134:137], v[214:217], v[78:81]
	v_mfma_f32_16x16x32_bf16 v[74:77], v[142:145], v[214:217], v[74:77]
	v_mfma_f32_16x16x32_bf16 v[118:121], v[146:149], v[184:187], v[118:121]
	v_mfma_f32_16x16x32_bf16 v[114:117], v[166:169], v[184:187], v[114:117]
	v_mfma_f32_16x16x32_bf16 v[102:105], v[146:149], v[192:195], v[102:105]
	v_mfma_f32_16x16x32_bf16 v[98:101], v[166:169], v[192:195], v[98:101]
	v_mfma_f32_16x16x32_bf16 v[86:89], v[146:149], v[202:205], v[86:89]
	v_mfma_f32_16x16x32_bf16 v[82:85], v[166:169], v[202:205], v[82:85]
	v_mfma_f32_16x16x32_bf16 v[70:73], v[146:149], v[210:213], v[70:73]
	v_mfma_f32_16x16x32_bf16 v[66:69], v[166:169], v[210:213], v[66:69]
	v_mfma_f32_16x16x32_bf16 v[118:121], v[150:153], v[188:191], v[118:121]
	v_mfma_f32_16x16x32_bf16 v[114:117], v[170:173], v[188:191], v[114:117]
	v_mfma_f32_16x16x32_bf16 v[102:105], v[150:153], v[196:199], v[102:105]
	v_mfma_f32_16x16x32_bf16 v[98:101], v[170:173], v[196:199], v[98:101]
	v_mfma_f32_16x16x32_bf16 v[86:89], v[150:153], v[206:209], v[86:89]
	v_mfma_f32_16x16x32_bf16 v[82:85], v[170:173], v[206:209], v[82:85]
	v_mfma_f32_16x16x32_bf16 v[70:73], v[150:153], v[214:217], v[70:73]
	v_mfma_f32_16x16x32_bf16 v[66:69], v[170:173], v[214:217], v[66:69]
	s_setprio 0
	s_barrier
	v_lshl_add_u64 v[174:175], s[38:39], 0, v[154:155]
	s_add_i32 s38, s93, s33
	s_mov_b32 m0, s38
	ds_read_b128 v[184:187], v179 offset:16384
	ds_read_b128 v[188:191], v179 offset:17408
	ds_read_b128 v[192:195], v179 offset:18432
	ds_read_b128 v[196:199], v179 offset:19456
	ds_read_b128 v[202:205], v179 offset:20480
	ds_read_b128 v[206:209], v179 offset:21504
	ds_read_b128 v[210:213], v179 offset:22528
	ds_read_b128 v[214:217], v179 offset:23552
	global_load_lds_dwordx4 v[174:175], off
	v_lshl_add_u64 v[218:219], v[174:175], 0, s[34:35]
	s_add_i32 m0, s38, 0x2000
	s_add_i32 s38, s94, s33
	global_load_lds_dwordx4 v[218:219], off
	v_lshl_add_u64 v[218:219], v[174:175], 0, s[52:53]
	s_mov_b32 m0, s38
	s_nop 0
	global_load_lds_dwordx4 v[218:219], off
	v_lshl_add_u64 v[218:219], v[174:175], 0, s[54:55]
	s_add_i32 m0, s38, 0x2000
	s_nop 0
	global_load_lds_dwordx4 v[218:219], off
	v_lshl_add_u64 v[218:219], s[36:37], 0, v[154:155]
	s_mov_b32 m0, s68
	v_lshl_add_u64 v[220:221], v[218:219], 0, s[34:35]
	global_load_lds_dwordx4 v[218:219], off
	s_mov_b32 m0, s69
	s_nop 0
	global_load_lds_dwordx4 v[220:221], off
	s_waitcnt vmcnt(8)
	s_waitcnt lgkmcnt(0)
	s_barrier
	s_setprio 1
	s_waitcnt lgkmcnt(0)
	v_mfma_f32_16x16x32_bf16 v[62:65], v[130:133], v[184:187], v[62:65]
	v_mfma_f32_16x16x32_bf16 v[58:61], v[138:141], v[184:187], v[58:61]
	v_mfma_f32_16x16x32_bf16 v[46:49], v[130:133], v[192:195], v[46:49]
	v_mfma_f32_16x16x32_bf16 v[42:45], v[138:141], v[192:195], v[42:45]
	v_mfma_f32_16x16x32_bf16 v[30:33], v[130:133], v[202:205], v[30:33]
	v_mfma_f32_16x16x32_bf16 v[26:29], v[138:141], v[202:205], v[26:29]
	v_mfma_f32_16x16x32_bf16 v[14:17], v[130:133], v[210:213], v[14:17]
	v_mfma_f32_16x16x32_bf16 v[10:13], v[138:141], v[210:213], v[10:13]
	v_mfma_f32_16x16x32_bf16 v[62:65], v[134:137], v[188:191], v[62:65]
	v_mfma_f32_16x16x32_bf16 v[58:61], v[142:145], v[188:191], v[58:61]
	v_mfma_f32_16x16x32_bf16 v[46:49], v[134:137], v[196:199], v[46:49]
	v_mfma_f32_16x16x32_bf16 v[42:45], v[142:145], v[196:199], v[42:45]
	v_mfma_f32_16x16x32_bf16 v[30:33], v[134:137], v[206:209], v[30:33]
	v_mfma_f32_16x16x32_bf16 v[26:29], v[142:145], v[206:209], v[26:29]
	v_mfma_f32_16x16x32_bf16 v[14:17], v[134:137], v[214:217], v[14:17]
	v_mfma_f32_16x16x32_bf16 v[10:13], v[142:145], v[214:217], v[10:13]
	v_mfma_f32_16x16x32_bf16 v[54:57], v[146:149], v[184:187], v[54:57]
	v_mfma_f32_16x16x32_bf16 v[50:53], v[166:169], v[184:187], v[50:53]
	v_mfma_f32_16x16x32_bf16 v[38:41], v[146:149], v[192:195], v[38:41]
	v_mfma_f32_16x16x32_bf16 v[34:37], v[166:169], v[192:195], v[34:37]
	v_mfma_f32_16x16x32_bf16 v[22:25], v[146:149], v[202:205], v[22:25]
	v_mfma_f32_16x16x32_bf16 v[18:21], v[166:169], v[202:205], v[18:21]
	v_mfma_f32_16x16x32_bf16 v[6:9], v[146:149], v[210:213], v[6:9]
	v_mfma_f32_16x16x32_bf16 v[2:5], v[166:169], v[210:213], v[2:5]
	v_mfma_f32_16x16x32_bf16 v[54:57], v[150:153], v[188:191], v[54:57]
	v_mfma_f32_16x16x32_bf16 v[50:53], v[170:173], v[188:191], v[50:53]
	v_mfma_f32_16x16x32_bf16 v[38:41], v[150:153], v[196:199], v[38:41]
	v_mfma_f32_16x16x32_bf16 v[34:37], v[170:173], v[196:199], v[34:37]
	v_mfma_f32_16x16x32_bf16 v[22:25], v[150:153], v[206:209], v[22:25]
	v_mfma_f32_16x16x32_bf16 v[18:21], v[170:173], v[206:209], v[18:21]
	v_mfma_f32_16x16x32_bf16 v[6:9], v[150:153], v[214:217], v[6:9]
	v_mfma_f32_16x16x32_bf16 v[2:5], v[170:173], v[214:217], v[2:5]
	s_setprio 0
	s_barrier
; #define PG8_STAGE(bufoff, gbase, voff) do { _Pragma("unroll") for (int _i = 0; _i < 2; ++_i) \
;         __builtin_amdgcn_global_load_lds((const unsigned*)((const char*)(gbase) + (voff)[_i]), (PG8_LAS unsigned*)(lds + (bufoff) + ldsw + _i * 8192), 16, 0, 0); } while (0)
; #define PG8_LDA(dst, b, h) do { _Pragma("unroll") for (int m = 0; m < 4; ++m) _Pragma("unroll") for (int k = 0; k < 2; ++k) dst[m][k] = *(const PG8_LAS bf16x8*)(lds + PG8_SA(b, h) + aoff + m * 2048 + k * 1024); } while (0)
; #define PG8_LDB(dst, b, h) do { _Pragma("unroll") for (int n = 0; n < 2; ++n) _Pragma("unroll") for (int k = 0; k < 2; ++k) dst[n][k] = *(const PG8_LAS bf16x8*)(lds + PG8_SB(b, h) + boff + n * 2048 + k * 1024); } while (0)
; #define PG8_MMA(ai, bj, At, Bt) do { __builtin_amdgcn_s_setprio(1); _Pragma("unroll") for (int m = 0; m < 4; ++m) _Pragma("unroll") for (int n = 0; n < 2; ++n) _Pragma("unroll") for (int k = 0; k < 2; ++k) \
;         acc[ai][bj][m][n] = __builtin_amdgcn_mfma_f32_16x16x32_bf16(Bt[n][k], At[m][k], acc[ai][bj][m][n], 0, 0, 0); __builtin_amdgcn_s_setprio(0); } while (0)
; #define PG8_WAIT_V(n) asm volatile("s_waitcnt vmcnt(" #n ")" ::: "memory")
; #define PG8_WAIT_L(n) asm volatile("s_waitcnt lgkmcnt(" #n ")" ::: "memory")
; #define PG8_BAR __builtin_amdgcn_s_barrier()
; #define PG8_SCHED __builtin_amdgcn_sched_barrier(0)
; template <class Epi, class Sched, bool ALIGN_EPI = false, bool SP2 = false>
; __device__ __forceinline__ void gemm_phase(PG8_LAS unsigned char* lds, const Gemm g, const Sched& S, const Epi& E) {
;     ...
;             PG8_LDB(B0, 1, 0); PG8_LDB(B1, 1, 1); PG8_SCHED; PG8_LDA(At, 1, 0); PG8_STAGE(PG8_SA(0, 1), a2 + hstep, voffA);
;             PG8_WAIT_V(8); PG8_WAIT_L(0); PG8_BAR; PG8_MMA(0, 0, At, B0); PG8_MMA(0, 1, At, B1); PG8_BAR; PG8_SCHED;
	s_add_i32 s36, 0, 0x18000
	s_add_i32 s37, 0, 0x1c000
	v_add_u32_e32 v142, s36, v159
	v_add_u32_e32 v156, s37, v159
	ds_read_b128 v[130:133], v142
	ds_read_b128 v[134:137], v142 offset:1024
	ds_read_b128 v[138:141], v142 offset:2048
	ds_read_b128 v[142:145], v142 offset:3072
	ds_read_b128 v[146:149], v156
	ds_read_b128 v[150:153], v156 offset:1024
	ds_read_b128 v[166:169], v156 offset:2048
	ds_read_b128 v[170:173], v156 offset:3072
	s_mov_b32 m0, s70
	v_lshl_add_u64 v[220:221], v[218:219], 0, s[52:53]
	ds_read_b128 v[184:187], v179 offset:32768
	ds_read_b128 v[188:191], v179 offset:33792
	ds_read_b128 v[192:195], v179 offset:34816
	ds_read_b128 v[196:199], v179 offset:35840
	ds_read_b128 v[202:205], v179 offset:36864
	ds_read_b128 v[206:209], v179 offset:37888
	ds_read_b128 v[210:213], v179 offset:38912
	ds_read_b128 v[214:217], v179 offset:39936
	global_load_lds_dwordx4 v[220:221], off
	v_lshl_add_u64 v[220:221], v[218:219], 0, s[54:55]
	s_mov_b32 m0, s71
	s_nop 0
	global_load_lds_dwordx4 v[220:221], off
	s_waitcnt vmcnt(8)
	s_waitcnt lgkmcnt(0)
	s_barrier
	s_setprio 1
	s_waitcnt lgkmcnt(0)
	v_mfma_f32_16x16x32_bf16 v[126:129], v[130:133], v[184:187], v[126:129]
	v_mfma_f32_16x16x32_bf16 v[122:125], v[138:141], v[184:187], v[122:125]
	v_mfma_f32_16x16x32_bf16 v[110:113], v[130:133], v[192:195], v[110:113]
	v_mfma_f32_16x16x32_bf16 v[106:109], v[138:141], v[192:195], v[106:109]
	v_mfma_f32_16x16x32_bf16 v[94:97], v[130:133], v[202:205], v[94:97]
	v_mfma_f32_16x16x32_bf16 v[90:93], v[138:141], v[202:205], v[90:93]
	v_mfma_f32_16x16x32_bf16 v[78:81], v[130:133], v[210:213], v[78:81]
	v_mfma_f32_16x16x32_bf16 v[74:77], v[138:141], v[210:213], v[74:77]
	v_mfma_f32_16x16x32_bf16 v[126:129], v[134:137], v[188:191], v[126:129]
	v_mfma_f32_16x16x32_bf16 v[122:125], v[142:145], v[188:191], v[122:125]
	v_mfma_f32_16x16x32_bf16 v[110:113], v[134:137], v[196:199], v[110:113]
	v_mfma_f32_16x16x32_bf16 v[106:109], v[142:145], v[196:199], v[106:109]
	v_mfma_f32_16x16x32_bf16 v[94:97], v[134:137], v[206:209], v[94:97]
	v_mfma_f32_16x16x32_bf16 v[90:93], v[142:145], v[206:209], v[90:93]
	v_mfma_f32_16x16x32_bf16 v[78:81], v[134:137], v[214:217], v[78:81]
	v_mfma_f32_16x16x32_bf16 v[74:77], v[142:145], v[214:217], v[74:77]
	v_mfma_f32_16x16x32_bf16 v[118:121], v[146:149], v[184:187], v[118:121]
	v_mfma_f32_16x16x32_bf16 v[114:117], v[166:169], v[184:187], v[114:117]
	v_mfma_f32_16x16x32_bf16 v[102:105], v[146:149], v[192:195], v[102:105]
	v_mfma_f32_16x16x32_bf16 v[98:101], v[166:169], v[192:195], v[98:101]
	v_mfma_f32_16x16x32_bf16 v[86:89], v[146:149], v[202:205], v[86:89]
	v_mfma_f32_16x16x32_bf16 v[82:85], v[166:169], v[202:205], v[82:85]
	v_mfma_f32_16x16x32_bf16 v[70:73], v[146:149], v[210:213], v[70:73]
	v_mfma_f32_16x16x32_bf16 v[66:69], v[166:169], v[210:213], v[66:69]
	v_mfma_f32_16x16x32_bf16 v[118:121], v[150:153], v[188:191], v[118:121]
	v_mfma_f32_16x16x32_bf16 v[114:117], v[170:173], v[188:191], v[114:117]
	v_mfma_f32_16x16x32_bf16 v[102:105], v[150:153], v[196:199], v[102:105]
	v_mfma_f32_16x16x32_bf16 v[98:101], v[170:173], v[196:199], v[98:101]
	v_mfma_f32_16x16x32_bf16 v[86:89], v[150:153], v[206:209], v[86:89]
	v_mfma_f32_16x16x32_bf16 v[82:85], v[170:173], v[206:209], v[82:85]
	v_mfma_f32_16x16x32_bf16 v[70:73], v[150:153], v[214:217], v[70:73]
	v_mfma_f32_16x16x32_bf16 v[66:69], v[170:173], v[214:217], v[66:69]
	s_setprio 0
	s_barrier
; #define PG8_STAGE(bufoff, gbase, voff) do { _Pragma("unroll") for (int _i = 0; _i < 2; ++_i) \
;         __builtin_amdgcn_global_load_lds((const unsigned*)((const char*)(gbase) + (voff)[_i]), (PG8_LAS unsigned*)(lds + (bufoff) + ldsw + _i * 8192), 16, 0, 0); } while (0)
; #define PG8_LDA(dst, b, h) do { _Pragma("unroll") for (int m = 0; m < 4; ++m) _Pragma("unroll") for (int k = 0; k < 2; ++k) dst[m][k] = *(const PG8_LAS bf16x8*)(lds + PG8_SA(b, h) + aoff + m * 2048 + k * 1024); } while (0)
; #define PG8_MMA(ai, bj, At, Bt) do { __builtin_amdgcn_s_setprio(1); _Pragma("unroll") for (int m = 0; m < 4; ++m) _Pragma("unroll") for (int n = 0; n < 2; ++n) _Pragma("unroll") for (int k = 0; k < 2; ++k) \
;         acc[ai][bj][m][n] = __builtin_amdgcn_mfma_f32_16x16x32_bf16(Bt[n][k], At[m][k], acc[ai][bj][m][n], 0, 0, 0); __builtin_amdgcn_s_setprio(0); } while (0)
; #define PG8_WAIT_V(n) asm volatile("s_waitcnt vmcnt(" #n ")" ::: "memory")
; #define PG8_WAIT_L(n) asm volatile("s_waitcnt lgkmcnt(" #n ")" ::: "memory")
; #define PG8_BAR __builtin_amdgcn_s_barrier()
; #define PG8_SCHED __builtin_amdgcn_sched_barrier(0)
; template <class Epi, class Sched, bool ALIGN_EPI = false, bool SP2 = false>
; __device__ __forceinline__ void gemm_phase(PG8_LAS unsigned char* lds, const Gemm g, const Sched& S, const Epi& E) {
;     ...
;             PG8_LDA(At, 1, 1); PG8_STAGE(PG8_SB(1, 0), b3, voffB); PG8_STAGE(PG8_SB(1, 1), b3 + hstep, voffB); PG8_STAGE(PG8_SA(1, 0), a3, voffA);
;             PG8_WAIT_V(8); PG8_WAIT_L(0); PG8_BAR; PG8_MMA(1, 0, At, B0); PG8_MMA(1, 1, At, B1); PG8_BAR; PG8_SCHED;
;     ...
;         if constexpr (ALIGN_EPI) { if (wr == 0) PG8_BAR; }
;         if constexpr (!Epi::AFTER_DRAIN) { E(acc, cur, wr, wc, fr, fq); S.done(cur); }
;         if (!has_next) break;
	s_add_i32 s36, s36, s33
	v_lshl_add_u64 v[220:221], v[174:175], 0, s[58:59]
	s_mov_b32 m0, s36
	ds_read_b128 v[184:187], v179 offset:49152
	ds_read_b128 v[188:191], v179 offset:50176
	ds_read_b128 v[192:195], v179 offset:51200
	ds_read_b128 v[196:199], v179 offset:52224
	ds_read_b128 v[202:205], v179 offset:53248
	ds_read_b128 v[206:209], v179 offset:54272
	ds_read_b128 v[210:213], v179 offset:55296
	ds_read_b128 v[214:217], v179 offset:56320
	global_load_lds_dwordx4 v[220:221], off
	v_lshl_add_u64 v[220:221], v[174:175], 0, s[60:61]
	s_add_i32 m0, s36, 0x2000
	s_add_i32 s36, s37, s33
	global_load_lds_dwordx4 v[220:221], off
	v_lshl_add_u64 v[220:221], v[174:175], 0, s[62:63]
	s_mov_b32 m0, s36
	v_lshl_add_u64 v[174:175], v[174:175], 0, s[64:65]
	global_load_lds_dwordx4 v[220:221], off
	s_add_i32 m0, s36, 0x2000
	s_nop 0
	global_load_lds_dwordx4 v[174:175], off
	v_lshl_add_u64 v[174:175], v[218:219], 0, s[58:59]
	s_mov_b32 m0, s73
	s_nop 0
	global_load_lds_dwordx4 v[174:175], off
	v_lshl_add_u64 v[174:175], v[218:219], 0, s[60:61]
	s_mov_b32 m0, s74
	s_nop 0
	global_load_lds_dwordx4 v[174:175], off
	s_waitcnt vmcnt(8)
	s_waitcnt lgkmcnt(0)
	s_barrier
	s_setprio 1
	s_waitcnt lgkmcnt(0)
	v_mfma_f32_16x16x32_bf16 v[62:65], v[130:133], v[184:187], v[62:65]
	v_mfma_f32_16x16x32_bf16 v[58:61], v[138:141], v[184:187], v[58:61]
	v_mfma_f32_16x16x32_bf16 v[46:49], v[130:133], v[192:195], v[46:49]
	v_mfma_f32_16x16x32_bf16 v[42:45], v[138:141], v[192:195], v[42:45]
	v_mfma_f32_16x16x32_bf16 v[30:33], v[130:133], v[202:205], v[30:33]
	v_mfma_f32_16x16x32_bf16 v[26:29], v[138:141], v[202:205], v[26:29]
	v_mfma_f32_16x16x32_bf16 v[14:17], v[130:133], v[210:213], v[14:17]
	v_mfma_f32_16x16x32_bf16 v[10:13], v[138:141], v[210:213], v[10:13]
	v_mfma_f32_16x16x32_bf16 v[62:65], v[134:137], v[188:191], v[62:65]
	v_mfma_f32_16x16x32_bf16 v[58:61], v[142:145], v[188:191], v[58:61]
	v_mfma_f32_16x16x32_bf16 v[46:49], v[134:137], v[196:199], v[46:49]
	v_mfma_f32_16x16x32_bf16 v[42:45], v[142:145], v[196:199], v[42:45]
	v_mfma_f32_16x16x32_bf16 v[30:33], v[134:137], v[206:209], v[30:33]
	v_mfma_f32_16x16x32_bf16 v[26:29], v[142:145], v[206:209], v[26:29]
	v_mfma_f32_16x16x32_bf16 v[14:17], v[134:137], v[214:217], v[14:17]
	v_mfma_f32_16x16x32_bf16 v[10:13], v[142:145], v[214:217], v[10:13]
	v_mfma_f32_16x16x32_bf16 v[54:57], v[146:149], v[184:187], v[54:57]
	v_mfma_f32_16x16x32_bf16 v[50:53], v[166:169], v[184:187], v[50:53]
	v_mfma_f32_16x16x32_bf16 v[38:41], v[146:149], v[192:195], v[38:41]
	v_mfma_f32_16x16x32_bf16 v[34:37], v[166:169], v[192:195], v[34:37]
	v_mfma_f32_16x16x32_bf16 v[22:25], v[146:149], v[202:205], v[22:25]
	v_mfma_f32_16x16x32_bf16 v[18:21], v[166:169], v[202:205], v[18:21]
	v_mfma_f32_16x16x32_bf16 v[6:9], v[146:149], v[210:213], v[6:9]
	v_mfma_f32_16x16x32_bf16 v[2:5], v[166:169], v[210:213], v[2:5]
	v_mfma_f32_16x16x32_bf16 v[54:57], v[150:153], v[188:191], v[54:57]
	v_mfma_f32_16x16x32_bf16 v[50:53], v[170:173], v[188:191], v[50:53]
	v_mfma_f32_16x16x32_bf16 v[38:41], v[150:153], v[196:199], v[38:41]
	v_mfma_f32_16x16x32_bf16 v[34:37], v[170:173], v[196:199], v[34:37]
	v_mfma_f32_16x16x32_bf16 v[22:25], v[150:153], v[206:209], v[22:25]
	v_mfma_f32_16x16x32_bf16 v[18:21], v[170:173], v[206:209], v[18:21]
	v_mfma_f32_16x16x32_bf16 v[6:9], v[150:153], v[214:217], v[6:9]
	v_mfma_f32_16x16x32_bf16 v[2:5], v[170:173], v[214:217], v[2:5]
	s_setprio 0
	s_barrier
	s_add_i32 s15, s15, 2
	s_add_u32 s6, s6, 0x8000
	s_addc_u32 s7, s7, 0
	s_add_u32 s8, s8, 0x8000
	s_addc_u32 s9, s9, 0
	s_cmp_gt_u32 s15, 13
	s_cbranch_scc0 .LBB0_152
	s_and_b64 vcc, exec, s[66:67]
	s_cbranch_vccnz .LBB0_156
	v_lshl_add_u32 v166, s12, 8, v1
	s_cmp_gt_i32 s88, 3
	s_mov_b64 s[6:7], -1
	s_cbranch_scc1 .LBB0_157

; #define PG8_STAGE(bufoff, gbase, voff) do { _Pragma("unroll") for (int _i = 0; _i < 2; ++_i) \
;         __builtin_amdgcn_global_load_lds((const unsigned*)((const char*)(gbase) + (voff)[_i]), (PG8_LAS unsigned*)(lds + (bufoff) + ldsw + _i * 8192), 16, 0, 0); } while (0)
; #define PG8_LDA(dst, b, h) do { _Pragma("unroll") for (int m = 0; m < 4; ++m) _Pragma("unroll") for (int k = 0; k < 2; ++k) dst[m][k] = *(const PG8_LAS bf16x8*)(lds + PG8_SA(b, h) + aoff + m * 2048 + k * 1024); } while (0)
; #define PG8_LDB(dst, b, h) do { _Pragma("unroll") for (int n = 0; n < 2; ++n) _Pragma("unroll") for (int k = 0; k < 2; ++k) dst[n][k] = *(const PG8_LAS bf16x8*)(lds + PG8_SB(b, h) + boff + n * 2048 + k * 1024); } while (0)
; #define PG8_WAIT_V(n) asm volatile("s_waitcnt vmcnt(" #n ")" ::: "memory")
; #define PG8_WAIT_L(n) asm volatile("s_waitcnt lgkmcnt(" #n ")" ::: "memory")
; #define PG8_BAR __builtin_amdgcn_s_barrier()
; #define PG8_SCHED __builtin_amdgcn_sched_barrier(0)
; template <class Epi, class Sched, bool ALIGN_EPI = false, bool SP2 = false>
; __device__ __forceinline__ void gemm_phase(PG8_LAS unsigned char* lds, const Gemm g, const Sched& S, const Epi& E) {
;     ...
;         const bool has_next = S.next(ui + 1, nxt);
;         const char* nA = has_next ? (const char*)g.A + (size_t)nxt.pm * tstep : cA; const char* nB = has_next ? (const char*)g.Bt + (size_t)nxt.pn * tstep : cB;
;         for (int t = 0; t < nt; t += 2) {
;             const bool last = (t == nt - 2);
;             const char* a1 = cA + (size_t)(t + 1) * kstep;
;             const char* a2 = last ? nA : cA + (size_t)(t + 2) * kstep; const char* b2 = last ? nB : cB + (size_t)(t + 2) * kstep;
;             const char* a3 = a2 + kstep; const char* b3 = b2 + kstep;
;             if (last && has_next) S.a_ready(nxt);
;             if constexpr (SP2) {
;             PG8_LDB(B0, 0, 0); PG8_LDB(B1, 0, 1); PG8_SCHED; PG8_LDA(At, 0, 0); PG8_STAGE(PG8_SA(1, 1), a1 + hstep, voffA);
;             PG8_WAIT_V(8); PG8_WAIT_L(0); PG8_BAR; PG8_MMA(0, 0, At, B0); PG8_MMA(0, 1, At, B1); PG8_BAR; PG8_SCHED;
;             PG8_LDA(At, 0, 1); PG8_STAGE(PG8_SB(0, 0), b2, voffB); PG8_STAGE(PG8_SB(0, 1), b2 + hstep, voffB); PG8_STAGE(PG8_SA(0, 0), a2, voffA);
;             PG8_WAIT_V(8); PG8_WAIT_L(0); PG8_BAR; PG8_MMA(1, 0, At, B0); PG8_MMA(1, 1, At, B1); PG8_BAR; PG8_SCHED;
.LBB0_880:
	s_ashr_i32 s55, s54, 31
	s_lshl_b64 s[48:49], s[54:55], 19
	s_add_u32 s56, s8, s48
	s_addc_u32 s57, s9, s49
	s_and_b64 s[48:49], s[6:7], exec
	s_cselect_b32 s13, s57, s63
	s_cselect_b32 s48, s56, s62
	s_ashr_i32 s53, s52, 31
	s_lshl_b64 s[50:51], s[52:53], 19
	s_add_u32 s58, s10, s50
	s_addc_u32 s59, s11, s51
	s_and_b64 s[50:51], s[6:7], exec
	s_cselect_b32 s49, s59, s65
	s_cselect_b32 s50, s58, s64
	s_add_u32 s62, s62, 0x44000
	s_addc_u32 s63, s63, 0
	s_add_u32 s51, s64, 0x8000
	s_addc_u32 s53, s65, 0
	s_mov_b32 s55, -2
	s_waitcnt lgkmcnt(0)
	ds_read_b128 v[130:133], v161
	ds_read_b128 v[134:137], v161 offset:1024
	ds_read_b128 v[144:147], v161 offset:2048
	ds_read_b128 v[148:151], v161 offset:3072
	ds_read_b128 v[152:155], v162
	ds_read_b128 v[166:169], v162 offset:1024
	ds_read_b128 v[170:173], v162 offset:2048
	ds_read_b128 v[174:177], v162 offset:3072
	s_add_u32 s61, s62, 0xfffc4000
	s_addc_u32 s64, s63, -1
	s_cmp_eq_u32 s55, 12
	s_cselect_b32 s65, s13, s64
	s_cselect_b32 s64, s48, s61
	s_cselect_b32 s81, s49, s53
	s_cselect_b32 s80, s50, s51
	v_lshl_add_u64 v[158:159], s[62:63], 0, v[138:139]
	s_add_i32 m0, s1, 0xc000
	ds_read_b128 v[178:181], v163
	ds_read_b128 v[182:185], v163 offset:1024
	ds_read_b128 v[186:189], v163 offset:2048
	ds_read_b128 v[190:193], v163 offset:3072
	ds_read_b128 v[194:197], v163 offset:4096
	ds_read_b128 v[202:205], v163 offset:5120
	ds_read_b128 v[206:209], v163 offset:6144
	ds_read_b128 v[210:213], v163 offset:7168
	global_load_lds_dwordx4 v[158:159], off
	v_lshl_add_u64 v[158:159], v[158:159], 0, s[14:15]
	s_add_i32 m0, s1, 0xe000
	s_nop 0
	global_load_lds_dwordx4 v[158:159], off
	s_waitcnt vmcnt(8)
	s_waitcnt lgkmcnt(0)
	s_barrier
	s_setprio 1
	s_waitcnt lgkmcnt(0)
	v_mfma_f32_16x16x32_bf16 v[126:129], v[130:133], v[178:181], 0
	v_mfma_f32_16x16x32_bf16 v[122:125], v[144:147], v[178:181], 0
	v_mfma_f32_16x16x32_bf16 v[110:113], v[130:133], v[186:189], 0
	v_mfma_f32_16x16x32_bf16 v[106:109], v[144:147], v[186:189], 0
	v_mfma_f32_16x16x32_bf16 v[94:97], v[130:133], v[194:197], 0
	v_mfma_f32_16x16x32_bf16 v[90:93], v[144:147], v[194:197], 0
	v_mfma_f32_16x16x32_bf16 v[78:81], v[130:133], v[206:209], 0
	v_mfma_f32_16x16x32_bf16 v[74:77], v[144:147], v[206:209], 0
	v_mfma_f32_16x16x32_bf16 v[126:129], v[134:137], v[182:185], v[126:129]
	v_mfma_f32_16x16x32_bf16 v[122:125], v[148:151], v[182:185], v[122:125]
	v_mfma_f32_16x16x32_bf16 v[110:113], v[134:137], v[190:193], v[110:113]
	v_mfma_f32_16x16x32_bf16 v[106:109], v[148:151], v[190:193], v[106:109]
	v_mfma_f32_16x16x32_bf16 v[94:97], v[134:137], v[202:205], v[94:97]
	v_mfma_f32_16x16x32_bf16 v[90:93], v[148:151], v[202:205], v[90:93]
	v_mfma_f32_16x16x32_bf16 v[78:81], v[134:137], v[210:213], v[78:81]
	v_mfma_f32_16x16x32_bf16 v[74:77], v[148:151], v[210:213], v[74:77]
	v_mfma_f32_16x16x32_bf16 v[118:121], v[152:155], v[178:181], 0
	v_mfma_f32_16x16x32_bf16 v[114:117], v[170:173], v[178:181], 0
	v_mfma_f32_16x16x32_bf16 v[102:105], v[152:155], v[186:189], 0
	v_mfma_f32_16x16x32_bf16 v[98:101], v[170:173], v[186:189], 0
	v_mfma_f32_16x16x32_bf16 v[86:89], v[152:155], v[194:197], 0
	v_mfma_f32_16x16x32_bf16 v[82:85], v[170:173], v[194:197], 0
	v_mfma_f32_16x16x32_bf16 v[70:73], v[152:155], v[206:209], 0
	v_mfma_f32_16x16x32_bf16 v[66:69], v[170:173], v[206:209], 0
	v_mfma_f32_16x16x32_bf16 v[118:121], v[166:169], v[182:185], v[118:121]
	v_mfma_f32_16x16x32_bf16 v[114:117], v[174:177], v[182:185], v[114:117]
	v_mfma_f32_16x16x32_bf16 v[102:105], v[166:169], v[190:193], v[102:105]
	v_mfma_f32_16x16x32_bf16 v[98:101], v[174:177], v[190:193], v[98:101]
	v_mfma_f32_16x16x32_bf16 v[86:89], v[166:169], v[202:205], v[86:89]
	v_mfma_f32_16x16x32_bf16 v[82:85], v[174:177], v[202:205], v[82:85]
	v_mfma_f32_16x16x32_bf16 v[70:73], v[166:169], v[210:213], v[70:73]
	v_mfma_f32_16x16x32_bf16 v[66:69], v[174:177], v[210:213], v[66:69]
	s_setprio 0
	s_barrier
	s_add_i32 s61, s77, s0
	v_lshl_add_u64 v[158:159], s[80:81], 0, v[138:139]
	s_mov_b32 m0, s61
	ds_read_b128 v[178:181], v163 offset:16384
	ds_read_b128 v[182:185], v163 offset:17408
	ds_read_b128 v[186:189], v163 offset:18432
	ds_read_b128 v[190:193], v163 offset:19456
	ds_read_b128 v[194:197], v163 offset:20480
	ds_read_b128 v[202:205], v163 offset:21504
	ds_read_b128 v[206:209], v163 offset:22528
	ds_read_b128 v[210:213], v163 offset:23552
	global_load_lds_dwordx4 v[158:159], off
	v_lshl_add_u64 v[198:199], v[158:159], 0, s[14:15]
	s_add_i32 m0, s61, 0x2000
	s_add_i32 s61, s78, s0
	global_load_lds_dwordx4 v[198:199], off
	v_lshl_add_u64 v[198:199], v[158:159], 0, s[16:17]
	s_mov_b32 m0, s61
	s_nop 0
	global_load_lds_dwordx4 v[198:199], off
	v_lshl_add_u64 v[198:199], v[158:159], 0, s[20:21]
	s_add_i32 m0, s61, 0x2000
	s_nop 0
	global_load_lds_dwordx4 v[198:199], off
	v_lshl_add_u64 v[198:199], s[64:65], 0, v[138:139]
	s_mov_b32 m0, s1
	v_lshl_add_u64 v[214:215], v[198:199], 0, s[14:15]
	global_load_lds_dwordx4 v[198:199], off
	s_mov_b32 m0, s33
	s_nop 0
	global_load_lds_dwordx4 v[214:215], off
	s_waitcnt vmcnt(8)
	s_waitcnt lgkmcnt(0)
	s_barrier
; #define PG8_STAGE(bufoff, gbase, voff) do { _Pragma("unroll") for (int _i = 0; _i < 2; ++_i) \
;         __builtin_amdgcn_global_load_lds((const unsigned*)((const char*)(gbase) + (voff)[_i]), (PG8_LAS unsigned*)(lds + (bufoff) + ldsw + _i * 8192), 16, 0, 0); } while (0)
; #define PG8_LDA(dst, b, h) do { _Pragma("unroll") for (int m = 0; m < 4; ++m) _Pragma("unroll") for (int k = 0; k < 2; ++k) dst[m][k] = *(const PG8_LAS bf16x8*)(lds + PG8_SA(b, h) + aoff + m * 2048 + k * 1024); } while (0)
; #define PG8_LDB(dst, b, h) do { _Pragma("unroll") for (int n = 0; n < 2; ++n) _Pragma("unroll") for (int k = 0; k < 2; ++k) dst[n][k] = *(const PG8_LAS bf16x8*)(lds + PG8_SB(b, h) + boff + n * 2048 + k * 1024); } while (0)
; #define PG8_MMA(ai, bj, At, Bt) do { __builtin_amdgcn_s_setprio(1); _Pragma("unroll") for (int m = 0; m < 4; ++m) _Pragma("unroll") for (int n = 0; n < 2; ++n) _Pragma("unroll") for (int k = 0; k < 2; ++k) \
;         acc[ai][bj][m][n] = __builtin_amdgcn_mfma_f32_16x16x32_bf16(Bt[n][k], At[m][k], acc[ai][bj][m][n], 0, 0, 0); __builtin_amdgcn_s_setprio(0); } while (0)
; #define PG8_WAIT_V(n) asm volatile("s_waitcnt vmcnt(" #n ")" ::: "memory")
; #define PG8_WAIT_L(n) asm volatile("s_waitcnt lgkmcnt(" #n ")" ::: "memory")
; #define PG8_BAR __builtin_amdgcn_s_barrier()
; #define PG8_SCHED __builtin_amdgcn_sched_barrier(0)
; template <class Epi, class Sched, bool ALIGN_EPI = false, bool SP2 = false>
; __device__ __forceinline__ void gemm_phase(PG8_LAS unsigned char* lds, const Gemm g, const Sched& S, const Epi& E) {
;     ...
;             PG8_WAIT_V(8); PG8_WAIT_L(0); PG8_BAR; PG8_MMA(1, 0, At, B0); PG8_MMA(1, 1, At, B1); PG8_BAR; PG8_SCHED;
;             PG8_LDB(B0, 1, 0); PG8_LDB(B1, 1, 1); PG8_SCHED; PG8_LDA(At, 1, 0); PG8_STAGE(PG8_SA(0, 1), a2 + hstep, voffA);
;             PG8_WAIT_V(8); PG8_WAIT_L(0); PG8_BAR; PG8_MMA(0, 0, At, B0); PG8_MMA(0, 1, At, B1); PG8_BAR; PG8_SCHED;
	s_setprio 1
	s_waitcnt lgkmcnt(0)
	v_mfma_f32_16x16x32_bf16 v[62:65], v[130:133], v[178:181], 0
	v_mfma_f32_16x16x32_bf16 v[58:61], v[144:147], v[178:181], 0
	v_mfma_f32_16x16x32_bf16 v[46:49], v[130:133], v[186:189], 0
	v_mfma_f32_16x16x32_bf16 v[42:45], v[144:147], v[186:189], 0
	v_mfma_f32_16x16x32_bf16 v[30:33], v[130:133], v[194:197], 0
	v_mfma_f32_16x16x32_bf16 v[26:29], v[144:147], v[194:197], 0
	v_mfma_f32_16x16x32_bf16 v[14:17], v[130:133], v[206:209], 0
	v_mfma_f32_16x16x32_bf16 v[10:13], v[144:147], v[206:209], 0
	v_mfma_f32_16x16x32_bf16 v[62:65], v[134:137], v[182:185], v[62:65]
	v_mfma_f32_16x16x32_bf16 v[58:61], v[148:151], v[182:185], v[58:61]
	v_mfma_f32_16x16x32_bf16 v[46:49], v[134:137], v[190:193], v[46:49]
	v_mfma_f32_16x16x32_bf16 v[42:45], v[148:151], v[190:193], v[42:45]
	v_mfma_f32_16x16x32_bf16 v[30:33], v[134:137], v[202:205], v[30:33]
	v_mfma_f32_16x16x32_bf16 v[26:29], v[148:151], v[202:205], v[26:29]
	v_mfma_f32_16x16x32_bf16 v[14:17], v[134:137], v[210:213], v[14:17]
	v_mfma_f32_16x16x32_bf16 v[10:13], v[148:151], v[210:213], v[10:13]
	v_mfma_f32_16x16x32_bf16 v[54:57], v[152:155], v[178:181], 0
	v_mfma_f32_16x16x32_bf16 v[50:53], v[170:173], v[178:181], 0
	v_mfma_f32_16x16x32_bf16 v[38:41], v[152:155], v[186:189], 0
	v_mfma_f32_16x16x32_bf16 v[34:37], v[170:173], v[186:189], 0
	v_mfma_f32_16x16x32_bf16 v[22:25], v[152:155], v[194:197], 0
	v_mfma_f32_16x16x32_bf16 v[18:21], v[170:173], v[194:197], 0
	v_mfma_f32_16x16x32_bf16 v[6:9], v[152:155], v[206:209], 0
	v_mfma_f32_16x16x32_bf16 v[2:5], v[170:173], v[206:209], 0
	v_mfma_f32_16x16x32_bf16 v[54:57], v[166:169], v[182:185], v[54:57]
	v_mfma_f32_16x16x32_bf16 v[50:53], v[174:177], v[182:185], v[50:53]
	v_mfma_f32_16x16x32_bf16 v[38:41], v[166:169], v[190:193], v[38:41]
	v_mfma_f32_16x16x32_bf16 v[34:37], v[174:177], v[190:193], v[34:37]
	v_mfma_f32_16x16x32_bf16 v[22:25], v[166:169], v[202:205], v[22:25]
	v_mfma_f32_16x16x32_bf16 v[18:21], v[174:177], v[202:205], v[18:21]
	v_mfma_f32_16x16x32_bf16 v[6:9], v[166:169], v[210:213], v[6:9]
	v_mfma_f32_16x16x32_bf16 v[2:5], v[174:177], v[210:213], v[2:5]
	s_setprio 0
	s_barrier
	s_add_i32 s61, 0, 0x18000
	s_add_i32 s64, 0, 0x1c000
	v_add_u32_e32 v148, s61, v160
	v_add_u32_e32 v156, s64, v160
	ds_read_b128 v[130:133], v148
	ds_read_b128 v[134:137], v148 offset:1024
	ds_read_b128 v[144:147], v148 offset:2048
	ds_read_b128 v[148:151], v148 offset:3072
	ds_read_b128 v[152:155], v156
	ds_read_b128 v[166:169], v156 offset:1024
	ds_read_b128 v[170:173], v156 offset:2048
	ds_read_b128 v[174:177], v156 offset:3072
	s_mov_b32 m0, s66
	v_lshl_add_u64 v[214:215], v[198:199], 0, s[16:17]
	ds_read_b128 v[178:181], v163 offset:32768
	ds_read_b128 v[182:185], v163 offset:33792
	ds_read_b128 v[186:189], v163 offset:34816
	ds_read_b128 v[190:193], v163 offset:35840
	ds_read_b128 v[194:197], v163 offset:36864
	ds_read_b128 v[202:205], v163 offset:37888
	ds_read_b128 v[206:209], v163 offset:38912
	ds_read_b128 v[210:213], v163 offset:39936
	global_load_lds_dwordx4 v[214:215], off
	v_lshl_add_u64 v[214:215], v[198:199], 0, s[20:21]
	s_mov_b32 m0, s67
	s_nop 0
	global_load_lds_dwordx4 v[214:215], off
	s_waitcnt vmcnt(8)
	s_waitcnt lgkmcnt(0)
	s_barrier
	s_setprio 1
	s_waitcnt lgkmcnt(0)
	v_mfma_f32_16x16x32_bf16 v[126:129], v[130:133], v[178:181], v[126:129]
	v_mfma_f32_16x16x32_bf16 v[122:125], v[144:147], v[178:181], v[122:125]
	v_mfma_f32_16x16x32_bf16 v[110:113], v[130:133], v[186:189], v[110:113]
	v_mfma_f32_16x16x32_bf16 v[106:109], v[144:147], v[186:189], v[106:109]
	v_mfma_f32_16x16x32_bf16 v[94:97], v[130:133], v[194:197], v[94:97]
	v_mfma_f32_16x16x32_bf16 v[90:93], v[144:147], v[194:197], v[90:93]
	v_mfma_f32_16x16x32_bf16 v[78:81], v[130:133], v[206:209], v[78:81]
	v_mfma_f32_16x16x32_bf16 v[74:77], v[144:147], v[206:209], v[74:77]
	v_mfma_f32_16x16x32_bf16 v[126:129], v[134:137], v[182:185], v[126:129]
	v_mfma_f32_16x16x32_bf16 v[122:125], v[148:151], v[182:185], v[122:125]
	v_mfma_f32_16x16x32_bf16 v[110:113], v[134:137], v[190:193], v[110:113]
	v_mfma_f32_16x16x32_bf16 v[106:109], v[148:151], v[190:193], v[106:109]
	v_mfma_f32_16x16x32_bf16 v[94:97], v[134:137], v[202:205], v[94:97]
	v_mfma_f32_16x16x32_bf16 v[90:93], v[148:151], v[202:205], v[90:93]
	v_mfma_f32_16x16x32_bf16 v[78:81], v[134:137], v[210:213], v[78:81]
	v_mfma_f32_16x16x32_bf16 v[74:77], v[148:151], v[210:213], v[74:77]
	v_mfma_f32_16x16x32_bf16 v[118:121], v[152:155], v[178:181], v[118:121]
	v_mfma_f32_16x16x32_bf16 v[114:117], v[170:173], v[178:181], v[114:117]
	v_mfma_f32_16x16x32_bf16 v[102:105], v[152:155], v[186:189], v[102:105]
	v_mfma_f32_16x16x32_bf16 v[98:101], v[170:173], v[186:189], v[98:101]
	v_mfma_f32_16x16x32_bf16 v[86:89], v[152:155], v[194:197], v[86:89]
	v_mfma_f32_16x16x32_bf16 v[82:85], v[170:173], v[194:197], v[82:85]
	v_mfma_f32_16x16x32_bf16 v[70:73], v[152:155], v[206:209], v[70:73]
	v_mfma_f32_16x16x32_bf16 v[66:69], v[170:173], v[206:209], v[66:69]
	v_mfma_f32_16x16x32_bf16 v[118:121], v[166:169], v[182:185], v[118:121]
	v_mfma_f32_16x16x32_bf16 v[114:117], v[174:177], v[182:185], v[114:117]
	v_mfma_f32_16x16x32_bf16 v[102:105], v[166:169], v[190:193], v[102:105]
	v_mfma_f32_16x16x32_bf16 v[98:101], v[174:177], v[190:193], v[98:101]
	v_mfma_f32_16x16x32_bf16 v[86:89], v[166:169], v[202:205], v[86:89]
	v_mfma_f32_16x16x32_bf16 v[82:85], v[174:177], v[202:205], v[82:85]
	v_mfma_f32_16x16x32_bf16 v[70:73], v[166:169], v[210:213], v[70:73]
	v_mfma_f32_16x16x32_bf16 v[66:69], v[174:177], v[210:213], v[66:69]
	s_setprio 0
	s_barrier
; #define PG8_STAGE(bufoff, gbase, voff) do { _Pragma("unroll") for (int _i = 0; _i < 2; ++_i) \
;         __builtin_amdgcn_global_load_lds((const unsigned*)((const char*)(gbase) + (voff)[_i]), (PG8_LAS unsigned*)(lds + (bufoff) + ldsw + _i * 8192), 16, 0, 0); } while (0)
; #define PG8_LDA(dst, b, h) do { _Pragma("unroll") for (int m = 0; m < 4; ++m) _Pragma("unroll") for (int k = 0; k < 2; ++k) dst[m][k] = *(const PG8_LAS bf16x8*)(lds + PG8_SA(b, h) + aoff + m * 2048 + k * 1024); } while (0)
; #define PG8_LDB(dst, b, h) do { _Pragma("unroll") for (int n = 0; n < 2; ++n) _Pragma("unroll") for (int k = 0; k < 2; ++k) dst[n][k] = *(const PG8_LAS bf16x8*)(lds + PG8_SB(b, h) + boff + n * 2048 + k * 1024); } while (0)
; #define PG8_MMA(ai, bj, At, Bt) do { __builtin_amdgcn_s_setprio(1); _Pragma("unroll") for (int m = 0; m < 4; ++m) _Pragma("unroll") for (int n = 0; n < 2; ++n) _Pragma("unroll") for (int k = 0; k < 2; ++k) \
;         acc[ai][bj][m][n] = __builtin_amdgcn_mfma_f32_16x16x32_bf16(Bt[n][k], At[m][k], acc[ai][bj][m][n], 0, 0, 0); __builtin_amdgcn_s_setprio(0); } while (0)
; #define PG8_WAIT_V(n) asm volatile("s_waitcnt vmcnt(" #n ")" ::: "memory")
; #define PG8_WAIT_L(n) asm volatile("s_waitcnt lgkmcnt(" #n ")" ::: "memory")
; #define PG8_BAR __builtin_amdgcn_s_barrier()
; #define PG8_SCHED __builtin_amdgcn_sched_barrier(0)
; template <class Epi, class Sched, bool ALIGN_EPI = false, bool SP2 = false>
; __device__ __forceinline__ void gemm_phase(PG8_LAS unsigned char* lds, const Gemm g, const Sched& S, const Epi& E) {
;     ...
;             PG8_LDB(B0, 0, 0); PG8_LDB(B1, 0, 1); PG8_SCHED; PG8_LDA(At, 0, 0); PG8_STAGE(PG8_SA(1, 1), a1 + hstep, voffA);
;             PG8_WAIT_V(8); PG8_WAIT_L(0); PG8_BAR; PG8_MMA(0, 0, At, B0); PG8_MMA(0, 1, At, B1); PG8_BAR; PG8_SCHED;
;     ...
;             PG8_LDA(At, 1, 1); PG8_STAGE(PG8_SB(1, 0), b3, voffB); PG8_STAGE(PG8_SB(1, 1), b3 + hstep, voffB); PG8_STAGE(PG8_SA(1, 0), a3, voffA);
;             PG8_WAIT_V(8); PG8_WAIT_L(0); PG8_BAR; PG8_MMA(1, 0, At, B0); PG8_MMA(1, 1, At, B1); PG8_BAR; PG8_SCHED;
	s_add_i32 s61, s61, s0
	v_lshl_add_u64 v[214:215], v[158:159], 0, s[28:29]
	s_mov_b32 m0, s61
	ds_read_b128 v[178:181], v163 offset:49152
	ds_read_b128 v[182:185], v163 offset:50176
	ds_read_b128 v[186:189], v163 offset:51200
	ds_read_b128 v[190:193], v163 offset:52224
	ds_read_b128 v[194:197], v163 offset:53248
	ds_read_b128 v[202:205], v163 offset:54272
	ds_read_b128 v[206:209], v163 offset:55296
	ds_read_b128 v[210:213], v163 offset:56320
	global_load_lds_dwordx4 v[214:215], off
	v_lshl_add_u64 v[214:215], v[158:159], 0, s[30:31]
	s_add_i32 m0, s61, 0x2000
	s_add_i32 s61, s64, s0
	global_load_lds_dwordx4 v[214:215], off
	v_lshl_add_u64 v[214:215], v[158:159], 0, s[34:35]
	s_mov_b32 m0, s61
	v_lshl_add_u64 v[158:159], v[158:159], 0, s[36:37]
	global_load_lds_dwordx4 v[214:215], off
	s_add_i32 m0, s61, 0x2000
	s_nop 0
	global_load_lds_dwordx4 v[158:159], off
	v_lshl_add_u64 v[158:159], v[198:199], 0, s[28:29]
	s_mov_b32 m0, s69
	s_nop 0
	global_load_lds_dwordx4 v[158:159], off
	v_lshl_add_u64 v[158:159], v[198:199], 0, s[30:31]
	s_mov_b32 m0, s70
	s_nop 0
	global_load_lds_dwordx4 v[158:159], off
	s_waitcnt vmcnt(8)
	s_waitcnt lgkmcnt(0)
	s_barrier
	s_setprio 1
	s_waitcnt lgkmcnt(0)
	v_mfma_f32_16x16x32_bf16 v[62:65], v[130:133], v[178:181], v[62:65]
	v_mfma_f32_16x16x32_bf16 v[58:61], v[144:147], v[178:181], v[58:61]
	v_mfma_f32_16x16x32_bf16 v[46:49], v[130:133], v[186:189], v[46:49]
	v_mfma_f32_16x16x32_bf16 v[42:45], v[144:147], v[186:189], v[42:45]
	v_mfma_f32_16x16x32_bf16 v[30:33], v[130:133], v[194:197], v[30:33]
	v_mfma_f32_16x16x32_bf16 v[26:29], v[144:147], v[194:197], v[26:29]
	v_mfma_f32_16x16x32_bf16 v[14:17], v[130:133], v[206:209], v[14:17]
	v_mfma_f32_16x16x32_bf16 v[10:13], v[144:147], v[206:209], v[10:13]
	v_mfma_f32_16x16x32_bf16 v[62:65], v[134:137], v[182:185], v[62:65]
	v_mfma_f32_16x16x32_bf16 v[58:61], v[148:151], v[182:185], v[58:61]
	v_mfma_f32_16x16x32_bf16 v[46:49], v[134:137], v[190:193], v[46:49]
	v_mfma_f32_16x16x32_bf16 v[42:45], v[148:151], v[190:193], v[42:45]
	v_mfma_f32_16x16x32_bf16 v[30:33], v[134:137], v[202:205], v[30:33]
	v_mfma_f32_16x16x32_bf16 v[26:29], v[148:151], v[202:205], v[26:29]
	v_mfma_f32_16x16x32_bf16 v[14:17], v[134:137], v[210:213], v[14:17]
	v_mfma_f32_16x16x32_bf16 v[10:13], v[148:151], v[210:213], v[10:13]
	v_mfma_f32_16x16x32_bf16 v[54:57], v[152:155], v[178:181], v[54:57]
	v_mfma_f32_16x16x32_bf16 v[50:53], v[170:173], v[178:181], v[50:53]
	v_mfma_f32_16x16x32_bf16 v[38:41], v[152:155], v[186:189], v[38:41]
	v_mfma_f32_16x16x32_bf16 v[34:37], v[170:173], v[186:189], v[34:37]
	v_mfma_f32_16x16x32_bf16 v[22:25], v[152:155], v[194:197], v[22:25]
	v_mfma_f32_16x16x32_bf16 v[18:21], v[170:173], v[194:197], v[18:21]
	v_mfma_f32_16x16x32_bf16 v[6:9], v[152:155], v[206:209], v[6:9]
	v_mfma_f32_16x16x32_bf16 v[2:5], v[170:173], v[206:209], v[2:5]
	v_mfma_f32_16x16x32_bf16 v[54:57], v[166:169], v[182:185], v[54:57]
	v_mfma_f32_16x16x32_bf16 v[50:53], v[174:177], v[182:185], v[50:53]
	v_mfma_f32_16x16x32_bf16 v[38:41], v[166:169], v[190:193], v[38:41]
	v_mfma_f32_16x16x32_bf16 v[34:37], v[174:177], v[190:193], v[34:37]
	v_mfma_f32_16x16x32_bf16 v[22:25], v[166:169], v[202:205], v[22:25]
	v_mfma_f32_16x16x32_bf16 v[18:21], v[174:177], v[202:205], v[18:21]
	v_mfma_f32_16x16x32_bf16 v[6:9], v[166:169], v[210:213], v[6:9]
	v_mfma_f32_16x16x32_bf16 v[2:5], v[174:177], v[210:213], v[2:5]
	s_setprio 0
	s_barrier
	s_add_i32 s55, s55, 2
	s_add_u32 s62, s62, 0x8000
	s_addc_u32 s63, s63, 0
	s_add_u32 s51, s51, 0x8000
	s_addc_u32 s53, s53, 0
	s_cmp_gt_u32 s55, 13
	s_cbranch_scc0 .LBB0_881
.LBB0_881:
	ds_read_b128 v[130:133], v161
	ds_read_b128 v[134:137], v161 offset:1024
	ds_read_b128 v[144:147], v161 offset:2048
	ds_read_b128 v[148:151], v161 offset:3072
	ds_read_b128 v[152:155], v162
	ds_read_b128 v[166:169], v162 offset:1024
	ds_read_b128 v[170:173], v162 offset:2048
	ds_read_b128 v[174:177], v162 offset:3072
	s_add_u32 s61, s62, 0xfffc4000
	s_addc_u32 s64, s63, -1
	s_cmp_eq_u32 s55, 12
	s_cselect_b32 s65, s13, s64
	s_cselect_b32 s64, s48, s61
	s_cselect_b32 s81, s49, s53
	s_cselect_b32 s80, s50, s51
	v_lshl_add_u64 v[158:159], s[62:63], 0, v[138:139]
	s_add_i32 m0, s1, 0xc000
	ds_read_b128 v[178:181], v163
	ds_read_b128 v[182:185], v163 offset:1024
	ds_read_b128 v[186:189], v163 offset:2048
	ds_read_b128 v[190:193], v163 offset:3072
	ds_read_b128 v[194:197], v163 offset:4096
	ds_read_b128 v[202:205], v163 offset:5120
	ds_read_b128 v[206:209], v163 offset:6144
	ds_read_b128 v[210:213], v163 offset:7168
	global_load_lds_dwordx4 v[158:159], off
	v_lshl_add_u64 v[158:159], v[158:159], 0, s[14:15]
	s_add_i32 m0, s1, 0xe000
	s_nop 0
	global_load_lds_dwordx4 v[158:159], off
	s_waitcnt vmcnt(8)
	s_waitcnt lgkmcnt(0)
	s_barrier
; #define PG8_STAGE(bufoff, gbase, voff) do { _Pragma("unroll") for (int _i = 0; _i < 2; ++_i) \
;         __builtin_amdgcn_global_load_lds((const unsigned*)((const char*)(gbase) + (voff)[_i]), (PG8_LAS unsigned*)(lds + (bufoff) + ldsw + _i * 8192), 16, 0, 0); } while (0)
; #define PG8_LDA(dst, b, h) do { _Pragma("unroll") for (int m = 0; m < 4; ++m) _Pragma("unroll") for (int k = 0; k < 2; ++k) dst[m][k] = *(const PG8_LAS bf16x8*)(lds + PG8_SA(b, h) + aoff + m * 2048 + k * 1024); } while (0)
; #define PG8_LDB(dst, b, h) do { _Pragma("unroll") for (int n = 0; n < 2; ++n) _Pragma("unroll") for (int k = 0; k < 2; ++k) dst[n][k] = *(const PG8_LAS bf16x8*)(lds + PG8_SB(b, h) + boff + n * 2048 + k * 1024); } while (0)
; #define PG8_MMA(ai, bj, At, Bt) do { __builtin_amdgcn_s_setprio(1); _Pragma("unroll") for (int m = 0; m < 4; ++m) _Pragma("unroll") for (int n = 0; n < 2; ++n) _Pragma("unroll") for (int k = 0; k < 2; ++k) \
;         acc[ai][bj][m][n] = __builtin_amdgcn_mfma_f32_16x16x32_bf16(Bt[n][k], At[m][k], acc[ai][bj][m][n], 0, 0, 0); __builtin_amdgcn_s_setprio(0); } while (0)
; #define PG8_WAIT_V(n) asm volatile("s_waitcnt vmcnt(" #n ")" ::: "memory")
; #define PG8_WAIT_L(n) asm volatile("s_waitcnt lgkmcnt(" #n ")" ::: "memory")
; #define PG8_BAR __builtin_amdgcn_s_barrier()
; #define PG8_SCHED __builtin_amdgcn_sched_barrier(0)
; template <class Epi, class Sched, bool ALIGN_EPI = false, bool SP2 = false>
; __device__ __forceinline__ void gemm_phase(PG8_LAS unsigned char* lds, const Gemm g, const Sched& S, const Epi& E) {
;     ...
;             PG8_WAIT_V(8); PG8_WAIT_L(0); PG8_BAR; PG8_MMA(0, 0, At, B0); PG8_MMA(0, 1, At, B1); PG8_BAR; PG8_SCHED;
;             PG8_LDA(At, 0, 1); PG8_STAGE(PG8_SB(0, 0), b2, voffB); PG8_STAGE(PG8_SB(0, 1), b2 + hstep, voffB); PG8_STAGE(PG8_SA(0, 0), a2, voffA);
;             PG8_WAIT_V(8); PG8_WAIT_L(0); PG8_BAR; PG8_MMA(1, 0, At, B0); PG8_MMA(1, 1, At, B1); PG8_BAR; PG8_SCHED;
;             PG8_LDB(B0, 1, 0); PG8_LDB(B1, 1, 1); PG8_SCHED; PG8_LDA(At, 1, 0); PG8_STAGE(PG8_SA(0, 1), a2 + hstep, voffA);
;             PG8_WAIT_V(8); PG8_WAIT_L(0); PG8_BAR; PG8_MMA(0, 0, At, B0); PG8_MMA(0, 1, At, B1); PG8_BAR; PG8_SCHED;
	s_setprio 1
	s_waitcnt lgkmcnt(0)
	v_mfma_f32_16x16x32_bf16 v[126:129], v[130:133], v[178:181], v[126:129]
	v_mfma_f32_16x16x32_bf16 v[122:125], v[144:147], v[178:181], v[122:125]
	v_mfma_f32_16x16x32_bf16 v[110:113], v[130:133], v[186:189], v[110:113]
	v_mfma_f32_16x16x32_bf16 v[106:109], v[144:147], v[186:189], v[106:109]
	v_mfma_f32_16x16x32_bf16 v[94:97], v[130:133], v[194:197], v[94:97]
	v_mfma_f32_16x16x32_bf16 v[90:93], v[144:147], v[194:197], v[90:93]
	v_mfma_f32_16x16x32_bf16 v[78:81], v[130:133], v[206:209], v[78:81]
	v_mfma_f32_16x16x32_bf16 v[74:77], v[144:147], v[206:209], v[74:77]
	v_mfma_f32_16x16x32_bf16 v[126:129], v[134:137], v[182:185], v[126:129]
	v_mfma_f32_16x16x32_bf16 v[122:125], v[148:151], v[182:185], v[122:125]
	v_mfma_f32_16x16x32_bf16 v[110:113], v[134:137], v[190:193], v[110:113]
	v_mfma_f32_16x16x32_bf16 v[106:109], v[148:151], v[190:193], v[106:109]
	v_mfma_f32_16x16x32_bf16 v[94:97], v[134:137], v[202:205], v[94:97]
	v_mfma_f32_16x16x32_bf16 v[90:93], v[148:151], v[202:205], v[90:93]
	v_mfma_f32_16x16x32_bf16 v[78:81], v[134:137], v[210:213], v[78:81]
	v_mfma_f32_16x16x32_bf16 v[74:77], v[148:151], v[210:213], v[74:77]
	v_mfma_f32_16x16x32_bf16 v[118:121], v[152:155], v[178:181], v[118:121]
	v_mfma_f32_16x16x32_bf16 v[114:117], v[170:173], v[178:181], v[114:117]
	v_mfma_f32_16x16x32_bf16 v[102:105], v[152:155], v[186:189], v[102:105]
	v_mfma_f32_16x16x32_bf16 v[98:101], v[170:173], v[186:189], v[98:101]
	v_mfma_f32_16x16x32_bf16 v[86:89], v[152:155], v[194:197], v[86:89]
	v_mfma_f32_16x16x32_bf16 v[82:85], v[170:173], v[194:197], v[82:85]
	v_mfma_f32_16x16x32_bf16 v[70:73], v[152:155], v[206:209], v[70:73]
	v_mfma_f32_16x16x32_bf16 v[66:69], v[170:173], v[206:209], v[66:69]
	v_mfma_f32_16x16x32_bf16 v[118:121], v[166:169], v[182:185], v[118:121]
	v_mfma_f32_16x16x32_bf16 v[114:117], v[174:177], v[182:185], v[114:117]
	v_mfma_f32_16x16x32_bf16 v[102:105], v[166:169], v[190:193], v[102:105]
	v_mfma_f32_16x16x32_bf16 v[98:101], v[174:177], v[190:193], v[98:101]
	v_mfma_f32_16x16x32_bf16 v[86:89], v[166:169], v[202:205], v[86:89]
	v_mfma_f32_16x16x32_bf16 v[82:85], v[174:177], v[202:205], v[82:85]
	v_mfma_f32_16x16x32_bf16 v[70:73], v[166:169], v[210:213], v[70:73]
	v_mfma_f32_16x16x32_bf16 v[66:69], v[174:177], v[210:213], v[66:69]
	s_setprio 0
	s_barrier
	s_add_i32 s61, s77, s0
	v_lshl_add_u64 v[158:159], s[80:81], 0, v[138:139]
	s_mov_b32 m0, s61
	ds_read_b128 v[178:181], v163 offset:16384
	ds_read_b128 v[182:185], v163 offset:17408
	ds_read_b128 v[186:189], v163 offset:18432
	ds_read_b128 v[190:193], v163 offset:19456
	ds_read_b128 v[194:197], v163 offset:20480
	ds_read_b128 v[202:205], v163 offset:21504
	ds_read_b128 v[206:209], v163 offset:22528
	ds_read_b128 v[210:213], v163 offset:23552
	global_load_lds_dwordx4 v[158:159], off
	v_lshl_add_u64 v[198:199], v[158:159], 0, s[14:15]
	s_add_i32 m0, s61, 0x2000
	s_add_i32 s61, s78, s0
	global_load_lds_dwordx4 v[198:199], off
	v_lshl_add_u64 v[198:199], v[158:159], 0, s[16:17]
	s_mov_b32 m0, s61
	s_nop 0
	global_load_lds_dwordx4 v[198:199], off
	v_lshl_add_u64 v[198:199], v[158:159], 0, s[20:21]
	s_add_i32 m0, s61, 0x2000
	s_nop 0
	global_load_lds_dwordx4 v[198:199], off
	v_lshl_add_u64 v[198:199], s[64:65], 0, v[138:139]
	s_mov_b32 m0, s1
	v_lshl_add_u64 v[214:215], v[198:199], 0, s[14:15]
	global_load_lds_dwordx4 v[198:199], off
	s_mov_b32 m0, s33
	s_nop 0
	global_load_lds_dwordx4 v[214:215], off
	s_waitcnt vmcnt(8)
	s_waitcnt lgkmcnt(0)
	s_barrier
	s_setprio 1
	s_waitcnt lgkmcnt(0)
	v_mfma_f32_16x16x32_bf16 v[62:65], v[130:133], v[178:181], v[62:65]
	v_mfma_f32_16x16x32_bf16 v[58:61], v[144:147], v[178:181], v[58:61]
	v_mfma_f32_16x16x32_bf16 v[46:49], v[130:133], v[186:189], v[46:49]
	v_mfma_f32_16x16x32_bf16 v[42:45], v[144:147], v[186:189], v[42:45]
	v_mfma_f32_16x16x32_bf16 v[30:33], v[130:133], v[194:197], v[30:33]
	v_mfma_f32_16x16x32_bf16 v[26:29], v[144:147], v[194:197], v[26:29]
	v_mfma_f32_16x16x32_bf16 v[14:17], v[130:133], v[206:209], v[14:17]
	v_mfma_f32_16x16x32_bf16 v[10:13], v[144:147], v[206:209], v[10:13]
	v_mfma_f32_16x16x32_bf16 v[62:65], v[134:137], v[182:185], v[62:65]
	v_mfma_f32_16x16x32_bf16 v[58:61], v[148:151], v[182:185], v[58:61]
	v_mfma_f32_16x16x32_bf16 v[46:49], v[134:137], v[190:193], v[46:49]
	v_mfma_f32_16x16x32_bf16 v[42:45], v[148:151], v[190:193], v[42:45]
	v_mfma_f32_16x16x32_bf16 v[30:33], v[134:137], v[202:205], v[30:33]
	v_mfma_f32_16x16x32_bf16 v[26:29], v[148:151], v[202:205], v[26:29]
	v_mfma_f32_16x16x32_bf16 v[14:17], v[134:137], v[210:213], v[14:17]
	v_mfma_f32_16x16x32_bf16 v[10:13], v[148:151], v[210:213], v[10:13]
	v_mfma_f32_16x16x32_bf16 v[54:57], v[152:155], v[178:181], v[54:57]
	v_mfma_f32_16x16x32_bf16 v[50:53], v[170:173], v[178:181], v[50:53]
	v_mfma_f32_16x16x32_bf16 v[38:41], v[152:155], v[186:189], v[38:41]
	v_mfma_f32_16x16x32_bf16 v[34:37], v[170:173], v[186:189], v[34:37]
	v_mfma_f32_16x16x32_bf16 v[22:25], v[152:155], v[194:197], v[22:25]
	v_mfma_f32_16x16x32_bf16 v[18:21], v[170:173], v[194:197], v[18:21]
	v_mfma_f32_16x16x32_bf16 v[6:9], v[152:155], v[206:209], v[6:9]
	v_mfma_f32_16x16x32_bf16 v[2:5], v[170:173], v[206:209], v[2:5]
	v_mfma_f32_16x16x32_bf16 v[54:57], v[166:169], v[182:185], v[54:57]
	v_mfma_f32_16x16x32_bf16 v[50:53], v[174:177], v[182:185], v[50:53]
	v_mfma_f32_16x16x32_bf16 v[38:41], v[166:169], v[190:193], v[38:41]
	v_mfma_f32_16x16x32_bf16 v[34:37], v[174:177], v[190:193], v[34:37]
	v_mfma_f32_16x16x32_bf16 v[22:25], v[166:169], v[202:205], v[22:25]
	v_mfma_f32_16x16x32_bf16 v[18:21], v[174:177], v[202:205], v[18:21]
	v_mfma_f32_16x16x32_bf16 v[6:9], v[166:169], v[210:213], v[6:9]
	v_mfma_f32_16x16x32_bf16 v[2:5], v[174:177], v[210:213], v[2:5]
	s_setprio 0
	s_barrier
; #define PG8_STAGE(bufoff, gbase, voff) do { _Pragma("unroll") for (int _i = 0; _i < 2; ++_i) \
;         __builtin_amdgcn_global_load_lds((const unsigned*)((const char*)(gbase) + (voff)[_i]), (PG8_LAS unsigned*)(lds + (bufoff) + ldsw + _i * 8192), 16, 0, 0); } while (0)
; #define PG8_LDA(dst, b, h) do { _Pragma("unroll") for (int m = 0; m < 4; ++m) _Pragma("unroll") for (int k = 0; k < 2; ++k) dst[m][k] = *(const PG8_LAS bf16x8*)(lds + PG8_SA(b, h) + aoff + m * 2048 + k * 1024); } while (0)
; #define PG8_LDB(dst, b, h) do { _Pragma("unroll") for (int n = 0; n < 2; ++n) _Pragma("unroll") for (int k = 0; k < 2; ++k) dst[n][k] = *(const PG8_LAS bf16x8*)(lds + PG8_SB(b, h) + boff + n * 2048 + k * 1024); } while (0)
; #define PG8_MMA(ai, bj, At, Bt) do { __builtin_amdgcn_s_setprio(1); _Pragma("unroll") for (int m = 0; m < 4; ++m) _Pragma("unroll") for (int n = 0; n < 2; ++n) _Pragma("unroll") for (int k = 0; k < 2; ++k) \
;         acc[ai][bj][m][n] = __builtin_amdgcn_mfma_f32_16x16x32_bf16(Bt[n][k], At[m][k], acc[ai][bj][m][n], 0, 0, 0); __builtin_amdgcn_s_setprio(0); } while (0)
; #define PG8_WAIT_V(n) asm volatile("s_waitcnt vmcnt(" #n ")" ::: "memory")
; #define PG8_WAIT_L(n) asm volatile("s_waitcnt lgkmcnt(" #n ")" ::: "memory")
; #define PG8_BAR __builtin_amdgcn_s_barrier()
; #define PG8_SCHED __builtin_amdgcn_sched_barrier(0)
; template <class Epi, class Sched, bool ALIGN_EPI = false, bool SP2 = false>
; __device__ __forceinline__ void gemm_phase(PG8_LAS unsigned char* lds, const Gemm g, const Sched& S, const Epi& E) {
;     ...
;             PG8_LDB(B0, 1, 0); PG8_LDB(B1, 1, 1); PG8_SCHED; PG8_LDA(At, 1, 0); PG8_STAGE(PG8_SA(0, 1), a2 + hstep, voffA);
;             PG8_WAIT_V(8); PG8_WAIT_L(0); PG8_BAR; PG8_MMA(0, 0, At, B0); PG8_MMA(0, 1, At, B1); PG8_BAR; PG8_SCHED;
	s_add_i32 s61, 0, 0x18000
	s_add_i32 s64, 0, 0x1c000
	v_add_u32_e32 v148, s61, v160
	v_add_u32_e32 v156, s64, v160
	ds_read_b128 v[130:133], v148
	ds_read_b128 v[134:137], v148 offset:1024
	ds_read_b128 v[144:147], v148 offset:2048
	ds_read_b128 v[148:151], v148 offset:3072
	ds_read_b128 v[152:155], v156
	ds_read_b128 v[166:169], v156 offset:1024
	ds_read_b128 v[170:173], v156 offset:2048
	ds_read_b128 v[174:177], v156 offset:3072
	s_mov_b32 m0, s66
	v_lshl_add_u64 v[214:215], v[198:199], 0, s[16:17]
	ds_read_b128 v[178:181], v163 offset:32768
	ds_read_b128 v[182:185], v163 offset:33792
	ds_read_b128 v[186:189], v163 offset:34816
	ds_read_b128 v[190:193], v163 offset:35840
	ds_read_b128 v[194:197], v163 offset:36864
	ds_read_b128 v[202:205], v163 offset:37888
	ds_read_b128 v[206:209], v163 offset:38912
	ds_read_b128 v[210:213], v163 offset:39936
	global_load_lds_dwordx4 v[214:215], off
	v_lshl_add_u64 v[214:215], v[198:199], 0, s[20:21]
	s_mov_b32 m0, s67
	s_nop 0
	global_load_lds_dwordx4 v[214:215], off
	s_waitcnt vmcnt(8)
	s_waitcnt lgkmcnt(0)
	s_barrier
	s_setprio 1
	s_waitcnt lgkmcnt(0)
	v_mfma_f32_16x16x32_bf16 v[126:129], v[130:133], v[178:181], v[126:129]
	v_mfma_f32_16x16x32_bf16 v[122:125], v[144:147], v[178:181], v[122:125]
	v_mfma_f32_16x16x32_bf16 v[110:113], v[130:133], v[186:189], v[110:113]
	v_mfma_f32_16x16x32_bf16 v[106:109], v[144:147], v[186:189], v[106:109]
	v_mfma_f32_16x16x32_bf16 v[94:97], v[130:133], v[194:197], v[94:97]
	v_mfma_f32_16x16x32_bf16 v[90:93], v[144:147], v[194:197], v[90:93]
	v_mfma_f32_16x16x32_bf16 v[78:81], v[130:133], v[206:209], v[78:81]
	v_mfma_f32_16x16x32_bf16 v[74:77], v[144:147], v[206:209], v[74:77]
	v_mfma_f32_16x16x32_bf16 v[126:129], v[134:137], v[182:185], v[126:129]
	v_mfma_f32_16x16x32_bf16 v[122:125], v[148:151], v[182:185], v[122:125]
	v_mfma_f32_16x16x32_bf16 v[110:113], v[134:137], v[190:193], v[110:113]
	v_mfma_f32_16x16x32_bf16 v[106:109], v[148:151], v[190:193], v[106:109]
	v_mfma_f32_16x16x32_bf16 v[94:97], v[134:137], v[202:205], v[94:97]
	v_mfma_f32_16x16x32_bf16 v[90:93], v[148:151], v[202:205], v[90:93]
	v_mfma_f32_16x16x32_bf16 v[78:81], v[134:137], v[210:213], v[78:81]
	v_mfma_f32_16x16x32_bf16 v[74:77], v[148:151], v[210:213], v[74:77]
	v_mfma_f32_16x16x32_bf16 v[118:121], v[152:155], v[178:181], v[118:121]
	v_mfma_f32_16x16x32_bf16 v[114:117], v[170:173], v[178:181], v[114:117]
	v_mfma_f32_16x16x32_bf16 v[102:105], v[152:155], v[186:189], v[102:105]
	v_mfma_f32_16x16x32_bf16 v[98:101], v[170:173], v[186:189], v[98:101]
	v_mfma_f32_16x16x32_bf16 v[86:89], v[152:155], v[194:197], v[86:89]
	v_mfma_f32_16x16x32_bf16 v[82:85], v[170:173], v[194:197], v[82:85]
	v_mfma_f32_16x16x32_bf16 v[70:73], v[152:155], v[206:209], v[70:73]
	v_mfma_f32_16x16x32_bf16 v[66:69], v[170:173], v[206:209], v[66:69]
	v_mfma_f32_16x16x32_bf16 v[118:121], v[166:169], v[182:185], v[118:121]
	v_mfma_f32_16x16x32_bf16 v[114:117], v[174:177], v[182:185], v[114:117]
	v_mfma_f32_16x16x32_bf16 v[102:105], v[166:169], v[190:193], v[102:105]
	v_mfma_f32_16x16x32_bf16 v[98:101], v[174:177], v[190:193], v[98:101]
	v_mfma_f32_16x16x32_bf16 v[86:89], v[166:169], v[202:205], v[86:89]
	v_mfma_f32_16x16x32_bf16 v[82:85], v[174:177], v[202:205], v[82:85]
	v_mfma_f32_16x16x32_bf16 v[70:73], v[166:169], v[210:213], v[70:73]
	v_mfma_f32_16x16x32_bf16 v[66:69], v[174:177], v[210:213], v[66:69]
	s_setprio 0
	s_barrier
; #define PG8_STAGE(bufoff, gbase, voff) do { _Pragma("unroll") for (int _i = 0; _i < 2; ++_i) \
;         __builtin_amdgcn_global_load_lds((const unsigned*)((const char*)(gbase) + (voff)[_i]), (PG8_LAS unsigned*)(lds + (bufoff) + ldsw + _i * 8192), 16, 0, 0); } while (0)
; #define PG8_LDA(dst, b, h) do { _Pragma("unroll") for (int m = 0; m < 4; ++m) _Pragma("unroll") for (int k = 0; k < 2; ++k) dst[m][k] = *(const PG8_LAS bf16x8*)(lds + PG8_SA(b, h) + aoff + m * 2048 + k * 1024); } while (0)
; #define PG8_MMA(ai, bj, At, Bt) do { __builtin_amdgcn_s_setprio(1); _Pragma("unroll") for (int m = 0; m < 4; ++m) _Pragma("unroll") for (int n = 0; n < 2; ++n) _Pragma("unroll") for (int k = 0; k < 2; ++k) \
;         acc[ai][bj][m][n] = __builtin_amdgcn_mfma_f32_16x16x32_bf16(Bt[n][k], At[m][k], acc[ai][bj][m][n], 0, 0, 0); __builtin_amdgcn_s_setprio(0); } while (0)
; #define PG8_WAIT_V(n) asm volatile("s_waitcnt vmcnt(" #n ")" ::: "memory")
; #define PG8_WAIT_L(n) asm volatile("s_waitcnt lgkmcnt(" #n ")" ::: "memory")
; #define PG8_BAR __builtin_amdgcn_s_barrier()
; #define PG8_SCHED __builtin_amdgcn_sched_barrier(0)
; template <class Epi, class Sched, bool ALIGN_EPI = false, bool SP2 = false>
; __device__ __forceinline__ void gemm_phase(PG8_LAS unsigned char* lds, const Gemm g, const Sched& S, const Epi& E) {
;     ...
;             PG8_LDA(At, 1, 1); PG8_STAGE(PG8_SB(1, 0), b3, voffB); PG8_STAGE(PG8_SB(1, 1), b3 + hstep, voffB); PG8_STAGE(PG8_SA(1, 0), a3, voffA);
;             PG8_WAIT_V(8); PG8_WAIT_L(0); PG8_BAR; PG8_MMA(1, 0, At, B0); PG8_MMA(1, 1, At, B1); PG8_BAR; PG8_SCHED;
;     ...
;         if constexpr (ALIGN_EPI) { if (wr == 0) PG8_BAR; }
	s_add_i32 s61, s61, s0
	v_lshl_add_u64 v[214:215], v[158:159], 0, s[28:29]
	s_mov_b32 m0, s61
	ds_read_b128 v[178:181], v163 offset:49152
	ds_read_b128 v[182:185], v163 offset:50176
	ds_read_b128 v[186:189], v163 offset:51200
	ds_read_b128 v[190:193], v163 offset:52224
	ds_read_b128 v[194:197], v163 offset:53248
	ds_read_b128 v[202:205], v163 offset:54272
	ds_read_b128 v[206:209], v163 offset:55296
	ds_read_b128 v[210:213], v163 offset:56320
	global_load_lds_dwordx4 v[214:215], off
	v_lshl_add_u64 v[214:215], v[158:159], 0, s[30:31]
	s_add_i32 m0, s61, 0x2000
	s_add_i32 s61, s64, s0
	global_load_lds_dwordx4 v[214:215], off
	v_lshl_add_u64 v[214:215], v[158:159], 0, s[34:35]
	s_mov_b32 m0, s61
	v_lshl_add_u64 v[158:159], v[158:159], 0, s[36:37]
	global_load_lds_dwordx4 v[214:215], off
	s_add_i32 m0, s61, 0x2000
	s_nop 0
	global_load_lds_dwordx4 v[158:159], off
	v_lshl_add_u64 v[158:159], v[198:199], 0, s[28:29]
	s_mov_b32 m0, s69
	s_nop 0
	global_load_lds_dwordx4 v[158:159], off
	v_lshl_add_u64 v[158:159], v[198:199], 0, s[30:31]
	s_mov_b32 m0, s70
	s_nop 0
	global_load_lds_dwordx4 v[158:159], off
	s_waitcnt vmcnt(8)
	s_waitcnt lgkmcnt(0)
	s_barrier
	s_setprio 1
	s_waitcnt lgkmcnt(0)
	v_mfma_f32_16x16x32_bf16 v[62:65], v[130:133], v[178:181], v[62:65]
	v_mfma_f32_16x16x32_bf16 v[58:61], v[144:147], v[178:181], v[58:61]
	v_mfma_f32_16x16x32_bf16 v[46:49], v[130:133], v[186:189], v[46:49]
	v_mfma_f32_16x16x32_bf16 v[42:45], v[144:147], v[186:189], v[42:45]
	v_mfma_f32_16x16x32_bf16 v[30:33], v[130:133], v[194:197], v[30:33]
	v_mfma_f32_16x16x32_bf16 v[26:29], v[144:147], v[194:197], v[26:29]
	v_mfma_f32_16x16x32_bf16 v[14:17], v[130:133], v[206:209], v[14:17]
	v_mfma_f32_16x16x32_bf16 v[10:13], v[144:147], v[206:209], v[10:13]
	v_mfma_f32_16x16x32_bf16 v[62:65], v[134:137], v[182:185], v[62:65]
	v_mfma_f32_16x16x32_bf16 v[58:61], v[148:151], v[182:185], v[58:61]
	v_mfma_f32_16x16x32_bf16 v[46:49], v[134:137], v[190:193], v[46:49]
	v_mfma_f32_16x16x32_bf16 v[42:45], v[148:151], v[190:193], v[42:45]
	v_mfma_f32_16x16x32_bf16 v[30:33], v[134:137], v[202:205], v[30:33]
	v_mfma_f32_16x16x32_bf16 v[26:29], v[148:151], v[202:205], v[26:29]
	v_mfma_f32_16x16x32_bf16 v[14:17], v[134:137], v[210:213], v[14:17]
	v_mfma_f32_16x16x32_bf16 v[10:13], v[148:151], v[210:213], v[10:13]
	v_mfma_f32_16x16x32_bf16 v[54:57], v[152:155], v[178:181], v[54:57]
	v_mfma_f32_16x16x32_bf16 v[50:53], v[170:173], v[178:181], v[50:53]
	v_mfma_f32_16x16x32_bf16 v[38:41], v[152:155], v[186:189], v[38:41]
	v_mfma_f32_16x16x32_bf16 v[34:37], v[170:173], v[186:189], v[34:37]
	v_mfma_f32_16x16x32_bf16 v[22:25], v[152:155], v[194:197], v[22:25]
	v_mfma_f32_16x16x32_bf16 v[18:21], v[170:173], v[194:197], v[18:21]
	v_mfma_f32_16x16x32_bf16 v[6:9], v[152:155], v[206:209], v[6:9]
	v_mfma_f32_16x16x32_bf16 v[2:5], v[170:173], v[206:209], v[2:5]
	v_mfma_f32_16x16x32_bf16 v[54:57], v[166:169], v[182:185], v[54:57]
	v_mfma_f32_16x16x32_bf16 v[50:53], v[174:177], v[182:185], v[50:53]
	v_mfma_f32_16x16x32_bf16 v[38:41], v[166:169], v[190:193], v[38:41]
	v_mfma_f32_16x16x32_bf16 v[34:37], v[174:177], v[190:193], v[34:37]
	v_mfma_f32_16x16x32_bf16 v[22:25], v[166:169], v[202:205], v[22:25]
	v_mfma_f32_16x16x32_bf16 v[18:21], v[174:177], v[202:205], v[18:21]
	v_mfma_f32_16x16x32_bf16 v[6:9], v[166:169], v[210:213], v[6:9]
	v_mfma_f32_16x16x32_bf16 v[2:5], v[174:177], v[210:213], v[2:5]
	s_setprio 0
	s_barrier
	s_add_i32 s55, s55, 2
	s_add_u32 s62, s62, 0x8000
	s_addc_u32 s63, s63, 0
	s_add_u32 s51, s51, 0x8000
	s_addc_u32 s53, s53, 0
	s_cmp_gt_u32 s55, 13
	s_cbranch_scc0 .LBB0_881
	s_mov_b64 s[18:19], s[92:93]
	s_and_b64 vcc, exec, s[38:39]
	s_cbranch_vccz .LBB0_884
	s_barrier

; #define PG8_STAGE(bufoff, gbase, voff) do { _Pragma("unroll") for (int _i = 0; _i < 2; ++_i) \
;         __builtin_amdgcn_global_load_lds((const unsigned*)((const char*)(gbase) + (voff)[_i]), (PG8_LAS unsigned*)(lds + (bufoff) + ldsw + _i * 8192), 16, 0, 0); } while (0)
; #define PG8_LDA(dst, b, h) do { _Pragma("unroll") for (int m = 0; m < 4; ++m) _Pragma("unroll") for (int k = 0; k < 2; ++k) dst[m][k] = *(const PG8_LAS bf16x8*)(lds + PG8_SA(b, h) + aoff + m * 2048 + k * 1024); } while (0)
; #define PG8_LDB(dst, b, h) do { _Pragma("unroll") for (int n = 0; n < 2; ++n) _Pragma("unroll") for (int k = 0; k < 2; ++k) dst[n][k] = *(const PG8_LAS bf16x8*)(lds + PG8_SB(b, h) + boff + n * 2048 + k * 1024); } while (0)
; #define PG8_WAIT_V(n) asm volatile("s_waitcnt vmcnt(" #n ")" ::: "memory")
; #define PG8_WAIT_L(n) asm volatile("s_waitcnt lgkmcnt(" #n ")" ::: "memory")
; #define PG8_BAR __builtin_amdgcn_s_barrier()
; #define PG8_SCHED __builtin_amdgcn_sched_barrier(0)
; template <class Epi, class Sched, bool ALIGN_EPI = false, bool SP2 = false>
; __device__ __forceinline__ void gemm_phase(PG8_LAS unsigned char* lds, const Gemm g, const Sched& S, const Epi& E) {
;     ...
;         const bool has_next = S.next(ui + 1, nxt);
;         const char* nA = has_next ? (const char*)g.A + (size_t)nxt.pm * tstep : cA; const char* nB = has_next ? (const char*)g.Bt + (size_t)nxt.pn * tstep : cB;
;         for (int t = 0; t < nt; t += 2) {
;             const bool last = (t == nt - 2);
;             const char* a1 = cA + (size_t)(t + 1) * kstep;
;             const char* a2 = last ? nA : cA + (size_t)(t + 2) * kstep; const char* b2 = last ? nB : cB + (size_t)(t + 2) * kstep;
;             const char* a3 = a2 + kstep; const char* b3 = b2 + kstep;
;             if (last && has_next) S.a_ready(nxt);
;             if constexpr (SP2) {
;             PG8_LDB(B0, 0, 0); PG8_LDB(B1, 0, 1); PG8_SCHED; PG8_LDA(At, 0, 0); PG8_STAGE(PG8_SA(1, 1), a1 + hstep, voffA);
;             PG8_WAIT_V(8); PG8_WAIT_L(0); PG8_BAR; PG8_MMA(0, 0, At, B0); PG8_MMA(0, 1, At, B1); PG8_BAR; PG8_SCHED;
;             PG8_LDA(At, 0, 1); PG8_STAGE(PG8_SB(0, 0), b2, voffB); PG8_STAGE(PG8_SB(0, 1), b2 + hstep, voffB); PG8_STAGE(PG8_SA(0, 0), a2, voffA);
;             PG8_WAIT_V(8); PG8_WAIT_L(0); PG8_BAR; PG8_MMA(1, 0, At, B0); PG8_MMA(1, 1, At, B1); PG8_BAR; PG8_SCHED;
.LBB0_980:
	s_ashr_i32 s39, s38, 31
	s_lshl_b64 s[40:41], s[38:39], 19
	s_add_u32 s40, s1, s40
	s_addc_u32 s41, s33, s41
	s_and_b64 s[42:43], s[2:3], exec
	s_cselect_b32 s39, s41, s13
	s_cselect_b32 s48, s40, s12
	s_ashr_i32 s37, s36, 31
	s_lshl_b64 s[42:43], s[36:37], 19
	s_add_u32 s42, s8, s42
	s_addc_u32 s43, s9, s43
	s_and_b64 s[50:51], s[2:3], exec
	s_cselect_b32 s37, s43, s45
	s_cselect_b32 s49, s42, s44
	s_add_u32 s12, s12, 0x44000
	s_addc_u32 s13, s13, 0
	s_add_u32 s44, s44, 0x8000
	s_addc_u32 s45, s45, 0
	s_mov_b32 s50, -2
	ds_read_b128 v[138:141], v144
	ds_read_b128 v[150:153], v144 offset:1024
	ds_read_b128 v[154:157], v144 offset:2048
	ds_read_b128 v[158:161], v144 offset:3072
	ds_read_b128 v[162:165], v145
	ds_read_b128 v[166:169], v145 offset:1024
	ds_read_b128 v[170:173], v145 offset:2048
	ds_read_b128 v[174:177], v145 offset:3072
	s_add_u32 s51, s12, 0xfffc4000
	s_addc_u32 s67, s13, -1
	s_cmp_eq_u32 s50, 12
	s_cselect_b32 s69, s39, s67
	s_cselect_b32 s68, s48, s51
	s_cselect_b32 s71, s37, s45
	s_cselect_b32 s70, s49, s44
	v_lshl_add_u64 v[198:199], s[12:13], 0, v[130:131]
	s_add_i32 m0, s47, 0xc000
	ds_read_b128 v[178:181], v146
	ds_read_b128 v[182:185], v146 offset:1024
	ds_read_b128 v[186:189], v146 offset:2048
	ds_read_b128 v[190:193], v146 offset:3072
	ds_read_b128 v[194:197], v146 offset:4096
	ds_read_b128 v[202:205], v146 offset:5120
	ds_read_b128 v[206:209], v146 offset:6144
	ds_read_b128 v[210:213], v146 offset:7168
	global_load_lds_dwordx4 v[198:199], off
	v_lshl_add_u64 v[198:199], v[198:199], 0, s[6:7]
	s_add_i32 m0, s47, 0xe000
	s_nop 0
	global_load_lds_dwordx4 v[198:199], off
	s_waitcnt vmcnt(8)
	s_waitcnt lgkmcnt(0)
	s_barrier
	s_setprio 1
	s_waitcnt lgkmcnt(0)
	v_mfma_f32_16x16x32_bf16 v[118:121], v[138:141], v[178:181], 0
	v_mfma_f32_16x16x32_bf16 v[114:117], v[154:157], v[178:181], 0
	v_mfma_f32_16x16x32_bf16 v[102:105], v[138:141], v[186:189], 0
	v_mfma_f32_16x16x32_bf16 v[98:101], v[154:157], v[186:189], 0
	v_mfma_f32_16x16x32_bf16 v[86:89], v[138:141], v[194:197], 0
	v_mfma_f32_16x16x32_bf16 v[82:85], v[154:157], v[194:197], 0
	v_mfma_f32_16x16x32_bf16 v[70:73], v[138:141], v[206:209], 0
	v_mfma_f32_16x16x32_bf16 v[66:69], v[154:157], v[206:209], 0
	v_mfma_f32_16x16x32_bf16 v[118:121], v[150:153], v[182:185], v[118:121]
	v_mfma_f32_16x16x32_bf16 v[114:117], v[158:161], v[182:185], v[114:117]
	v_mfma_f32_16x16x32_bf16 v[102:105], v[150:153], v[190:193], v[102:105]
	v_mfma_f32_16x16x32_bf16 v[98:101], v[158:161], v[190:193], v[98:101]
	v_mfma_f32_16x16x32_bf16 v[86:89], v[150:153], v[202:205], v[86:89]
	v_mfma_f32_16x16x32_bf16 v[82:85], v[158:161], v[202:205], v[82:85]
	v_mfma_f32_16x16x32_bf16 v[70:73], v[150:153], v[210:213], v[70:73]
	v_mfma_f32_16x16x32_bf16 v[66:69], v[158:161], v[210:213], v[66:69]
	v_mfma_f32_16x16x32_bf16 v[126:129], v[162:165], v[178:181], 0
	v_mfma_f32_16x16x32_bf16 v[122:125], v[170:173], v[178:181], 0
	v_mfma_f32_16x16x32_bf16 v[110:113], v[162:165], v[186:189], 0
	v_mfma_f32_16x16x32_bf16 v[106:109], v[170:173], v[186:189], 0
	v_mfma_f32_16x16x32_bf16 v[94:97], v[162:165], v[194:197], 0
	v_mfma_f32_16x16x32_bf16 v[90:93], v[170:173], v[194:197], 0
	v_mfma_f32_16x16x32_bf16 v[78:81], v[162:165], v[206:209], 0
	v_mfma_f32_16x16x32_bf16 v[74:77], v[170:173], v[206:209], 0
	v_mfma_f32_16x16x32_bf16 v[126:129], v[166:169], v[182:185], v[126:129]
	v_mfma_f32_16x16x32_bf16 v[122:125], v[174:177], v[182:185], v[122:125]
	v_mfma_f32_16x16x32_bf16 v[110:113], v[166:169], v[190:193], v[110:113]
	v_mfma_f32_16x16x32_bf16 v[106:109], v[174:177], v[190:193], v[106:109]
	v_mfma_f32_16x16x32_bf16 v[94:97], v[166:169], v[202:205], v[94:97]
	v_mfma_f32_16x16x32_bf16 v[90:93], v[174:177], v[202:205], v[90:93]
	v_mfma_f32_16x16x32_bf16 v[78:81], v[166:169], v[210:213], v[78:81]
	v_mfma_f32_16x16x32_bf16 v[74:77], v[174:177], v[210:213], v[74:77]
	s_setprio 0
	s_barrier
	s_add_i32 s51, s64, s46
	v_lshl_add_u64 v[198:199], s[70:71], 0, v[130:131]
	s_mov_b32 m0, s51
	ds_read_b128 v[178:181], v146 offset:16384
	ds_read_b128 v[182:185], v146 offset:17408
	ds_read_b128 v[186:189], v146 offset:18432
	ds_read_b128 v[190:193], v146 offset:19456
	ds_read_b128 v[194:197], v146 offset:20480
	ds_read_b128 v[202:205], v146 offset:21504
	ds_read_b128 v[206:209], v146 offset:22528
	ds_read_b128 v[210:213], v146 offset:23552
	global_load_lds_dwordx4 v[198:199], off
	v_lshl_add_u64 v[214:215], v[198:199], 0, s[6:7]
	s_add_i32 m0, s51, 0x2000
	s_add_i32 s51, s65, s46
	global_load_lds_dwordx4 v[214:215], off
	v_lshl_add_u64 v[214:215], v[198:199], 0, s[10:11]
	s_mov_b32 m0, s51
	s_nop 0
	global_load_lds_dwordx4 v[214:215], off
	v_lshl_add_u64 v[214:215], v[198:199], 0, s[14:15]
	s_add_i32 m0, s51, 0x2000
	s_nop 0
	global_load_lds_dwordx4 v[214:215], off
	v_lshl_add_u64 v[214:215], s[68:69], 0, v[130:131]
	s_mov_b32 m0, s47
	v_lshl_add_u64 v[216:217], v[214:215], 0, s[6:7]
	global_load_lds_dwordx4 v[214:215], off
	s_mov_b32 m0, s52
	s_nop 0
	global_load_lds_dwordx4 v[216:217], off
	s_waitcnt vmcnt(8)
	s_waitcnt lgkmcnt(0)
	s_barrier
; #define PG8_STAGE(bufoff, gbase, voff) do { _Pragma("unroll") for (int _i = 0; _i < 2; ++_i) \
;         __builtin_amdgcn_global_load_lds((const unsigned*)((const char*)(gbase) + (voff)[_i]), (PG8_LAS unsigned*)(lds + (bufoff) + ldsw + _i * 8192), 16, 0, 0); } while (0)
; #define PG8_LDA(dst, b, h) do { _Pragma("unroll") for (int m = 0; m < 4; ++m) _Pragma("unroll") for (int k = 0; k < 2; ++k) dst[m][k] = *(const PG8_LAS bf16x8*)(lds + PG8_SA(b, h) + aoff + m * 2048 + k * 1024); } while (0)
; #define PG8_LDB(dst, b, h) do { _Pragma("unroll") for (int n = 0; n < 2; ++n) _Pragma("unroll") for (int k = 0; k < 2; ++k) dst[n][k] = *(const PG8_LAS bf16x8*)(lds + PG8_SB(b, h) + boff + n * 2048 + k * 1024); } while (0)
; #define PG8_MMA(ai, bj, At, Bt) do { __builtin_amdgcn_s_setprio(1); _Pragma("unroll") for (int m = 0; m < 4; ++m) _Pragma("unroll") for (int n = 0; n < 2; ++n) _Pragma("unroll") for (int k = 0; k < 2; ++k) \
;         acc[ai][bj][m][n] = __builtin_amdgcn_mfma_f32_16x16x32_bf16(Bt[n][k], At[m][k], acc[ai][bj][m][n], 0, 0, 0); __builtin_amdgcn_s_setprio(0); } while (0)
; #define PG8_WAIT_V(n) asm volatile("s_waitcnt vmcnt(" #n ")" ::: "memory")
; #define PG8_WAIT_L(n) asm volatile("s_waitcnt lgkmcnt(" #n ")" ::: "memory")
; #define PG8_BAR __builtin_amdgcn_s_barrier()
; #define PG8_SCHED __builtin_amdgcn_sched_barrier(0)
; template <class Epi, class Sched, bool ALIGN_EPI = false, bool SP2 = false>
; __device__ __forceinline__ void gemm_phase(PG8_LAS unsigned char* lds, const Gemm g, const Sched& S, const Epi& E) {
;     ...
;             PG8_WAIT_V(8); PG8_WAIT_L(0); PG8_BAR; PG8_MMA(1, 0, At, B0); PG8_MMA(1, 1, At, B1); PG8_BAR; PG8_SCHED;
;             PG8_LDB(B0, 1, 0); PG8_LDB(B1, 1, 1); PG8_SCHED; PG8_LDA(At, 1, 0); PG8_STAGE(PG8_SA(0, 1), a2 + hstep, voffA);
;             PG8_WAIT_V(8); PG8_WAIT_L(0); PG8_BAR; PG8_MMA(0, 0, At, B0); PG8_MMA(0, 1, At, B1); PG8_BAR; PG8_SCHED;
	s_setprio 1
	s_waitcnt lgkmcnt(0)
	v_mfma_f32_16x16x32_bf16 v[54:57], v[138:141], v[178:181], 0
	v_mfma_f32_16x16x32_bf16 v[50:53], v[154:157], v[178:181], 0
	v_mfma_f32_16x16x32_bf16 v[38:41], v[138:141], v[186:189], 0
	v_mfma_f32_16x16x32_bf16 v[34:37], v[154:157], v[186:189], 0
	v_mfma_f32_16x16x32_bf16 v[22:25], v[138:141], v[194:197], 0
	v_mfma_f32_16x16x32_bf16 v[18:21], v[154:157], v[194:197], 0
	v_mfma_f32_16x16x32_bf16 v[6:9], v[138:141], v[206:209], 0
	v_mfma_f32_16x16x32_bf16 v[2:5], v[154:157], v[206:209], 0
	v_mfma_f32_16x16x32_bf16 v[54:57], v[150:153], v[182:185], v[54:57]
	v_mfma_f32_16x16x32_bf16 v[50:53], v[158:161], v[182:185], v[50:53]
	v_mfma_f32_16x16x32_bf16 v[38:41], v[150:153], v[190:193], v[38:41]
	v_mfma_f32_16x16x32_bf16 v[34:37], v[158:161], v[190:193], v[34:37]
	v_mfma_f32_16x16x32_bf16 v[22:25], v[150:153], v[202:205], v[22:25]
	v_mfma_f32_16x16x32_bf16 v[18:21], v[158:161], v[202:205], v[18:21]
	v_mfma_f32_16x16x32_bf16 v[6:9], v[150:153], v[210:213], v[6:9]
	v_mfma_f32_16x16x32_bf16 v[2:5], v[158:161], v[210:213], v[2:5]
	v_mfma_f32_16x16x32_bf16 v[62:65], v[162:165], v[178:181], 0
	v_mfma_f32_16x16x32_bf16 v[58:61], v[170:173], v[178:181], 0
	v_mfma_f32_16x16x32_bf16 v[46:49], v[162:165], v[186:189], 0
	v_mfma_f32_16x16x32_bf16 v[42:45], v[170:173], v[186:189], 0
	v_mfma_f32_16x16x32_bf16 v[30:33], v[162:165], v[194:197], 0
	v_mfma_f32_16x16x32_bf16 v[26:29], v[170:173], v[194:197], 0
	v_mfma_f32_16x16x32_bf16 v[14:17], v[162:165], v[206:209], 0
	v_mfma_f32_16x16x32_bf16 v[10:13], v[170:173], v[206:209], 0
	v_mfma_f32_16x16x32_bf16 v[62:65], v[166:169], v[182:185], v[62:65]
	v_mfma_f32_16x16x32_bf16 v[58:61], v[174:177], v[182:185], v[58:61]
	v_mfma_f32_16x16x32_bf16 v[46:49], v[166:169], v[190:193], v[46:49]
	v_mfma_f32_16x16x32_bf16 v[42:45], v[174:177], v[190:193], v[42:45]
	v_mfma_f32_16x16x32_bf16 v[30:33], v[166:169], v[202:205], v[30:33]
	v_mfma_f32_16x16x32_bf16 v[26:29], v[174:177], v[202:205], v[26:29]
	v_mfma_f32_16x16x32_bf16 v[14:17], v[166:169], v[210:213], v[14:17]
	v_mfma_f32_16x16x32_bf16 v[10:13], v[174:177], v[210:213], v[10:13]
	s_setprio 0
	s_barrier
	s_add_i32 s51, 0, 0x18000
	v_add_u32_e32 v132, s51, v143
	s_add_i32 s67, 0, 0x1c000
	ds_read_b128 v[138:141], v132
	ds_read_b128 v[150:153], v132 offset:1024
	ds_read_b128 v[154:157], v132 offset:2048
	ds_read_b128 v[158:161], v132 offset:3072
	v_add_u32_e32 v132, s67, v143
	ds_read_b128 v[162:165], v132
	ds_read_b128 v[166:169], v132 offset:1024
	ds_read_b128 v[170:173], v132 offset:2048
	ds_read_b128 v[174:177], v132 offset:3072
	s_mov_b32 m0, s53
	v_lshl_add_u64 v[216:217], v[214:215], 0, s[10:11]
	ds_read_b128 v[178:181], v146 offset:32768
	ds_read_b128 v[182:185], v146 offset:33792
	ds_read_b128 v[186:189], v146 offset:34816
	ds_read_b128 v[190:193], v146 offset:35840
	ds_read_b128 v[194:197], v146 offset:36864
	ds_read_b128 v[202:205], v146 offset:37888
	ds_read_b128 v[206:209], v146 offset:38912
	ds_read_b128 v[210:213], v146 offset:39936
	global_load_lds_dwordx4 v[216:217], off
	v_lshl_add_u64 v[216:217], v[214:215], 0, s[14:15]
	s_mov_b32 m0, s54
	s_nop 0
	global_load_lds_dwordx4 v[216:217], off
	s_waitcnt vmcnt(8)
	s_waitcnt lgkmcnt(0)
	s_barrier
	s_setprio 1
	s_waitcnt lgkmcnt(0)
	v_mfma_f32_16x16x32_bf16 v[118:121], v[138:141], v[178:181], v[118:121]
	v_mfma_f32_16x16x32_bf16 v[114:117], v[154:157], v[178:181], v[114:117]
	v_mfma_f32_16x16x32_bf16 v[102:105], v[138:141], v[186:189], v[102:105]
	v_mfma_f32_16x16x32_bf16 v[98:101], v[154:157], v[186:189], v[98:101]
	v_mfma_f32_16x16x32_bf16 v[86:89], v[138:141], v[194:197], v[86:89]
	v_mfma_f32_16x16x32_bf16 v[82:85], v[154:157], v[194:197], v[82:85]
	v_mfma_f32_16x16x32_bf16 v[70:73], v[138:141], v[206:209], v[70:73]
	v_mfma_f32_16x16x32_bf16 v[66:69], v[154:157], v[206:209], v[66:69]
	v_mfma_f32_16x16x32_bf16 v[118:121], v[150:153], v[182:185], v[118:121]
	v_mfma_f32_16x16x32_bf16 v[114:117], v[158:161], v[182:185], v[114:117]
	v_mfma_f32_16x16x32_bf16 v[102:105], v[150:153], v[190:193], v[102:105]
	v_mfma_f32_16x16x32_bf16 v[98:101], v[158:161], v[190:193], v[98:101]
	v_mfma_f32_16x16x32_bf16 v[86:89], v[150:153], v[202:205], v[86:89]
	v_mfma_f32_16x16x32_bf16 v[82:85], v[158:161], v[202:205], v[82:85]
	v_mfma_f32_16x16x32_bf16 v[70:73], v[150:153], v[210:213], v[70:73]
	v_mfma_f32_16x16x32_bf16 v[66:69], v[158:161], v[210:213], v[66:69]
	v_mfma_f32_16x16x32_bf16 v[126:129], v[162:165], v[178:181], v[126:129]
	v_mfma_f32_16x16x32_bf16 v[122:125], v[170:173], v[178:181], v[122:125]
	v_mfma_f32_16x16x32_bf16 v[110:113], v[162:165], v[186:189], v[110:113]
	v_mfma_f32_16x16x32_bf16 v[106:109], v[170:173], v[186:189], v[106:109]
	v_mfma_f32_16x16x32_bf16 v[94:97], v[162:165], v[194:197], v[94:97]
	v_mfma_f32_16x16x32_bf16 v[90:93], v[170:173], v[194:197], v[90:93]
	v_mfma_f32_16x16x32_bf16 v[78:81], v[162:165], v[206:209], v[78:81]
	v_mfma_f32_16x16x32_bf16 v[74:77], v[170:173], v[206:209], v[74:77]
	v_mfma_f32_16x16x32_bf16 v[126:129], v[166:169], v[182:185], v[126:129]
	v_mfma_f32_16x16x32_bf16 v[122:125], v[174:177], v[182:185], v[122:125]
	v_mfma_f32_16x16x32_bf16 v[110:113], v[166:169], v[190:193], v[110:113]
	v_mfma_f32_16x16x32_bf16 v[106:109], v[174:177], v[190:193], v[106:109]
	v_mfma_f32_16x16x32_bf16 v[94:97], v[166:169], v[202:205], v[94:97]
	v_mfma_f32_16x16x32_bf16 v[90:93], v[174:177], v[202:205], v[90:93]
	v_mfma_f32_16x16x32_bf16 v[78:81], v[166:169], v[210:213], v[78:81]
	v_mfma_f32_16x16x32_bf16 v[74:77], v[174:177], v[210:213], v[74:77]
	s_setprio 0
	s_barrier
; #define PG8_STAGE(bufoff, gbase, voff) do { _Pragma("unroll") for (int _i = 0; _i < 2; ++_i) \
;         __builtin_amdgcn_global_load_lds((const unsigned*)((const char*)(gbase) + (voff)[_i]), (PG8_LAS unsigned*)(lds + (bufoff) + ldsw + _i * 8192), 16, 0, 0); } while (0)
; #define PG8_LDA(dst, b, h) do { _Pragma("unroll") for (int m = 0; m < 4; ++m) _Pragma("unroll") for (int k = 0; k < 2; ++k) dst[m][k] = *(const PG8_LAS bf16x8*)(lds + PG8_SA(b, h) + aoff + m * 2048 + k * 1024); } while (0)
; #define PG8_LDB(dst, b, h) do { _Pragma("unroll") for (int n = 0; n < 2; ++n) _Pragma("unroll") for (int k = 0; k < 2; ++k) dst[n][k] = *(const PG8_LAS bf16x8*)(lds + PG8_SB(b, h) + boff + n * 2048 + k * 1024); } while (0)
; #define PG8_MMA(ai, bj, At, Bt) do { __builtin_amdgcn_s_setprio(1); _Pragma("unroll") for (int m = 0; m < 4; ++m) _Pragma("unroll") for (int n = 0; n < 2; ++n) _Pragma("unroll") for (int k = 0; k < 2; ++k) \
;         acc[ai][bj][m][n] = __builtin_amdgcn_mfma_f32_16x16x32_bf16(Bt[n][k], At[m][k], acc[ai][bj][m][n], 0, 0, 0); __builtin_amdgcn_s_setprio(0); } while (0)
; #define PG8_WAIT_V(n) asm volatile("s_waitcnt vmcnt(" #n ")" ::: "memory")
; #define PG8_WAIT_L(n) asm volatile("s_waitcnt lgkmcnt(" #n ")" ::: "memory")
; #define PG8_BAR __builtin_amdgcn_s_barrier()
; #define PG8_SCHED __builtin_amdgcn_sched_barrier(0)
; template <class Epi, class Sched, bool ALIGN_EPI = false, bool SP2 = false>
; __device__ __forceinline__ void gemm_phase(PG8_LAS unsigned char* lds, const Gemm g, const Sched& S, const Epi& E) {
;     ...
;             PG8_LDB(B0, 0, 0); PG8_LDB(B1, 0, 1); PG8_SCHED; PG8_LDA(At, 0, 0); PG8_STAGE(PG8_SA(1, 1), a1 + hstep, voffA);
;             PG8_WAIT_V(8); PG8_WAIT_L(0); PG8_BAR; PG8_MMA(0, 0, At, B0); PG8_MMA(0, 1, At, B1); PG8_BAR; PG8_SCHED;
;     ...
;             PG8_LDA(At, 1, 1); PG8_STAGE(PG8_SB(1, 0), b3, voffB); PG8_STAGE(PG8_SB(1, 1), b3 + hstep, voffB); PG8_STAGE(PG8_SA(1, 0), a3, voffA);
;             PG8_WAIT_V(8); PG8_WAIT_L(0); PG8_BAR; PG8_MMA(1, 0, At, B0); PG8_MMA(1, 1, At, B1); PG8_BAR; PG8_SCHED;
	s_add_i32 s51, s51, s46
	v_lshl_add_u64 v[216:217], v[198:199], 0, s[18:19]
	s_mov_b32 m0, s51
	ds_read_b128 v[178:181], v146 offset:49152
	ds_read_b128 v[182:185], v146 offset:50176
	ds_read_b128 v[186:189], v146 offset:51200
	ds_read_b128 v[190:193], v146 offset:52224
	ds_read_b128 v[194:197], v146 offset:53248
	ds_read_b128 v[202:205], v146 offset:54272
	ds_read_b128 v[206:209], v146 offset:55296
	ds_read_b128 v[210:213], v146 offset:56320
	global_load_lds_dwordx4 v[216:217], off
	v_lshl_add_u64 v[216:217], v[198:199], 0, s[20:21]
	s_add_i32 m0, s51, 0x2000
	s_add_i32 s51, s67, s46
	global_load_lds_dwordx4 v[216:217], off
	v_lshl_add_u64 v[216:217], v[198:199], 0, s[22:23]
	s_mov_b32 m0, s51
	v_lshl_add_u64 v[198:199], v[198:199], 0, s[24:25]
	global_load_lds_dwordx4 v[216:217], off
	s_add_i32 m0, s51, 0x2000
	s_nop 0
	global_load_lds_dwordx4 v[198:199], off
	v_lshl_add_u64 v[198:199], v[214:215], 0, s[18:19]
	s_mov_b32 m0, s56
	s_nop 0
	global_load_lds_dwordx4 v[198:199], off
	v_lshl_add_u64 v[198:199], v[214:215], 0, s[20:21]
	s_mov_b32 m0, s57
	s_nop 0
	global_load_lds_dwordx4 v[198:199], off
	s_waitcnt vmcnt(8)
	s_waitcnt lgkmcnt(0)
	s_barrier
	s_setprio 1
	s_waitcnt lgkmcnt(0)
	v_mfma_f32_16x16x32_bf16 v[54:57], v[138:141], v[178:181], v[54:57]
	v_mfma_f32_16x16x32_bf16 v[50:53], v[154:157], v[178:181], v[50:53]
	v_mfma_f32_16x16x32_bf16 v[38:41], v[138:141], v[186:189], v[38:41]
	v_mfma_f32_16x16x32_bf16 v[34:37], v[154:157], v[186:189], v[34:37]
	v_mfma_f32_16x16x32_bf16 v[22:25], v[138:141], v[194:197], v[22:25]
	v_mfma_f32_16x16x32_bf16 v[18:21], v[154:157], v[194:197], v[18:21]
	v_mfma_f32_16x16x32_bf16 v[6:9], v[138:141], v[206:209], v[6:9]
	v_mfma_f32_16x16x32_bf16 v[2:5], v[154:157], v[206:209], v[2:5]
	v_mfma_f32_16x16x32_bf16 v[54:57], v[150:153], v[182:185], v[54:57]
	v_mfma_f32_16x16x32_bf16 v[50:53], v[158:161], v[182:185], v[50:53]
	v_mfma_f32_16x16x32_bf16 v[38:41], v[150:153], v[190:193], v[38:41]
	v_mfma_f32_16x16x32_bf16 v[34:37], v[158:161], v[190:193], v[34:37]
	v_mfma_f32_16x16x32_bf16 v[22:25], v[150:153], v[202:205], v[22:25]
	v_mfma_f32_16x16x32_bf16 v[18:21], v[158:161], v[202:205], v[18:21]
	v_mfma_f32_16x16x32_bf16 v[6:9], v[150:153], v[210:213], v[6:9]
	v_mfma_f32_16x16x32_bf16 v[2:5], v[158:161], v[210:213], v[2:5]
	v_mfma_f32_16x16x32_bf16 v[62:65], v[162:165], v[178:181], v[62:65]
	v_mfma_f32_16x16x32_bf16 v[58:61], v[170:173], v[178:181], v[58:61]
	v_mfma_f32_16x16x32_bf16 v[46:49], v[162:165], v[186:189], v[46:49]
	v_mfma_f32_16x16x32_bf16 v[42:45], v[170:173], v[186:189], v[42:45]
	v_mfma_f32_16x16x32_bf16 v[30:33], v[162:165], v[194:197], v[30:33]
	v_mfma_f32_16x16x32_bf16 v[26:29], v[170:173], v[194:197], v[26:29]
	v_mfma_f32_16x16x32_bf16 v[14:17], v[162:165], v[206:209], v[14:17]
	v_mfma_f32_16x16x32_bf16 v[10:13], v[170:173], v[206:209], v[10:13]
	v_mfma_f32_16x16x32_bf16 v[62:65], v[166:169], v[182:185], v[62:65]
	v_mfma_f32_16x16x32_bf16 v[58:61], v[174:177], v[182:185], v[58:61]
	v_mfma_f32_16x16x32_bf16 v[46:49], v[166:169], v[190:193], v[46:49]
	v_mfma_f32_16x16x32_bf16 v[42:45], v[174:177], v[190:193], v[42:45]
	v_mfma_f32_16x16x32_bf16 v[30:33], v[166:169], v[202:205], v[30:33]
	v_mfma_f32_16x16x32_bf16 v[26:29], v[174:177], v[202:205], v[26:29]
	v_mfma_f32_16x16x32_bf16 v[14:17], v[166:169], v[210:213], v[14:17]
	v_mfma_f32_16x16x32_bf16 v[10:13], v[174:177], v[210:213], v[10:13]
	s_setprio 0
	s_barrier
	s_add_i32 s50, s50, 2
	s_add_u32 s12, s12, 0x8000
	s_addc_u32 s13, s13, 0
	s_add_u32 s44, s44, 0x8000
	s_addc_u32 s45, s45, 0
	s_cmp_gt_u32 s50, 13
	s_cbranch_scc0 .LBB0_981
.LBB0_981:
	ds_read_b128 v[138:141], v144
	ds_read_b128 v[150:153], v144 offset:1024
	ds_read_b128 v[154:157], v144 offset:2048
	ds_read_b128 v[158:161], v144 offset:3072
	ds_read_b128 v[162:165], v145
	ds_read_b128 v[166:169], v145 offset:1024
	ds_read_b128 v[170:173], v145 offset:2048
	ds_read_b128 v[174:177], v145 offset:3072
	s_add_u32 s51, s12, 0xfffc4000
	s_addc_u32 s67, s13, -1
	s_cmp_eq_u32 s50, 12
	s_cselect_b32 s69, s39, s67
	s_cselect_b32 s68, s48, s51
	s_cselect_b32 s71, s37, s45
	s_cselect_b32 s70, s49, s44
	v_lshl_add_u64 v[198:199], s[12:13], 0, v[130:131]
	s_add_i32 m0, s47, 0xc000
	ds_read_b128 v[178:181], v146
	ds_read_b128 v[182:185], v146 offset:1024
	ds_read_b128 v[186:189], v146 offset:2048
	ds_read_b128 v[190:193], v146 offset:3072
	ds_read_b128 v[194:197], v146 offset:4096
	ds_read_b128 v[202:205], v146 offset:5120
	ds_read_b128 v[206:209], v146 offset:6144
	ds_read_b128 v[210:213], v146 offset:7168
	global_load_lds_dwordx4 v[198:199], off
	v_lshl_add_u64 v[198:199], v[198:199], 0, s[6:7]
	s_add_i32 m0, s47, 0xe000
	s_nop 0
	global_load_lds_dwordx4 v[198:199], off
	s_waitcnt vmcnt(8)
	s_waitcnt lgkmcnt(0)
	s_barrier
; #define PG8_STAGE(bufoff, gbase, voff) do { _Pragma("unroll") for (int _i = 0; _i < 2; ++_i) \
;         __builtin_amdgcn_global_load_lds((const unsigned*)((const char*)(gbase) + (voff)[_i]), (PG8_LAS unsigned*)(lds + (bufoff) + ldsw + _i * 8192), 16, 0, 0); } while (0)
; #define PG8_LDA(dst, b, h) do { _Pragma("unroll") for (int m = 0; m < 4; ++m) _Pragma("unroll") for (int k = 0; k < 2; ++k) dst[m][k] = *(const PG8_LAS bf16x8*)(lds + PG8_SA(b, h) + aoff + m * 2048 + k * 1024); } while (0)
; #define PG8_LDB(dst, b, h) do { _Pragma("unroll") for (int n = 0; n < 2; ++n) _Pragma("unroll") for (int k = 0; k < 2; ++k) dst[n][k] = *(const PG8_LAS bf16x8*)(lds + PG8_SB(b, h) + boff + n * 2048 + k * 1024); } while (0)
; #define PG8_MMA(ai, bj, At, Bt) do { __builtin_amdgcn_s_setprio(1); _Pragma("unroll") for (int m = 0; m < 4; ++m) _Pragma("unroll") for (int n = 0; n < 2; ++n) _Pragma("unroll") for (int k = 0; k < 2; ++k) \
;         acc[ai][bj][m][n] = __builtin_amdgcn_mfma_f32_16x16x32_bf16(Bt[n][k], At[m][k], acc[ai][bj][m][n], 0, 0, 0); __builtin_amdgcn_s_setprio(0); } while (0)
; #define PG8_WAIT_V(n) asm volatile("s_waitcnt vmcnt(" #n ")" ::: "memory")
; #define PG8_WAIT_L(n) asm volatile("s_waitcnt lgkmcnt(" #n ")" ::: "memory")
; #define PG8_BAR __builtin_amdgcn_s_barrier()
; #define PG8_SCHED __builtin_amdgcn_sched_barrier(0)
; template <class Epi, class Sched, bool ALIGN_EPI = false, bool SP2 = false>
; __device__ __forceinline__ void gemm_phase(PG8_LAS unsigned char* lds, const Gemm g, const Sched& S, const Epi& E) {
;     ...
;             PG8_WAIT_V(8); PG8_WAIT_L(0); PG8_BAR; PG8_MMA(0, 0, At, B0); PG8_MMA(0, 1, At, B1); PG8_BAR; PG8_SCHED;
;             PG8_LDA(At, 0, 1); PG8_STAGE(PG8_SB(0, 0), b2, voffB); PG8_STAGE(PG8_SB(0, 1), b2 + hstep, voffB); PG8_STAGE(PG8_SA(0, 0), a2, voffA);
;             PG8_WAIT_V(8); PG8_WAIT_L(0); PG8_BAR; PG8_MMA(1, 0, At, B0); PG8_MMA(1, 1, At, B1); PG8_BAR; PG8_SCHED;
;             PG8_LDB(B0, 1, 0); PG8_LDB(B1, 1, 1); PG8_SCHED; PG8_LDA(At, 1, 0); PG8_STAGE(PG8_SA(0, 1), a2 + hstep, voffA);
;             PG8_WAIT_V(8); PG8_WAIT_L(0); PG8_BAR; PG8_MMA(0, 0, At, B0); PG8_MMA(0, 1, At, B1); PG8_BAR; PG8_SCHED;
	s_setprio 1
	s_waitcnt lgkmcnt(0)
	v_mfma_f32_16x16x32_bf16 v[118:121], v[138:141], v[178:181], v[118:121]
	v_mfma_f32_16x16x32_bf16 v[114:117], v[154:157], v[178:181], v[114:117]
	v_mfma_f32_16x16x32_bf16 v[102:105], v[138:141], v[186:189], v[102:105]
	v_mfma_f32_16x16x32_bf16 v[98:101], v[154:157], v[186:189], v[98:101]
	v_mfma_f32_16x16x32_bf16 v[86:89], v[138:141], v[194:197], v[86:89]
	v_mfma_f32_16x16x32_bf16 v[82:85], v[154:157], v[194:197], v[82:85]
	v_mfma_f32_16x16x32_bf16 v[70:73], v[138:141], v[206:209], v[70:73]
	v_mfma_f32_16x16x32_bf16 v[66:69], v[154:157], v[206:209], v[66:69]
	v_mfma_f32_16x16x32_bf16 v[118:121], v[150:153], v[182:185], v[118:121]
	v_mfma_f32_16x16x32_bf16 v[114:117], v[158:161], v[182:185], v[114:117]
	v_mfma_f32_16x16x32_bf16 v[102:105], v[150:153], v[190:193], v[102:105]
	v_mfma_f32_16x16x32_bf16 v[98:101], v[158:161], v[190:193], v[98:101]
	v_mfma_f32_16x16x32_bf16 v[86:89], v[150:153], v[202:205], v[86:89]
	v_mfma_f32_16x16x32_bf16 v[82:85], v[158:161], v[202:205], v[82:85]
	v_mfma_f32_16x16x32_bf16 v[70:73], v[150:153], v[210:213], v[70:73]
	v_mfma_f32_16x16x32_bf16 v[66:69], v[158:161], v[210:213], v[66:69]
	v_mfma_f32_16x16x32_bf16 v[126:129], v[162:165], v[178:181], v[126:129]
	v_mfma_f32_16x16x32_bf16 v[122:125], v[170:173], v[178:181], v[122:125]
	v_mfma_f32_16x16x32_bf16 v[110:113], v[162:165], v[186:189], v[110:113]
	v_mfma_f32_16x16x32_bf16 v[106:109], v[170:173], v[186:189], v[106:109]
	v_mfma_f32_16x16x32_bf16 v[94:97], v[162:165], v[194:197], v[94:97]
	v_mfma_f32_16x16x32_bf16 v[90:93], v[170:173], v[194:197], v[90:93]
	v_mfma_f32_16x16x32_bf16 v[78:81], v[162:165], v[206:209], v[78:81]
	v_mfma_f32_16x16x32_bf16 v[74:77], v[170:173], v[206:209], v[74:77]
	v_mfma_f32_16x16x32_bf16 v[126:129], v[166:169], v[182:185], v[126:129]
	v_mfma_f32_16x16x32_bf16 v[122:125], v[174:177], v[182:185], v[122:125]
	v_mfma_f32_16x16x32_bf16 v[110:113], v[166:169], v[190:193], v[110:113]
	v_mfma_f32_16x16x32_bf16 v[106:109], v[174:177], v[190:193], v[106:109]
	v_mfma_f32_16x16x32_bf16 v[94:97], v[166:169], v[202:205], v[94:97]
	v_mfma_f32_16x16x32_bf16 v[90:93], v[174:177], v[202:205], v[90:93]
	v_mfma_f32_16x16x32_bf16 v[78:81], v[166:169], v[210:213], v[78:81]
	v_mfma_f32_16x16x32_bf16 v[74:77], v[174:177], v[210:213], v[74:77]
	s_setprio 0
	s_barrier
	s_add_i32 s51, s64, s46
	v_lshl_add_u64 v[198:199], s[70:71], 0, v[130:131]
	s_mov_b32 m0, s51
	ds_read_b128 v[178:181], v146 offset:16384
	ds_read_b128 v[182:185], v146 offset:17408
	ds_read_b128 v[186:189], v146 offset:18432
	ds_read_b128 v[190:193], v146 offset:19456
	ds_read_b128 v[194:197], v146 offset:20480
	ds_read_b128 v[202:205], v146 offset:21504
	ds_read_b128 v[206:209], v146 offset:22528
	ds_read_b128 v[210:213], v146 offset:23552
	global_load_lds_dwordx4 v[198:199], off
	v_lshl_add_u64 v[214:215], v[198:199], 0, s[6:7]
	s_add_i32 m0, s51, 0x2000
	s_add_i32 s51, s65, s46
	global_load_lds_dwordx4 v[214:215], off
	v_lshl_add_u64 v[214:215], v[198:199], 0, s[10:11]
	s_mov_b32 m0, s51
	s_nop 0
	global_load_lds_dwordx4 v[214:215], off
	v_lshl_add_u64 v[214:215], v[198:199], 0, s[14:15]
	s_add_i32 m0, s51, 0x2000
	s_nop 0
	global_load_lds_dwordx4 v[214:215], off
	v_lshl_add_u64 v[214:215], s[68:69], 0, v[130:131]
	s_mov_b32 m0, s47
	v_lshl_add_u64 v[216:217], v[214:215], 0, s[6:7]
	global_load_lds_dwordx4 v[214:215], off
	s_mov_b32 m0, s52
	s_nop 0
	global_load_lds_dwordx4 v[216:217], off
	s_waitcnt vmcnt(8)
	s_waitcnt lgkmcnt(0)
	s_barrier
	s_setprio 1
	s_waitcnt lgkmcnt(0)
	v_mfma_f32_16x16x32_bf16 v[54:57], v[138:141], v[178:181], v[54:57]
	v_mfma_f32_16x16x32_bf16 v[50:53], v[154:157], v[178:181], v[50:53]
	v_mfma_f32_16x16x32_bf16 v[38:41], v[138:141], v[186:189], v[38:41]
	v_mfma_f32_16x16x32_bf16 v[34:37], v[154:157], v[186:189], v[34:37]
	v_mfma_f32_16x16x32_bf16 v[22:25], v[138:141], v[194:197], v[22:25]
	v_mfma_f32_16x16x32_bf16 v[18:21], v[154:157], v[194:197], v[18:21]
	v_mfma_f32_16x16x32_bf16 v[6:9], v[138:141], v[206:209], v[6:9]
	v_mfma_f32_16x16x32_bf16 v[2:5], v[154:157], v[206:209], v[2:5]
	v_mfma_f32_16x16x32_bf16 v[54:57], v[150:153], v[182:185], v[54:57]
	v_mfma_f32_16x16x32_bf16 v[50:53], v[158:161], v[182:185], v[50:53]
	v_mfma_f32_16x16x32_bf16 v[38:41], v[150:153], v[190:193], v[38:41]
	v_mfma_f32_16x16x32_bf16 v[34:37], v[158:161], v[190:193], v[34:37]
	v_mfma_f32_16x16x32_bf16 v[22:25], v[150:153], v[202:205], v[22:25]
	v_mfma_f32_16x16x32_bf16 v[18:21], v[158:161], v[202:205], v[18:21]
	v_mfma_f32_16x16x32_bf16 v[6:9], v[150:153], v[210:213], v[6:9]
	v_mfma_f32_16x16x32_bf16 v[2:5], v[158:161], v[210:213], v[2:5]
	v_mfma_f32_16x16x32_bf16 v[62:65], v[162:165], v[178:181], v[62:65]
	v_mfma_f32_16x16x32_bf16 v[58:61], v[170:173], v[178:181], v[58:61]
	v_mfma_f32_16x16x32_bf16 v[46:49], v[162:165], v[186:189], v[46:49]
	v_mfma_f32_16x16x32_bf16 v[42:45], v[170:173], v[186:189], v[42:45]
	v_mfma_f32_16x16x32_bf16 v[30:33], v[162:165], v[194:197], v[30:33]
	v_mfma_f32_16x16x32_bf16 v[26:29], v[170:173], v[194:197], v[26:29]
	v_mfma_f32_16x16x32_bf16 v[14:17], v[162:165], v[206:209], v[14:17]
	v_mfma_f32_16x16x32_bf16 v[10:13], v[170:173], v[206:209], v[10:13]
	v_mfma_f32_16x16x32_bf16 v[62:65], v[166:169], v[182:185], v[62:65]
	v_mfma_f32_16x16x32_bf16 v[58:61], v[174:177], v[182:185], v[58:61]
	v_mfma_f32_16x16x32_bf16 v[46:49], v[166:169], v[190:193], v[46:49]
	v_mfma_f32_16x16x32_bf16 v[42:45], v[174:177], v[190:193], v[42:45]
	v_mfma_f32_16x16x32_bf16 v[30:33], v[166:169], v[202:205], v[30:33]
	v_mfma_f32_16x16x32_bf16 v[26:29], v[174:177], v[202:205], v[26:29]
	v_mfma_f32_16x16x32_bf16 v[14:17], v[166:169], v[210:213], v[14:17]
	v_mfma_f32_16x16x32_bf16 v[10:13], v[174:177], v[210:213], v[10:13]
	s_setprio 0
	s_barrier
; #define PG8_STAGE(bufoff, gbase, voff) do { _Pragma("unroll") for (int _i = 0; _i < 2; ++_i) \
;         __builtin_amdgcn_global_load_lds((const unsigned*)((const char*)(gbase) + (voff)[_i]), (PG8_LAS unsigned*)(lds + (bufoff) + ldsw + _i * 8192), 16, 0, 0); } while (0)
; #define PG8_LDA(dst, b, h) do { _Pragma("unroll") for (int m = 0; m < 4; ++m) _Pragma("unroll") for (int k = 0; k < 2; ++k) dst[m][k] = *(const PG8_LAS bf16x8*)(lds + PG8_SA(b, h) + aoff + m * 2048 + k * 1024); } while (0)
; #define PG8_LDB(dst, b, h) do { _Pragma("unroll") for (int n = 0; n < 2; ++n) _Pragma("unroll") for (int k = 0; k < 2; ++k) dst[n][k] = *(const PG8_LAS bf16x8*)(lds + PG8_SB(b, h) + boff + n * 2048 + k * 1024); } while (0)
; #define PG8_MMA(ai, bj, At, Bt) do { __builtin_amdgcn_s_setprio(1); _Pragma("unroll") for (int m = 0; m < 4; ++m) _Pragma("unroll") for (int n = 0; n < 2; ++n) _Pragma("unroll") for (int k = 0; k < 2; ++k) \
;         acc[ai][bj][m][n] = __builtin_amdgcn_mfma_f32_16x16x32_bf16(Bt[n][k], At[m][k], acc[ai][bj][m][n], 0, 0, 0); __builtin_amdgcn_s_setprio(0); } while (0)
; #define PG8_WAIT_V(n) asm volatile("s_waitcnt vmcnt(" #n ")" ::: "memory")
; #define PG8_WAIT_L(n) asm volatile("s_waitcnt lgkmcnt(" #n ")" ::: "memory")
; #define PG8_BAR __builtin_amdgcn_s_barrier()
; #define PG8_SCHED __builtin_amdgcn_sched_barrier(0)
; template <class Epi, class Sched, bool ALIGN_EPI = false, bool SP2 = false>
; __device__ __forceinline__ void gemm_phase(PG8_LAS unsigned char* lds, const Gemm g, const Sched& S, const Epi& E) {
;     ...
;             PG8_LDB(B0, 1, 0); PG8_LDB(B1, 1, 1); PG8_SCHED; PG8_LDA(At, 1, 0); PG8_STAGE(PG8_SA(0, 1), a2 + hstep, voffA);
;             PG8_WAIT_V(8); PG8_WAIT_L(0); PG8_BAR; PG8_MMA(0, 0, At, B0); PG8_MMA(0, 1, At, B1); PG8_BAR; PG8_SCHED;
	s_add_i32 s51, 0, 0x18000
	v_add_u32_e32 v132, s51, v143
	s_add_i32 s67, 0, 0x1c000
	ds_read_b128 v[138:141], v132
	ds_read_b128 v[150:153], v132 offset:1024
	ds_read_b128 v[154:157], v132 offset:2048
	ds_read_b128 v[158:161], v132 offset:3072
	v_add_u32_e32 v132, s67, v143
	ds_read_b128 v[162:165], v132
	ds_read_b128 v[166:169], v132 offset:1024
	ds_read_b128 v[170:173], v132 offset:2048
	ds_read_b128 v[174:177], v132 offset:3072
	s_mov_b32 m0, s53
	v_lshl_add_u64 v[216:217], v[214:215], 0, s[10:11]
	ds_read_b128 v[178:181], v146 offset:32768
	ds_read_b128 v[182:185], v146 offset:33792
	ds_read_b128 v[186:189], v146 offset:34816
	ds_read_b128 v[190:193], v146 offset:35840
	ds_read_b128 v[194:197], v146 offset:36864
	ds_read_b128 v[202:205], v146 offset:37888
	ds_read_b128 v[206:209], v146 offset:38912
	ds_read_b128 v[210:213], v146 offset:39936
	global_load_lds_dwordx4 v[216:217], off
	v_lshl_add_u64 v[216:217], v[214:215], 0, s[14:15]
	s_mov_b32 m0, s54
	s_nop 0
	global_load_lds_dwordx4 v[216:217], off
	s_waitcnt vmcnt(8)
	s_waitcnt lgkmcnt(0)
	s_barrier
	s_setprio 1
	s_waitcnt lgkmcnt(0)
	v_mfma_f32_16x16x32_bf16 v[118:121], v[138:141], v[178:181], v[118:121]
	v_mfma_f32_16x16x32_bf16 v[114:117], v[154:157], v[178:181], v[114:117]
	v_mfma_f32_16x16x32_bf16 v[102:105], v[138:141], v[186:189], v[102:105]
	v_mfma_f32_16x16x32_bf16 v[98:101], v[154:157], v[186:189], v[98:101]
	v_mfma_f32_16x16x32_bf16 v[86:89], v[138:141], v[194:197], v[86:89]
	v_mfma_f32_16x16x32_bf16 v[82:85], v[154:157], v[194:197], v[82:85]
	v_mfma_f32_16x16x32_bf16 v[70:73], v[138:141], v[206:209], v[70:73]
	v_mfma_f32_16x16x32_bf16 v[66:69], v[154:157], v[206:209], v[66:69]
	v_mfma_f32_16x16x32_bf16 v[118:121], v[150:153], v[182:185], v[118:121]
	v_mfma_f32_16x16x32_bf16 v[114:117], v[158:161], v[182:185], v[114:117]
	v_mfma_f32_16x16x32_bf16 v[102:105], v[150:153], v[190:193], v[102:105]
	v_mfma_f32_16x16x32_bf16 v[98:101], v[158:161], v[190:193], v[98:101]
	v_mfma_f32_16x16x32_bf16 v[86:89], v[150:153], v[202:205], v[86:89]
	v_mfma_f32_16x16x32_bf16 v[82:85], v[158:161], v[202:205], v[82:85]
	v_mfma_f32_16x16x32_bf16 v[70:73], v[150:153], v[210:213], v[70:73]
	v_mfma_f32_16x16x32_bf16 v[66:69], v[158:161], v[210:213], v[66:69]
	v_mfma_f32_16x16x32_bf16 v[126:129], v[162:165], v[178:181], v[126:129]
	v_mfma_f32_16x16x32_bf16 v[122:125], v[170:173], v[178:181], v[122:125]
	v_mfma_f32_16x16x32_bf16 v[110:113], v[162:165], v[186:189], v[110:113]
	v_mfma_f32_16x16x32_bf16 v[106:109], v[170:173], v[186:189], v[106:109]
	v_mfma_f32_16x16x32_bf16 v[94:97], v[162:165], v[194:197], v[94:97]
	v_mfma_f32_16x16x32_bf16 v[90:93], v[170:173], v[194:197], v[90:93]
	v_mfma_f32_16x16x32_bf16 v[78:81], v[162:165], v[206:209], v[78:81]
	v_mfma_f32_16x16x32_bf16 v[74:77], v[170:173], v[206:209], v[74:77]
	v_mfma_f32_16x16x32_bf16 v[126:129], v[166:169], v[182:185], v[126:129]
	v_mfma_f32_16x16x32_bf16 v[122:125], v[174:177], v[182:185], v[122:125]
	v_mfma_f32_16x16x32_bf16 v[110:113], v[166:169], v[190:193], v[110:113]
	v_mfma_f32_16x16x32_bf16 v[106:109], v[174:177], v[190:193], v[106:109]
	v_mfma_f32_16x16x32_bf16 v[94:97], v[166:169], v[202:205], v[94:97]
	v_mfma_f32_16x16x32_bf16 v[90:93], v[174:177], v[202:205], v[90:93]
	v_mfma_f32_16x16x32_bf16 v[78:81], v[166:169], v[210:213], v[78:81]
	v_mfma_f32_16x16x32_bf16 v[74:77], v[174:177], v[210:213], v[74:77]
	s_setprio 0
	s_barrier
; #define PG8_STAGE(bufoff, gbase, voff) do { _Pragma("unroll") for (int _i = 0; _i < 2; ++_i) \
;         __builtin_amdgcn_global_load_lds((const unsigned*)((const char*)(gbase) + (voff)[_i]), (PG8_LAS unsigned*)(lds + (bufoff) + ldsw + _i * 8192), 16, 0, 0); } while (0)
; #define PG8_LDA(dst, b, h) do { _Pragma("unroll") for (int m = 0; m < 4; ++m) _Pragma("unroll") for (int k = 0; k < 2; ++k) dst[m][k] = *(const PG8_LAS bf16x8*)(lds + PG8_SA(b, h) + aoff + m * 2048 + k * 1024); } while (0)
; #define PG8_MMA(ai, bj, At, Bt) do { __builtin_amdgcn_s_setprio(1); _Pragma("unroll") for (int m = 0; m < 4; ++m) _Pragma("unroll") for (int n = 0; n < 2; ++n) _Pragma("unroll") for (int k = 0; k < 2; ++k) \
;         acc[ai][bj][m][n] = __builtin_amdgcn_mfma_f32_16x16x32_bf16(Bt[n][k], At[m][k], acc[ai][bj][m][n], 0, 0, 0); __builtin_amdgcn_s_setprio(0); } while (0)
; #define PG8_WAIT_V(n) asm volatile("s_waitcnt vmcnt(" #n ")" ::: "memory")
; #define PG8_WAIT_L(n) asm volatile("s_waitcnt lgkmcnt(" #n ")" ::: "memory")
; #define PG8_BAR __builtin_amdgcn_s_barrier()
; #define PG8_SCHED __builtin_amdgcn_sched_barrier(0)
;     __device__ __forceinline__ void operator()(const f32x4 (&acc)[2][2][4][2], const Unit& u, int wr, int wc, int fr, int fq) const {
;         const int row0 = u.pm * BM + wr * 64 + fr; const int col0 = u.pn * HALF + wc * 32 + 8 * fq; const float* ss = (const float*)ws + EC_SS; bf16_t* H = (bf16_t*)(ws + EW_H);
; #pragma unroll
;         for (int ai = 0; ai < 2; ++ai)
; #pragma unroll
;             for (int m = 0; m < 4; ++m) { const int row = row0 + ai * HALF + m * 16;
;                 const float r = 1.0f / sqrtf(__hip_atomic_load(ss + row, __ATOMIC_RELAXED, __HIP_MEMORY_SCOPE_AGENT) * (1.0f / 1024.0f) + 1e-6f);
; template <class Epi, class Sched, bool ALIGN_EPI = false, bool SP2 = false>
; __device__ __forceinline__ void gemm_phase(PG8_LAS unsigned char* lds, const Gemm g, const Sched& S, const Epi& E) {
;     ...
;             PG8_LDA(At, 1, 1); PG8_STAGE(PG8_SB(1, 0), b3, voffB); PG8_STAGE(PG8_SB(1, 1), b3 + hstep, voffB); PG8_STAGE(PG8_SA(1, 0), a3, voffA);
;             PG8_WAIT_V(8); PG8_WAIT_L(0); PG8_BAR; PG8_MMA(1, 0, At, B0); PG8_MMA(1, 1, At, B1); PG8_BAR; PG8_SCHED;
	s_add_i32 s51, s51, s46
	v_lshl_add_u64 v[216:217], v[198:199], 0, s[18:19]
	s_mov_b32 m0, s51
	ds_read_b128 v[178:181], v146 offset:49152
	ds_read_b128 v[182:185], v146 offset:50176
	ds_read_b128 v[186:189], v146 offset:51200
	ds_read_b128 v[190:193], v146 offset:52224
	ds_read_b128 v[194:197], v146 offset:53248
	ds_read_b128 v[202:205], v146 offset:54272
	ds_read_b128 v[206:209], v146 offset:55296
	ds_read_b128 v[210:213], v146 offset:56320
	global_load_lds_dwordx4 v[216:217], off
	v_lshl_add_u64 v[216:217], v[198:199], 0, s[20:21]
	s_add_i32 m0, s51, 0x2000
	s_add_i32 s51, s67, s46
	global_load_lds_dwordx4 v[216:217], off
	v_lshl_add_u64 v[216:217], v[198:199], 0, s[22:23]
	s_mov_b32 m0, s51
	v_lshl_add_u64 v[198:199], v[198:199], 0, s[24:25]
	global_load_lds_dwordx4 v[216:217], off
	s_add_i32 m0, s51, 0x2000
	s_nop 0
	global_load_lds_dwordx4 v[198:199], off
	v_lshl_add_u64 v[198:199], v[214:215], 0, s[18:19]
	s_mov_b32 m0, s56
	s_nop 0
	global_load_lds_dwordx4 v[198:199], off
	v_lshl_add_u64 v[198:199], v[214:215], 0, s[20:21]
	s_mov_b32 m0, s57
	s_nop 0
	global_load_lds_dwordx4 v[198:199], off
	s_waitcnt vmcnt(8)
	s_waitcnt lgkmcnt(0)
	s_barrier
	s_setprio 1
	s_waitcnt lgkmcnt(0)
	v_mfma_f32_16x16x32_bf16 v[54:57], v[138:141], v[178:181], v[54:57]
	v_mfma_f32_16x16x32_bf16 v[50:53], v[154:157], v[178:181], v[50:53]
	v_mfma_f32_16x16x32_bf16 v[38:41], v[138:141], v[186:189], v[38:41]
	v_mfma_f32_16x16x32_bf16 v[34:37], v[154:157], v[186:189], v[34:37]
	v_mfma_f32_16x16x32_bf16 v[22:25], v[138:141], v[194:197], v[22:25]
	v_mfma_f32_16x16x32_bf16 v[18:21], v[154:157], v[194:197], v[18:21]
	v_mfma_f32_16x16x32_bf16 v[6:9], v[138:141], v[206:209], v[6:9]
	v_mfma_f32_16x16x32_bf16 v[2:5], v[154:157], v[206:209], v[2:5]
	v_mfma_f32_16x16x32_bf16 v[54:57], v[150:153], v[182:185], v[54:57]
	v_mfma_f32_16x16x32_bf16 v[50:53], v[158:161], v[182:185], v[50:53]
	v_mfma_f32_16x16x32_bf16 v[38:41], v[150:153], v[190:193], v[38:41]
	v_mfma_f32_16x16x32_bf16 v[34:37], v[158:161], v[190:193], v[34:37]
	v_mfma_f32_16x16x32_bf16 v[22:25], v[150:153], v[202:205], v[22:25]
	v_mfma_f32_16x16x32_bf16 v[18:21], v[158:161], v[202:205], v[18:21]
	v_mfma_f32_16x16x32_bf16 v[6:9], v[150:153], v[210:213], v[6:9]
	v_mfma_f32_16x16x32_bf16 v[2:5], v[158:161], v[210:213], v[2:5]
	v_mfma_f32_16x16x32_bf16 v[62:65], v[162:165], v[178:181], v[62:65]
	v_mfma_f32_16x16x32_bf16 v[58:61], v[170:173], v[178:181], v[58:61]
	v_mfma_f32_16x16x32_bf16 v[46:49], v[162:165], v[186:189], v[46:49]
	v_mfma_f32_16x16x32_bf16 v[42:45], v[170:173], v[186:189], v[42:45]
	v_mfma_f32_16x16x32_bf16 v[30:33], v[162:165], v[194:197], v[30:33]
	v_mfma_f32_16x16x32_bf16 v[26:29], v[170:173], v[194:197], v[26:29]
	v_mfma_f32_16x16x32_bf16 v[14:17], v[162:165], v[206:209], v[14:17]
	v_mfma_f32_16x16x32_bf16 v[10:13], v[170:173], v[206:209], v[10:13]
	v_mfma_f32_16x16x32_bf16 v[62:65], v[166:169], v[182:185], v[62:65]
	v_mfma_f32_16x16x32_bf16 v[58:61], v[174:177], v[182:185], v[58:61]
	v_mfma_f32_16x16x32_bf16 v[46:49], v[166:169], v[190:193], v[46:49]
	v_mfma_f32_16x16x32_bf16 v[42:45], v[174:177], v[190:193], v[42:45]
	v_mfma_f32_16x16x32_bf16 v[30:33], v[166:169], v[202:205], v[30:33]
	v_mfma_f32_16x16x32_bf16 v[26:29], v[174:177], v[202:205], v[26:29]
	v_mfma_f32_16x16x32_bf16 v[14:17], v[166:169], v[210:213], v[14:17]
	v_mfma_f32_16x16x32_bf16 v[10:13], v[174:177], v[210:213], v[10:13]
	s_setprio 0
	s_barrier
	s_add_i32 s50, s50, 2
	s_add_u32 s12, s12, 0x8000
	s_addc_u32 s13, s13, 0
	s_add_u32 s44, s44, 0x8000
	s_addc_u32 s45, s45, 0
	s_cmp_gt_u32 s50, 13
	s_cbranch_scc0 .LBB0_981
	s_lshl_b32 s4, s4, 8
	s_add_i32 s4, s4, s58
	v_or_b32_e32 v138, s4, v1
	v_ashrrev_i32_e32 v139, 31, v138
	v_lshl_add_u64 v[140:141], v[138:139], 2, s[30:31]
	v_lshrrev_b32_e32 v218, 4, v142
	v_and_b32_e32 v219, 1, v218
	v_lshrrev_b32_e32 v218, 1, v218
	v_lshlrev_b32_e32 v222, 7, v219
	v_lshl_add_u32 v222, v218, 9, v222
	v_mov_b32_e32 v223, 0
	v_lshl_add_u64 v[220:221], v[140:141], 0, v[222:223]
	global_load_dword v224, v[220:221], off sc1
	global_load_dword v225, v[220:221], off offset:64 sc1
	s_and_b64 vcc, exec, s[28:29]
	s_cbranch_vccz .LBB0_984
	s_barrier

; #define PG8_STAGE(bufoff, gbase, voff) do { _Pragma("unroll") for (int _i = 0; _i < 2; ++_i) \
;         __builtin_amdgcn_global_load_lds((const unsigned*)((const char*)(gbase) + (voff)[_i]), (PG8_LAS unsigned*)(lds + (bufoff) + ldsw + _i * 8192), 16, 0, 0); } while (0)
; #define PG8_LDA(dst, b, h) do { _Pragma("unroll") for (int m = 0; m < 4; ++m) _Pragma("unroll") for (int k = 0; k < 2; ++k) dst[m][k] = *(const PG8_LAS bf16x8*)(lds + PG8_SA(b, h) + aoff + m * 2048 + k * 1024); } while (0)
; #define PG8_LDB(dst, b, h) do { _Pragma("unroll") for (int n = 0; n < 2; ++n) _Pragma("unroll") for (int k = 0; k < 2; ++k) dst[n][k] = *(const PG8_LAS bf16x8*)(lds + PG8_SB(b, h) + boff + n * 2048 + k * 1024); } while (0)
; #define PG8_WAIT_V(n) asm volatile("s_waitcnt vmcnt(" #n ")" ::: "memory")
; #define PG8_WAIT_L(n) asm volatile("s_waitcnt lgkmcnt(" #n ")" ::: "memory")
; #define PG8_BAR __builtin_amdgcn_s_barrier()
; #define PG8_SCHED __builtin_amdgcn_sched_barrier(0)
; template <class Epi, class Sched, bool ALIGN_EPI = false, bool SP2 = false>
; __device__ __forceinline__ void gemm_phase(PG8_LAS unsigned char* lds, const Gemm g, const Sched& S, const Epi& E) {
;     ...
;         const char* nA = has_next ? (const char*)g.A + (size_t)nxt.pm * tstep : cA; const char* nB = has_next ? (const char*)g.Bt + (size_t)nxt.pn * tstep : cB;
;         for (int t = 0; t < nt; t += 2) {
;             const bool last = (t == nt - 2);
;             const char* a1 = cA + (size_t)(t + 1) * kstep;
;             const char* a2 = last ? nA : cA + (size_t)(t + 2) * kstep; const char* b2 = last ? nB : cB + (size_t)(t + 2) * kstep;
;             const char* a3 = a2 + kstep; const char* b3 = b2 + kstep;
;             if (last && has_next) S.a_ready(nxt);
;             if constexpr (SP2) {
;             PG8_LDB(B0, 0, 0); PG8_LDB(B1, 0, 1); PG8_SCHED; PG8_LDA(At, 0, 0); PG8_STAGE(PG8_SA(1, 1), a1 + hstep, voffA);
;             PG8_WAIT_V(8); PG8_WAIT_L(0); PG8_BAR; PG8_MMA(0, 0, At, B0); PG8_MMA(0, 1, At, B1); PG8_BAR; PG8_SCHED;
;             PG8_LDA(At, 0, 1); PG8_STAGE(PG8_SB(0, 0), b2, voffB); PG8_STAGE(PG8_SB(0, 1), b2 + hstep, voffB); PG8_STAGE(PG8_SA(0, 0), a2, voffA);
;             PG8_WAIT_V(8); PG8_WAIT_L(0); PG8_BAR; PG8_MMA(1, 0, At, B0); PG8_MMA(1, 1, At, B1); PG8_BAR; PG8_SCHED;
.LBB0_1423:
	s_add_u32 s12, s12, 0xb4000
	s_addc_u32 s13, s13, 0
	s_add_u32 s36, s36, 0x8000
	s_addc_u32 s37, s37, 0
	s_mov_b32 s57, -2
	ds_read_b128 v[136:139], v143
	ds_read_b128 v[146:149], v143 offset:1024
	ds_read_b128 v[150:153], v143 offset:2048
	ds_read_b128 v[154:157], v143 offset:3072
	ds_read_b128 v[158:161], v144
	ds_read_b128 v[162:165], v144 offset:1024
	ds_read_b128 v[166:169], v144 offset:2048
	ds_read_b128 v[170:173], v144 offset:3072
	s_add_u32 s58, s12, 0xfff54000
	s_addc_u32 s59, s13, -1
	s_cmp_eq_u32 s57, 40
	s_cselect_b32 s59, s3, s59
	s_cselect_b32 s58, s2, s58
	s_cselect_b32 s61, s35, s37
	s_cselect_b32 s60, s34, s36
	v_lshl_add_u64 v[198:199], s[12:13], 0, v[128:129]
	s_add_i32 m0, s39, 0xc000
	ds_read_b128 v[174:177], v145
	ds_read_b128 v[178:181], v145 offset:1024
	ds_read_b128 v[182:185], v145 offset:2048
	ds_read_b128 v[186:189], v145 offset:3072
	ds_read_b128 v[190:193], v145 offset:4096
	ds_read_b128 v[194:197], v145 offset:5120
	ds_read_b128 v[202:205], v145 offset:6144
	ds_read_b128 v[206:209], v145 offset:7168
	global_load_lds_dwordx4 v[198:199], off
	v_lshl_add_u64 v[198:199], v[198:199], 0, s[10:11]
	s_add_i32 m0, s39, 0xe000
	s_nop 0
	global_load_lds_dwordx4 v[198:199], off
	s_waitcnt vmcnt(8)
	s_waitcnt lgkmcnt(0)
	s_barrier
	s_setprio 1
	s_waitcnt lgkmcnt(0)
	v_mfma_f32_16x16x32_bf16 v[124:127], v[136:139], v[174:177], 0
	v_mfma_f32_16x16x32_bf16 v[120:123], v[150:153], v[174:177], 0
	v_mfma_f32_16x16x32_bf16 v[108:111], v[136:139], v[182:185], 0
	v_mfma_f32_16x16x32_bf16 v[104:107], v[150:153], v[182:185], 0
	v_mfma_f32_16x16x32_bf16 v[92:95], v[136:139], v[190:193], 0
	v_mfma_f32_16x16x32_bf16 v[88:91], v[150:153], v[190:193], 0
	v_mfma_f32_16x16x32_bf16 v[76:79], v[136:139], v[202:205], 0
	v_mfma_f32_16x16x32_bf16 v[72:75], v[150:153], v[202:205], 0
	v_mfma_f32_16x16x32_bf16 v[124:127], v[146:149], v[178:181], v[124:127]
	v_mfma_f32_16x16x32_bf16 v[120:123], v[154:157], v[178:181], v[120:123]
	v_mfma_f32_16x16x32_bf16 v[108:111], v[146:149], v[186:189], v[108:111]
	v_mfma_f32_16x16x32_bf16 v[104:107], v[154:157], v[186:189], v[104:107]
	v_mfma_f32_16x16x32_bf16 v[92:95], v[146:149], v[194:197], v[92:95]
	v_mfma_f32_16x16x32_bf16 v[88:91], v[154:157], v[194:197], v[88:91]
	v_mfma_f32_16x16x32_bf16 v[76:79], v[146:149], v[206:209], v[76:79]
	v_mfma_f32_16x16x32_bf16 v[72:75], v[154:157], v[206:209], v[72:75]
	v_mfma_f32_16x16x32_bf16 v[116:119], v[158:161], v[174:177], 0
	v_mfma_f32_16x16x32_bf16 v[112:115], v[166:169], v[174:177], 0
	v_mfma_f32_16x16x32_bf16 v[100:103], v[158:161], v[182:185], 0
	v_mfma_f32_16x16x32_bf16 v[96:99], v[166:169], v[182:185], 0
	v_mfma_f32_16x16x32_bf16 v[84:87], v[158:161], v[190:193], 0
	v_mfma_f32_16x16x32_bf16 v[80:83], v[166:169], v[190:193], 0
	v_mfma_f32_16x16x32_bf16 v[68:71], v[158:161], v[202:205], 0
	v_mfma_f32_16x16x32_bf16 v[64:67], v[166:169], v[202:205], 0
	v_mfma_f32_16x16x32_bf16 v[116:119], v[162:165], v[178:181], v[116:119]
	v_mfma_f32_16x16x32_bf16 v[112:115], v[170:173], v[178:181], v[112:115]
	v_mfma_f32_16x16x32_bf16 v[100:103], v[162:165], v[186:189], v[100:103]
	v_mfma_f32_16x16x32_bf16 v[96:99], v[170:173], v[186:189], v[96:99]
	v_mfma_f32_16x16x32_bf16 v[84:87], v[162:165], v[194:197], v[84:87]
	v_mfma_f32_16x16x32_bf16 v[80:83], v[170:173], v[194:197], v[80:83]
	v_mfma_f32_16x16x32_bf16 v[68:71], v[162:165], v[206:209], v[68:71]
	v_mfma_f32_16x16x32_bf16 v[64:67], v[170:173], v[206:209], v[64:67]
	s_setprio 0
	s_barrier
	v_lshl_add_u64 v[198:199], s[60:61], 0, v[128:129]
	s_add_i32 s60, s51, s38
	s_mov_b32 m0, s60
	ds_read_b128 v[174:177], v145 offset:16384
	ds_read_b128 v[178:181], v145 offset:17408
	ds_read_b128 v[182:185], v145 offset:18432
	ds_read_b128 v[186:189], v145 offset:19456
	ds_read_b128 v[190:193], v145 offset:20480
	ds_read_b128 v[194:197], v145 offset:21504
	ds_read_b128 v[202:205], v145 offset:22528
	ds_read_b128 v[206:209], v145 offset:23552
	global_load_lds_dwordx4 v[198:199], off
	v_lshl_add_u64 v[210:211], v[198:199], 0, s[10:11]
	s_add_i32 m0, s60, 0x2000
	s_add_i32 s60, s52, s38
	global_load_lds_dwordx4 v[210:211], off
	v_lshl_add_u64 v[210:211], v[198:199], 0, s[14:15]
	s_mov_b32 m0, s60
	s_nop 0
	global_load_lds_dwordx4 v[210:211], off
	v_lshl_add_u64 v[210:211], v[198:199], 0, s[16:17]
	s_add_i32 m0, s60, 0x2000
	s_nop 0
	global_load_lds_dwordx4 v[210:211], off
	v_lshl_add_u64 v[210:211], s[58:59], 0, v[128:129]
	s_mov_b32 m0, s39
	v_lshl_add_u64 v[212:213], v[210:211], 0, s[10:11]
	global_load_lds_dwordx4 v[210:211], off
	s_mov_b32 m0, s40
	s_nop 0
	global_load_lds_dwordx4 v[212:213], off
	s_waitcnt vmcnt(8)
	s_waitcnt lgkmcnt(0)
	s_barrier
; #define PG8_STAGE(bufoff, gbase, voff) do { _Pragma("unroll") for (int _i = 0; _i < 2; ++_i) \
;         __builtin_amdgcn_global_load_lds((const unsigned*)((const char*)(gbase) + (voff)[_i]), (PG8_LAS unsigned*)(lds + (bufoff) + ldsw + _i * 8192), 16, 0, 0); } while (0)
; #define PG8_LDA(dst, b, h) do { _Pragma("unroll") for (int m = 0; m < 4; ++m) _Pragma("unroll") for (int k = 0; k < 2; ++k) dst[m][k] = *(const PG8_LAS bf16x8*)(lds + PG8_SA(b, h) + aoff + m * 2048 + k * 1024); } while (0)
; #define PG8_LDB(dst, b, h) do { _Pragma("unroll") for (int n = 0; n < 2; ++n) _Pragma("unroll") for (int k = 0; k < 2; ++k) dst[n][k] = *(const PG8_LAS bf16x8*)(lds + PG8_SB(b, h) + boff + n * 2048 + k * 1024); } while (0)
; #define PG8_MMA(ai, bj, At, Bt) do { __builtin_amdgcn_s_setprio(1); _Pragma("unroll") for (int m = 0; m < 4; ++m) _Pragma("unroll") for (int n = 0; n < 2; ++n) _Pragma("unroll") for (int k = 0; k < 2; ++k) \
;         acc[ai][bj][m][n] = __builtin_amdgcn_mfma_f32_16x16x32_bf16(Bt[n][k], At[m][k], acc[ai][bj][m][n], 0, 0, 0); __builtin_amdgcn_s_setprio(0); } while (0)
; #define PG8_WAIT_V(n) asm volatile("s_waitcnt vmcnt(" #n ")" ::: "memory")
; #define PG8_WAIT_L(n) asm volatile("s_waitcnt lgkmcnt(" #n ")" ::: "memory")
; #define PG8_BAR __builtin_amdgcn_s_barrier()
; #define PG8_SCHED __builtin_amdgcn_sched_barrier(0)
; template <class Epi, class Sched, bool ALIGN_EPI = false, bool SP2 = false>
; __device__ __forceinline__ void gemm_phase(PG8_LAS unsigned char* lds, const Gemm g, const Sched& S, const Epi& E) {
;     ...
;             PG8_WAIT_V(8); PG8_WAIT_L(0); PG8_BAR; PG8_MMA(1, 0, At, B0); PG8_MMA(1, 1, At, B1); PG8_BAR; PG8_SCHED;
;             PG8_LDB(B0, 1, 0); PG8_LDB(B1, 1, 1); PG8_SCHED; PG8_LDA(At, 1, 0); PG8_STAGE(PG8_SA(0, 1), a2 + hstep, voffA);
;             PG8_WAIT_V(8); PG8_WAIT_L(0); PG8_BAR; PG8_MMA(0, 0, At, B0); PG8_MMA(0, 1, At, B1); PG8_BAR; PG8_SCHED;
	s_setprio 1
	s_waitcnt lgkmcnt(0)
	v_mfma_f32_16x16x32_bf16 v[60:63], v[136:139], v[174:177], 0
	v_mfma_f32_16x16x32_bf16 v[56:59], v[150:153], v[174:177], 0
	v_mfma_f32_16x16x32_bf16 v[44:47], v[136:139], v[182:185], 0
	v_mfma_f32_16x16x32_bf16 v[40:43], v[150:153], v[182:185], 0
	v_mfma_f32_16x16x32_bf16 v[28:31], v[136:139], v[190:193], 0
	v_mfma_f32_16x16x32_bf16 v[24:27], v[150:153], v[190:193], 0
	v_mfma_f32_16x16x32_bf16 v[12:15], v[136:139], v[202:205], 0
	v_mfma_f32_16x16x32_bf16 v[8:11], v[150:153], v[202:205], 0
	v_mfma_f32_16x16x32_bf16 v[60:63], v[146:149], v[178:181], v[60:63]
	v_mfma_f32_16x16x32_bf16 v[56:59], v[154:157], v[178:181], v[56:59]
	v_mfma_f32_16x16x32_bf16 v[44:47], v[146:149], v[186:189], v[44:47]
	v_mfma_f32_16x16x32_bf16 v[40:43], v[154:157], v[186:189], v[40:43]
	v_mfma_f32_16x16x32_bf16 v[28:31], v[146:149], v[194:197], v[28:31]
	v_mfma_f32_16x16x32_bf16 v[24:27], v[154:157], v[194:197], v[24:27]
	v_mfma_f32_16x16x32_bf16 v[12:15], v[146:149], v[206:209], v[12:15]
	v_mfma_f32_16x16x32_bf16 v[8:11], v[154:157], v[206:209], v[8:11]
	v_mfma_f32_16x16x32_bf16 v[52:55], v[158:161], v[174:177], 0
	v_mfma_f32_16x16x32_bf16 v[48:51], v[166:169], v[174:177], 0
	v_mfma_f32_16x16x32_bf16 v[36:39], v[158:161], v[182:185], 0
	v_mfma_f32_16x16x32_bf16 v[32:35], v[166:169], v[182:185], 0
	v_mfma_f32_16x16x32_bf16 v[20:23], v[158:161], v[190:193], 0
	v_mfma_f32_16x16x32_bf16 v[16:19], v[166:169], v[190:193], 0
	v_mfma_f32_16x16x32_bf16 v[4:7], v[158:161], v[202:205], 0
	v_mfma_f32_16x16x32_bf16 v[0:3], v[166:169], v[202:205], 0
	v_mfma_f32_16x16x32_bf16 v[52:55], v[162:165], v[178:181], v[52:55]
	v_mfma_f32_16x16x32_bf16 v[48:51], v[170:173], v[178:181], v[48:51]
	v_mfma_f32_16x16x32_bf16 v[36:39], v[162:165], v[186:189], v[36:39]
	v_mfma_f32_16x16x32_bf16 v[32:35], v[170:173], v[186:189], v[32:35]
	v_mfma_f32_16x16x32_bf16 v[20:23], v[162:165], v[194:197], v[20:23]
	v_mfma_f32_16x16x32_bf16 v[16:19], v[170:173], v[194:197], v[16:19]
	v_mfma_f32_16x16x32_bf16 v[4:7], v[162:165], v[206:209], v[4:7]
	v_mfma_f32_16x16x32_bf16 v[0:3], v[170:173], v[206:209], v[0:3]
	s_setprio 0
	s_barrier
	s_add_i32 s58, 0, 0x18000
	v_add_u32_e32 v130, s58, v142
	s_add_i32 s59, 0, 0x1c000
	ds_read_b128 v[136:139], v130
	ds_read_b128 v[146:149], v130 offset:1024
	ds_read_b128 v[150:153], v130 offset:2048
	ds_read_b128 v[154:157], v130 offset:3072
	v_add_u32_e32 v130, s59, v142
	ds_read_b128 v[158:161], v130
	ds_read_b128 v[162:165], v130 offset:1024
	ds_read_b128 v[166:169], v130 offset:2048
	ds_read_b128 v[170:173], v130 offset:3072
	s_mov_b32 m0, s41
	v_lshl_add_u64 v[212:213], v[210:211], 0, s[14:15]
	ds_read_b128 v[174:177], v145 offset:32768
	ds_read_b128 v[178:181], v145 offset:33792
	ds_read_b128 v[182:185], v145 offset:34816
	ds_read_b128 v[186:189], v145 offset:35840
	ds_read_b128 v[190:193], v145 offset:36864
	ds_read_b128 v[194:197], v145 offset:37888
	ds_read_b128 v[202:205], v145 offset:38912
	ds_read_b128 v[206:209], v145 offset:39936
	global_load_lds_dwordx4 v[212:213], off
	v_lshl_add_u64 v[212:213], v[210:211], 0, s[16:17]
	s_mov_b32 m0, s42
	s_nop 0
	global_load_lds_dwordx4 v[212:213], off
	s_waitcnt vmcnt(8)
	s_waitcnt lgkmcnt(0)
	s_barrier
	s_setprio 1
	s_waitcnt lgkmcnt(0)
	v_mfma_f32_16x16x32_bf16 v[124:127], v[136:139], v[174:177], v[124:127]
	v_mfma_f32_16x16x32_bf16 v[120:123], v[150:153], v[174:177], v[120:123]
	v_mfma_f32_16x16x32_bf16 v[108:111], v[136:139], v[182:185], v[108:111]
	v_mfma_f32_16x16x32_bf16 v[104:107], v[150:153], v[182:185], v[104:107]
	v_mfma_f32_16x16x32_bf16 v[92:95], v[136:139], v[190:193], v[92:95]
	v_mfma_f32_16x16x32_bf16 v[88:91], v[150:153], v[190:193], v[88:91]
	v_mfma_f32_16x16x32_bf16 v[76:79], v[136:139], v[202:205], v[76:79]
	v_mfma_f32_16x16x32_bf16 v[72:75], v[150:153], v[202:205], v[72:75]
	v_mfma_f32_16x16x32_bf16 v[124:127], v[146:149], v[178:181], v[124:127]
	v_mfma_f32_16x16x32_bf16 v[120:123], v[154:157], v[178:181], v[120:123]
	v_mfma_f32_16x16x32_bf16 v[108:111], v[146:149], v[186:189], v[108:111]
	v_mfma_f32_16x16x32_bf16 v[104:107], v[154:157], v[186:189], v[104:107]
	v_mfma_f32_16x16x32_bf16 v[92:95], v[146:149], v[194:197], v[92:95]
	v_mfma_f32_16x16x32_bf16 v[88:91], v[154:157], v[194:197], v[88:91]
	v_mfma_f32_16x16x32_bf16 v[76:79], v[146:149], v[206:209], v[76:79]
	v_mfma_f32_16x16x32_bf16 v[72:75], v[154:157], v[206:209], v[72:75]
	v_mfma_f32_16x16x32_bf16 v[116:119], v[158:161], v[174:177], v[116:119]
	v_mfma_f32_16x16x32_bf16 v[112:115], v[166:169], v[174:177], v[112:115]
	v_mfma_f32_16x16x32_bf16 v[100:103], v[158:161], v[182:185], v[100:103]
	v_mfma_f32_16x16x32_bf16 v[96:99], v[166:169], v[182:185], v[96:99]
	v_mfma_f32_16x16x32_bf16 v[84:87], v[158:161], v[190:193], v[84:87]
	v_mfma_f32_16x16x32_bf16 v[80:83], v[166:169], v[190:193], v[80:83]
	v_mfma_f32_16x16x32_bf16 v[68:71], v[158:161], v[202:205], v[68:71]
	v_mfma_f32_16x16x32_bf16 v[64:67], v[166:169], v[202:205], v[64:67]
	v_mfma_f32_16x16x32_bf16 v[116:119], v[162:165], v[178:181], v[116:119]
	v_mfma_f32_16x16x32_bf16 v[112:115], v[170:173], v[178:181], v[112:115]
	v_mfma_f32_16x16x32_bf16 v[100:103], v[162:165], v[186:189], v[100:103]
	v_mfma_f32_16x16x32_bf16 v[96:99], v[170:173], v[186:189], v[96:99]
	v_mfma_f32_16x16x32_bf16 v[84:87], v[162:165], v[194:197], v[84:87]
	v_mfma_f32_16x16x32_bf16 v[80:83], v[170:173], v[194:197], v[80:83]
	v_mfma_f32_16x16x32_bf16 v[68:71], v[162:165], v[206:209], v[68:71]
	v_mfma_f32_16x16x32_bf16 v[64:67], v[170:173], v[206:209], v[64:67]
	s_setprio 0
	s_barrier
; #define PG8_STAGE(bufoff, gbase, voff) do { _Pragma("unroll") for (int _i = 0; _i < 2; ++_i) \
;         __builtin_amdgcn_global_load_lds((const unsigned*)((const char*)(gbase) + (voff)[_i]), (PG8_LAS unsigned*)(lds + (bufoff) + ldsw + _i * 8192), 16, 0, 0); } while (0)
; #define PG8_LDA(dst, b, h) do { _Pragma("unroll") for (int m = 0; m < 4; ++m) _Pragma("unroll") for (int k = 0; k < 2; ++k) dst[m][k] = *(const PG8_LAS bf16x8*)(lds + PG8_SA(b, h) + aoff + m * 2048 + k * 1024); } while (0)
; #define PG8_LDB(dst, b, h) do { _Pragma("unroll") for (int n = 0; n < 2; ++n) _Pragma("unroll") for (int k = 0; k < 2; ++k) dst[n][k] = *(const PG8_LAS bf16x8*)(lds + PG8_SB(b, h) + boff + n * 2048 + k * 1024); } while (0)
; #define PG8_MMA(ai, bj, At, Bt) do { __builtin_amdgcn_s_setprio(1); _Pragma("unroll") for (int m = 0; m < 4; ++m) _Pragma("unroll") for (int n = 0; n < 2; ++n) _Pragma("unroll") for (int k = 0; k < 2; ++k) \
;         acc[ai][bj][m][n] = __builtin_amdgcn_mfma_f32_16x16x32_bf16(Bt[n][k], At[m][k], acc[ai][bj][m][n], 0, 0, 0); __builtin_amdgcn_s_setprio(0); } while (0)
; #define PG8_WAIT_V(n) asm volatile("s_waitcnt vmcnt(" #n ")" ::: "memory")
; #define PG8_WAIT_L(n) asm volatile("s_waitcnt lgkmcnt(" #n ")" ::: "memory")
; #define PG8_BAR __builtin_amdgcn_s_barrier()
; #define PG8_SCHED __builtin_amdgcn_sched_barrier(0)
; template <class Epi, class Sched, bool ALIGN_EPI = false, bool SP2 = false>
; __device__ __forceinline__ void gemm_phase(PG8_LAS unsigned char* lds, const Gemm g, const Sched& S, const Epi& E) {
;     ...
;             PG8_LDB(B0, 0, 0); PG8_LDB(B1, 0, 1); PG8_SCHED; PG8_LDA(At, 0, 0); PG8_STAGE(PG8_SA(1, 1), a1 + hstep, voffA);
;             PG8_WAIT_V(8); PG8_WAIT_L(0); PG8_BAR; PG8_MMA(0, 0, At, B0); PG8_MMA(0, 1, At, B1); PG8_BAR; PG8_SCHED;
;     ...
;             PG8_LDA(At, 1, 1); PG8_STAGE(PG8_SB(1, 0), b3, voffB); PG8_STAGE(PG8_SB(1, 1), b3 + hstep, voffB); PG8_STAGE(PG8_SA(1, 0), a3, voffA);
;             PG8_WAIT_V(8); PG8_WAIT_L(0); PG8_BAR; PG8_MMA(1, 0, At, B0); PG8_MMA(1, 1, At, B1); PG8_BAR; PG8_SCHED;
	s_add_i32 s58, s58, s38
	v_lshl_add_u64 v[212:213], v[198:199], 0, s[20:21]
	s_mov_b32 m0, s58
	ds_read_b128 v[174:177], v145 offset:49152
	ds_read_b128 v[178:181], v145 offset:50176
	ds_read_b128 v[182:185], v145 offset:51200
	ds_read_b128 v[186:189], v145 offset:52224
	ds_read_b128 v[190:193], v145 offset:53248
	ds_read_b128 v[194:197], v145 offset:54272
	ds_read_b128 v[202:205], v145 offset:55296
	ds_read_b128 v[206:209], v145 offset:56320
	global_load_lds_dwordx4 v[212:213], off
	v_lshl_add_u64 v[212:213], v[198:199], 0, s[22:23]
	s_add_i32 m0, s58, 0x2000
	s_add_i32 s58, s59, s38
	global_load_lds_dwordx4 v[212:213], off
	v_lshl_add_u64 v[212:213], v[198:199], 0, s[24:25]
	s_mov_b32 m0, s58
	v_lshl_add_u64 v[198:199], v[198:199], 0, s[26:27]
	global_load_lds_dwordx4 v[212:213], off
	s_add_i32 m0, s58, 0x2000
	s_nop 0
	global_load_lds_dwordx4 v[198:199], off
	v_lshl_add_u64 v[198:199], v[210:211], 0, s[20:21]
	s_mov_b32 m0, s46
	s_nop 0
	global_load_lds_dwordx4 v[198:199], off
	v_lshl_add_u64 v[198:199], v[210:211], 0, s[22:23]
	s_mov_b32 m0, s47
	s_nop 0
	global_load_lds_dwordx4 v[198:199], off
	s_waitcnt vmcnt(8)
	s_waitcnt lgkmcnt(0)
	s_barrier
	s_setprio 1
	s_waitcnt lgkmcnt(0)
	v_mfma_f32_16x16x32_bf16 v[60:63], v[136:139], v[174:177], v[60:63]
	v_mfma_f32_16x16x32_bf16 v[56:59], v[150:153], v[174:177], v[56:59]
	v_mfma_f32_16x16x32_bf16 v[44:47], v[136:139], v[182:185], v[44:47]
	v_mfma_f32_16x16x32_bf16 v[40:43], v[150:153], v[182:185], v[40:43]
	v_mfma_f32_16x16x32_bf16 v[28:31], v[136:139], v[190:193], v[28:31]
	v_mfma_f32_16x16x32_bf16 v[24:27], v[150:153], v[190:193], v[24:27]
	v_mfma_f32_16x16x32_bf16 v[12:15], v[136:139], v[202:205], v[12:15]
	v_mfma_f32_16x16x32_bf16 v[8:11], v[150:153], v[202:205], v[8:11]
	v_mfma_f32_16x16x32_bf16 v[60:63], v[146:149], v[178:181], v[60:63]
	v_mfma_f32_16x16x32_bf16 v[56:59], v[154:157], v[178:181], v[56:59]
	v_mfma_f32_16x16x32_bf16 v[44:47], v[146:149], v[186:189], v[44:47]
	v_mfma_f32_16x16x32_bf16 v[40:43], v[154:157], v[186:189], v[40:43]
	v_mfma_f32_16x16x32_bf16 v[28:31], v[146:149], v[194:197], v[28:31]
	v_mfma_f32_16x16x32_bf16 v[24:27], v[154:157], v[194:197], v[24:27]
	v_mfma_f32_16x16x32_bf16 v[12:15], v[146:149], v[206:209], v[12:15]
	v_mfma_f32_16x16x32_bf16 v[8:11], v[154:157], v[206:209], v[8:11]
	v_mfma_f32_16x16x32_bf16 v[52:55], v[158:161], v[174:177], v[52:55]
	v_mfma_f32_16x16x32_bf16 v[48:51], v[166:169], v[174:177], v[48:51]
	v_mfma_f32_16x16x32_bf16 v[36:39], v[158:161], v[182:185], v[36:39]
	v_mfma_f32_16x16x32_bf16 v[32:35], v[166:169], v[182:185], v[32:35]
	v_mfma_f32_16x16x32_bf16 v[20:23], v[158:161], v[190:193], v[20:23]
	v_mfma_f32_16x16x32_bf16 v[16:19], v[166:169], v[190:193], v[16:19]
	v_mfma_f32_16x16x32_bf16 v[4:7], v[158:161], v[202:205], v[4:7]
	v_mfma_f32_16x16x32_bf16 v[0:3], v[166:169], v[202:205], v[0:3]
	v_mfma_f32_16x16x32_bf16 v[52:55], v[162:165], v[178:181], v[52:55]
	v_mfma_f32_16x16x32_bf16 v[48:51], v[170:173], v[178:181], v[48:51]
	v_mfma_f32_16x16x32_bf16 v[36:39], v[162:165], v[186:189], v[36:39]
	v_mfma_f32_16x16x32_bf16 v[32:35], v[170:173], v[186:189], v[32:35]
	v_mfma_f32_16x16x32_bf16 v[20:23], v[162:165], v[194:197], v[20:23]
	v_mfma_f32_16x16x32_bf16 v[16:19], v[170:173], v[194:197], v[16:19]
	v_mfma_f32_16x16x32_bf16 v[4:7], v[162:165], v[206:209], v[4:7]
	v_mfma_f32_16x16x32_bf16 v[0:3], v[170:173], v[206:209], v[0:3]
	s_setprio 0
	s_barrier
	s_add_i32 s57, s57, 2
	s_add_u32 s12, s12, 0x8000
	s_addc_u32 s13, s13, 0
	s_add_u32 s36, s36, 0x8000
	s_addc_u32 s37, s37, 0
	s_cmp_gt_u32 s57, 41
	s_cbranch_scc0 .LBB0_1424
.LBB0_1424:
	ds_read_b128 v[136:139], v143
	ds_read_b128 v[146:149], v143 offset:1024
	ds_read_b128 v[150:153], v143 offset:2048
	ds_read_b128 v[154:157], v143 offset:3072
	ds_read_b128 v[158:161], v144
	ds_read_b128 v[162:165], v144 offset:1024
	ds_read_b128 v[166:169], v144 offset:2048
	ds_read_b128 v[170:173], v144 offset:3072
	s_add_u32 s58, s12, 0xfff54000
	s_addc_u32 s59, s13, -1
	s_cmp_eq_u32 s57, 40
	s_cselect_b32 s59, s3, s59
	s_cselect_b32 s58, s2, s58
	s_cselect_b32 s61, s35, s37
	s_cselect_b32 s60, s34, s36
	v_lshl_add_u64 v[198:199], s[12:13], 0, v[128:129]
	s_add_i32 m0, s39, 0xc000
	ds_read_b128 v[174:177], v145
	ds_read_b128 v[178:181], v145 offset:1024
	ds_read_b128 v[182:185], v145 offset:2048
	ds_read_b128 v[186:189], v145 offset:3072
	ds_read_b128 v[190:193], v145 offset:4096
	ds_read_b128 v[194:197], v145 offset:5120
	ds_read_b128 v[202:205], v145 offset:6144
	ds_read_b128 v[206:209], v145 offset:7168
	global_load_lds_dwordx4 v[198:199], off
	v_lshl_add_u64 v[198:199], v[198:199], 0, s[10:11]
	s_add_i32 m0, s39, 0xe000
	s_nop 0
	global_load_lds_dwordx4 v[198:199], off
	s_waitcnt vmcnt(8)
	s_waitcnt lgkmcnt(0)
	s_barrier
; #define PG8_STAGE(bufoff, gbase, voff) do { _Pragma("unroll") for (int _i = 0; _i < 2; ++_i) \
;         __builtin_amdgcn_global_load_lds((const unsigned*)((const char*)(gbase) + (voff)[_i]), (PG8_LAS unsigned*)(lds + (bufoff) + ldsw + _i * 8192), 16, 0, 0); } while (0)
; #define PG8_LDA(dst, b, h) do { _Pragma("unroll") for (int m = 0; m < 4; ++m) _Pragma("unroll") for (int k = 0; k < 2; ++k) dst[m][k] = *(const PG8_LAS bf16x8*)(lds + PG8_SA(b, h) + aoff + m * 2048 + k * 1024); } while (0)
; #define PG8_LDB(dst, b, h) do { _Pragma("unroll") for (int n = 0; n < 2; ++n) _Pragma("unroll") for (int k = 0; k < 2; ++k) dst[n][k] = *(const PG8_LAS bf16x8*)(lds + PG8_SB(b, h) + boff + n * 2048 + k * 1024); } while (0)
; #define PG8_MMA(ai, bj, At, Bt) do { __builtin_amdgcn_s_setprio(1); _Pragma("unroll") for (int m = 0; m < 4; ++m) _Pragma("unroll") for (int n = 0; n < 2; ++n) _Pragma("unroll") for (int k = 0; k < 2; ++k) \
;         acc[ai][bj][m][n] = __builtin_amdgcn_mfma_f32_16x16x32_bf16(Bt[n][k], At[m][k], acc[ai][bj][m][n], 0, 0, 0); __builtin_amdgcn_s_setprio(0); } while (0)
; #define PG8_WAIT_V(n) asm volatile("s_waitcnt vmcnt(" #n ")" ::: "memory")
; #define PG8_WAIT_L(n) asm volatile("s_waitcnt lgkmcnt(" #n ")" ::: "memory")
; #define PG8_BAR __builtin_amdgcn_s_barrier()
; #define PG8_SCHED __builtin_amdgcn_sched_barrier(0)
; template <class Epi, class Sched, bool ALIGN_EPI = false, bool SP2 = false>
; __device__ __forceinline__ void gemm_phase(PG8_LAS unsigned char* lds, const Gemm g, const Sched& S, const Epi& E) {
;     ...
;             PG8_WAIT_V(8); PG8_WAIT_L(0); PG8_BAR; PG8_MMA(0, 0, At, B0); PG8_MMA(0, 1, At, B1); PG8_BAR; PG8_SCHED;
;             PG8_LDA(At, 0, 1); PG8_STAGE(PG8_SB(0, 0), b2, voffB); PG8_STAGE(PG8_SB(0, 1), b2 + hstep, voffB); PG8_STAGE(PG8_SA(0, 0), a2, voffA);
;             PG8_WAIT_V(8); PG8_WAIT_L(0); PG8_BAR; PG8_MMA(1, 0, At, B0); PG8_MMA(1, 1, At, B1); PG8_BAR; PG8_SCHED;
;             PG8_LDB(B0, 1, 0); PG8_LDB(B1, 1, 1); PG8_SCHED; PG8_LDA(At, 1, 0); PG8_STAGE(PG8_SA(0, 1), a2 + hstep, voffA);
;             PG8_WAIT_V(8); PG8_WAIT_L(0); PG8_BAR; PG8_MMA(0, 0, At, B0); PG8_MMA(0, 1, At, B1); PG8_BAR; PG8_SCHED;
	s_setprio 1
	s_waitcnt lgkmcnt(0)
	v_mfma_f32_16x16x32_bf16 v[124:127], v[136:139], v[174:177], v[124:127]
	v_mfma_f32_16x16x32_bf16 v[120:123], v[150:153], v[174:177], v[120:123]
	v_mfma_f32_16x16x32_bf16 v[108:111], v[136:139], v[182:185], v[108:111]
	v_mfma_f32_16x16x32_bf16 v[104:107], v[150:153], v[182:185], v[104:107]
	v_mfma_f32_16x16x32_bf16 v[92:95], v[136:139], v[190:193], v[92:95]
	v_mfma_f32_16x16x32_bf16 v[88:91], v[150:153], v[190:193], v[88:91]
	v_mfma_f32_16x16x32_bf16 v[76:79], v[136:139], v[202:205], v[76:79]
	v_mfma_f32_16x16x32_bf16 v[72:75], v[150:153], v[202:205], v[72:75]
	v_mfma_f32_16x16x32_bf16 v[124:127], v[146:149], v[178:181], v[124:127]
	v_mfma_f32_16x16x32_bf16 v[120:123], v[154:157], v[178:181], v[120:123]
	v_mfma_f32_16x16x32_bf16 v[108:111], v[146:149], v[186:189], v[108:111]
	v_mfma_f32_16x16x32_bf16 v[104:107], v[154:157], v[186:189], v[104:107]
	v_mfma_f32_16x16x32_bf16 v[92:95], v[146:149], v[194:197], v[92:95]
	v_mfma_f32_16x16x32_bf16 v[88:91], v[154:157], v[194:197], v[88:91]
	v_mfma_f32_16x16x32_bf16 v[76:79], v[146:149], v[206:209], v[76:79]
	v_mfma_f32_16x16x32_bf16 v[72:75], v[154:157], v[206:209], v[72:75]
	v_mfma_f32_16x16x32_bf16 v[116:119], v[158:161], v[174:177], v[116:119]
	v_mfma_f32_16x16x32_bf16 v[112:115], v[166:169], v[174:177], v[112:115]
	v_mfma_f32_16x16x32_bf16 v[100:103], v[158:161], v[182:185], v[100:103]
	v_mfma_f32_16x16x32_bf16 v[96:99], v[166:169], v[182:185], v[96:99]
	v_mfma_f32_16x16x32_bf16 v[84:87], v[158:161], v[190:193], v[84:87]
	v_mfma_f32_16x16x32_bf16 v[80:83], v[166:169], v[190:193], v[80:83]
	v_mfma_f32_16x16x32_bf16 v[68:71], v[158:161], v[202:205], v[68:71]
	v_mfma_f32_16x16x32_bf16 v[64:67], v[166:169], v[202:205], v[64:67]
	v_mfma_f32_16x16x32_bf16 v[116:119], v[162:165], v[178:181], v[116:119]
	v_mfma_f32_16x16x32_bf16 v[112:115], v[170:173], v[178:181], v[112:115]
	v_mfma_f32_16x16x32_bf16 v[100:103], v[162:165], v[186:189], v[100:103]
	v_mfma_f32_16x16x32_bf16 v[96:99], v[170:173], v[186:189], v[96:99]
	v_mfma_f32_16x16x32_bf16 v[84:87], v[162:165], v[194:197], v[84:87]
	v_mfma_f32_16x16x32_bf16 v[80:83], v[170:173], v[194:197], v[80:83]
	v_mfma_f32_16x16x32_bf16 v[68:71], v[162:165], v[206:209], v[68:71]
	v_mfma_f32_16x16x32_bf16 v[64:67], v[170:173], v[206:209], v[64:67]
	s_setprio 0
	s_barrier
	v_lshl_add_u64 v[198:199], s[60:61], 0, v[128:129]
	s_add_i32 s60, s51, s38
	s_mov_b32 m0, s60
	ds_read_b128 v[174:177], v145 offset:16384
	ds_read_b128 v[178:181], v145 offset:17408
	ds_read_b128 v[182:185], v145 offset:18432
	ds_read_b128 v[186:189], v145 offset:19456
	ds_read_b128 v[190:193], v145 offset:20480
	ds_read_b128 v[194:197], v145 offset:21504
	ds_read_b128 v[202:205], v145 offset:22528
	ds_read_b128 v[206:209], v145 offset:23552
	global_load_lds_dwordx4 v[198:199], off
	v_lshl_add_u64 v[210:211], v[198:199], 0, s[10:11]
	s_add_i32 m0, s60, 0x2000
	s_add_i32 s60, s52, s38
	global_load_lds_dwordx4 v[210:211], off
	v_lshl_add_u64 v[210:211], v[198:199], 0, s[14:15]
	s_mov_b32 m0, s60
	s_nop 0
	global_load_lds_dwordx4 v[210:211], off
	v_lshl_add_u64 v[210:211], v[198:199], 0, s[16:17]
	s_add_i32 m0, s60, 0x2000
	s_nop 0
	global_load_lds_dwordx4 v[210:211], off
	v_lshl_add_u64 v[210:211], s[58:59], 0, v[128:129]
	s_mov_b32 m0, s39
	v_lshl_add_u64 v[212:213], v[210:211], 0, s[10:11]
	global_load_lds_dwordx4 v[210:211], off
	s_mov_b32 m0, s40
	s_nop 0
	global_load_lds_dwordx4 v[212:213], off
	s_waitcnt vmcnt(8)
	s_waitcnt lgkmcnt(0)
	s_barrier
	s_setprio 1
	s_waitcnt lgkmcnt(0)
	v_mfma_f32_16x16x32_bf16 v[60:63], v[136:139], v[174:177], v[60:63]
	v_mfma_f32_16x16x32_bf16 v[56:59], v[150:153], v[174:177], v[56:59]
	v_mfma_f32_16x16x32_bf16 v[44:47], v[136:139], v[182:185], v[44:47]
	v_mfma_f32_16x16x32_bf16 v[40:43], v[150:153], v[182:185], v[40:43]
	v_mfma_f32_16x16x32_bf16 v[28:31], v[136:139], v[190:193], v[28:31]
	v_mfma_f32_16x16x32_bf16 v[24:27], v[150:153], v[190:193], v[24:27]
	v_mfma_f32_16x16x32_bf16 v[12:15], v[136:139], v[202:205], v[12:15]
	v_mfma_f32_16x16x32_bf16 v[8:11], v[150:153], v[202:205], v[8:11]
	v_mfma_f32_16x16x32_bf16 v[60:63], v[146:149], v[178:181], v[60:63]
	v_mfma_f32_16x16x32_bf16 v[56:59], v[154:157], v[178:181], v[56:59]
	v_mfma_f32_16x16x32_bf16 v[44:47], v[146:149], v[186:189], v[44:47]
	v_mfma_f32_16x16x32_bf16 v[40:43], v[154:157], v[186:189], v[40:43]
	v_mfma_f32_16x16x32_bf16 v[28:31], v[146:149], v[194:197], v[28:31]
	v_mfma_f32_16x16x32_bf16 v[24:27], v[154:157], v[194:197], v[24:27]
	v_mfma_f32_16x16x32_bf16 v[12:15], v[146:149], v[206:209], v[12:15]
	v_mfma_f32_16x16x32_bf16 v[8:11], v[154:157], v[206:209], v[8:11]
	v_mfma_f32_16x16x32_bf16 v[52:55], v[158:161], v[174:177], v[52:55]
	v_mfma_f32_16x16x32_bf16 v[48:51], v[166:169], v[174:177], v[48:51]
	v_mfma_f32_16x16x32_bf16 v[36:39], v[158:161], v[182:185], v[36:39]
	v_mfma_f32_16x16x32_bf16 v[32:35], v[166:169], v[182:185], v[32:35]
	v_mfma_f32_16x16x32_bf16 v[20:23], v[158:161], v[190:193], v[20:23]
	v_mfma_f32_16x16x32_bf16 v[16:19], v[166:169], v[190:193], v[16:19]
	v_mfma_f32_16x16x32_bf16 v[4:7], v[158:161], v[202:205], v[4:7]
	v_mfma_f32_16x16x32_bf16 v[0:3], v[166:169], v[202:205], v[0:3]
	v_mfma_f32_16x16x32_bf16 v[52:55], v[162:165], v[178:181], v[52:55]
	v_mfma_f32_16x16x32_bf16 v[48:51], v[170:173], v[178:181], v[48:51]
	v_mfma_f32_16x16x32_bf16 v[36:39], v[162:165], v[186:189], v[36:39]
	v_mfma_f32_16x16x32_bf16 v[32:35], v[170:173], v[186:189], v[32:35]
	v_mfma_f32_16x16x32_bf16 v[20:23], v[162:165], v[194:197], v[20:23]
	v_mfma_f32_16x16x32_bf16 v[16:19], v[170:173], v[194:197], v[16:19]
	v_mfma_f32_16x16x32_bf16 v[4:7], v[162:165], v[206:209], v[4:7]
	v_mfma_f32_16x16x32_bf16 v[0:3], v[170:173], v[206:209], v[0:3]
	s_setprio 0
	s_barrier
; #define PG8_STAGE(bufoff, gbase, voff) do { _Pragma("unroll") for (int _i = 0; _i < 2; ++_i) \
;         __builtin_amdgcn_global_load_lds((const unsigned*)((const char*)(gbase) + (voff)[_i]), (PG8_LAS unsigned*)(lds + (bufoff) + ldsw + _i * 8192), 16, 0, 0); } while (0)
; #define PG8_LDA(dst, b, h) do { _Pragma("unroll") for (int m = 0; m < 4; ++m) _Pragma("unroll") for (int k = 0; k < 2; ++k) dst[m][k] = *(const PG8_LAS bf16x8*)(lds + PG8_SA(b, h) + aoff + m * 2048 + k * 1024); } while (0)
; #define PG8_LDB(dst, b, h) do { _Pragma("unroll") for (int n = 0; n < 2; ++n) _Pragma("unroll") for (int k = 0; k < 2; ++k) dst[n][k] = *(const PG8_LAS bf16x8*)(lds + PG8_SB(b, h) + boff + n * 2048 + k * 1024); } while (0)
; #define PG8_MMA(ai, bj, At, Bt) do { __builtin_amdgcn_s_setprio(1); _Pragma("unroll") for (int m = 0; m < 4; ++m) _Pragma("unroll") for (int n = 0; n < 2; ++n) _Pragma("unroll") for (int k = 0; k < 2; ++k) \
;         acc[ai][bj][m][n] = __builtin_amdgcn_mfma_f32_16x16x32_bf16(Bt[n][k], At[m][k], acc[ai][bj][m][n], 0, 0, 0); __builtin_amdgcn_s_setprio(0); } while (0)
; #define PG8_WAIT_V(n) asm volatile("s_waitcnt vmcnt(" #n ")" ::: "memory")
; #define PG8_WAIT_L(n) asm volatile("s_waitcnt lgkmcnt(" #n ")" ::: "memory")
; #define PG8_BAR __builtin_amdgcn_s_barrier()
; #define PG8_SCHED __builtin_amdgcn_sched_barrier(0)
; template <class Epi, class Sched, bool ALIGN_EPI = false, bool SP2 = false>
; __device__ __forceinline__ void gemm_phase(PG8_LAS unsigned char* lds, const Gemm g, const Sched& S, const Epi& E) {
;     ...
;             PG8_LDB(B0, 1, 0); PG8_LDB(B1, 1, 1); PG8_SCHED; PG8_LDA(At, 1, 0); PG8_STAGE(PG8_SA(0, 1), a2 + hstep, voffA);
;             PG8_WAIT_V(8); PG8_WAIT_L(0); PG8_BAR; PG8_MMA(0, 0, At, B0); PG8_MMA(0, 1, At, B1); PG8_BAR; PG8_SCHED;
	s_add_i32 s58, 0, 0x18000
	v_add_u32_e32 v130, s58, v142
	s_add_i32 s59, 0, 0x1c000
	ds_read_b128 v[136:139], v130
	ds_read_b128 v[146:149], v130 offset:1024
	ds_read_b128 v[150:153], v130 offset:2048
	ds_read_b128 v[154:157], v130 offset:3072
	v_add_u32_e32 v130, s59, v142
	ds_read_b128 v[158:161], v130
	ds_read_b128 v[162:165], v130 offset:1024
	ds_read_b128 v[166:169], v130 offset:2048
	ds_read_b128 v[170:173], v130 offset:3072
	s_mov_b32 m0, s41
	v_lshl_add_u64 v[212:213], v[210:211], 0, s[14:15]
	ds_read_b128 v[174:177], v145 offset:32768
	ds_read_b128 v[178:181], v145 offset:33792
	ds_read_b128 v[182:185], v145 offset:34816
	ds_read_b128 v[186:189], v145 offset:35840
	ds_read_b128 v[190:193], v145 offset:36864
	ds_read_b128 v[194:197], v145 offset:37888
	ds_read_b128 v[202:205], v145 offset:38912
	ds_read_b128 v[206:209], v145 offset:39936
	global_load_lds_dwordx4 v[212:213], off
	v_lshl_add_u64 v[212:213], v[210:211], 0, s[16:17]
	s_mov_b32 m0, s42
	s_nop 0
	global_load_lds_dwordx4 v[212:213], off
	s_waitcnt vmcnt(8)
	s_waitcnt lgkmcnt(0)
	s_barrier
	s_setprio 1
	s_waitcnt lgkmcnt(0)
	v_mfma_f32_16x16x32_bf16 v[124:127], v[136:139], v[174:177], v[124:127]
	v_mfma_f32_16x16x32_bf16 v[120:123], v[150:153], v[174:177], v[120:123]
	v_mfma_f32_16x16x32_bf16 v[108:111], v[136:139], v[182:185], v[108:111]
	v_mfma_f32_16x16x32_bf16 v[104:107], v[150:153], v[182:185], v[104:107]
	v_mfma_f32_16x16x32_bf16 v[92:95], v[136:139], v[190:193], v[92:95]
	v_mfma_f32_16x16x32_bf16 v[88:91], v[150:153], v[190:193], v[88:91]
	v_mfma_f32_16x16x32_bf16 v[76:79], v[136:139], v[202:205], v[76:79]
	v_mfma_f32_16x16x32_bf16 v[72:75], v[150:153], v[202:205], v[72:75]
	v_mfma_f32_16x16x32_bf16 v[124:127], v[146:149], v[178:181], v[124:127]
	v_mfma_f32_16x16x32_bf16 v[120:123], v[154:157], v[178:181], v[120:123]
	v_mfma_f32_16x16x32_bf16 v[108:111], v[146:149], v[186:189], v[108:111]
	v_mfma_f32_16x16x32_bf16 v[104:107], v[154:157], v[186:189], v[104:107]
	v_mfma_f32_16x16x32_bf16 v[92:95], v[146:149], v[194:197], v[92:95]
	v_mfma_f32_16x16x32_bf16 v[88:91], v[154:157], v[194:197], v[88:91]
	v_mfma_f32_16x16x32_bf16 v[76:79], v[146:149], v[206:209], v[76:79]
	v_mfma_f32_16x16x32_bf16 v[72:75], v[154:157], v[206:209], v[72:75]
	v_mfma_f32_16x16x32_bf16 v[116:119], v[158:161], v[174:177], v[116:119]
	v_mfma_f32_16x16x32_bf16 v[112:115], v[166:169], v[174:177], v[112:115]
	v_mfma_f32_16x16x32_bf16 v[100:103], v[158:161], v[182:185], v[100:103]
	v_mfma_f32_16x16x32_bf16 v[96:99], v[166:169], v[182:185], v[96:99]
	v_mfma_f32_16x16x32_bf16 v[84:87], v[158:161], v[190:193], v[84:87]
	v_mfma_f32_16x16x32_bf16 v[80:83], v[166:169], v[190:193], v[80:83]
	v_mfma_f32_16x16x32_bf16 v[68:71], v[158:161], v[202:205], v[68:71]
	v_mfma_f32_16x16x32_bf16 v[64:67], v[166:169], v[202:205], v[64:67]
	v_mfma_f32_16x16x32_bf16 v[116:119], v[162:165], v[178:181], v[116:119]
	v_mfma_f32_16x16x32_bf16 v[112:115], v[170:173], v[178:181], v[112:115]
	v_mfma_f32_16x16x32_bf16 v[100:103], v[162:165], v[186:189], v[100:103]
	v_mfma_f32_16x16x32_bf16 v[96:99], v[170:173], v[186:189], v[96:99]
	v_mfma_f32_16x16x32_bf16 v[84:87], v[162:165], v[194:197], v[84:87]
	v_mfma_f32_16x16x32_bf16 v[80:83], v[170:173], v[194:197], v[80:83]
	v_mfma_f32_16x16x32_bf16 v[68:71], v[162:165], v[206:209], v[68:71]
	v_mfma_f32_16x16x32_bf16 v[64:67], v[170:173], v[206:209], v[64:67]
	s_setprio 0
	s_barrier
; #define PG8_STAGE(bufoff, gbase, voff) do { _Pragma("unroll") for (int _i = 0; _i < 2; ++_i) \
;         __builtin_amdgcn_global_load_lds((const unsigned*)((const char*)(gbase) + (voff)[_i]), (PG8_LAS unsigned*)(lds + (bufoff) + ldsw + _i * 8192), 16, 0, 0); } while (0)
; #define PG8_LDA(dst, b, h) do { _Pragma("unroll") for (int m = 0; m < 4; ++m) _Pragma("unroll") for (int k = 0; k < 2; ++k) dst[m][k] = *(const PG8_LAS bf16x8*)(lds + PG8_SA(b, h) + aoff + m * 2048 + k * 1024); } while (0)
; #define PG8_MMA(ai, bj, At, Bt) do { __builtin_amdgcn_s_setprio(1); _Pragma("unroll") for (int m = 0; m < 4; ++m) _Pragma("unroll") for (int n = 0; n < 2; ++n) _Pragma("unroll") for (int k = 0; k < 2; ++k) \
;         acc[ai][bj][m][n] = __builtin_amdgcn_mfma_f32_16x16x32_bf16(Bt[n][k], At[m][k], acc[ai][bj][m][n], 0, 0, 0); __builtin_amdgcn_s_setprio(0); } while (0)
; #define PG8_WAIT_V(n) asm volatile("s_waitcnt vmcnt(" #n ")" ::: "memory")
; #define PG8_WAIT_L(n) asm volatile("s_waitcnt lgkmcnt(" #n ")" ::: "memory")
; #define PG8_BAR __builtin_amdgcn_s_barrier()
; #define PG8_SCHED __builtin_amdgcn_sched_barrier(0)
; template <class Epi, class Sched, bool ALIGN_EPI = false, bool SP2 = false>
; __device__ __forceinline__ void gemm_phase(PG8_LAS unsigned char* lds, const Gemm g, const Sched& S, const Epi& E) {
;     ...
;             PG8_LDA(At, 1, 1); PG8_STAGE(PG8_SB(1, 0), b3, voffB); PG8_STAGE(PG8_SB(1, 1), b3 + hstep, voffB); PG8_STAGE(PG8_SA(1, 0), a3, voffA);
;             PG8_WAIT_V(8); PG8_WAIT_L(0); PG8_BAR; PG8_MMA(1, 0, At, B0); PG8_MMA(1, 1, At, B1); PG8_BAR; PG8_SCHED;
;     ...
;         if constexpr (ALIGN_EPI) { if (wr == 0) PG8_BAR; }
	s_add_i32 s58, s58, s38
	v_lshl_add_u64 v[212:213], v[198:199], 0, s[20:21]
	s_mov_b32 m0, s58
	ds_read_b128 v[174:177], v145 offset:49152
	ds_read_b128 v[178:181], v145 offset:50176
	ds_read_b128 v[182:185], v145 offset:51200
	ds_read_b128 v[186:189], v145 offset:52224
	ds_read_b128 v[190:193], v145 offset:53248
	ds_read_b128 v[194:197], v145 offset:54272
	ds_read_b128 v[202:205], v145 offset:55296
	ds_read_b128 v[206:209], v145 offset:56320
	global_load_lds_dwordx4 v[212:213], off
	v_lshl_add_u64 v[212:213], v[198:199], 0, s[22:23]
	s_add_i32 m0, s58, 0x2000
	s_add_i32 s58, s59, s38
	global_load_lds_dwordx4 v[212:213], off
	v_lshl_add_u64 v[212:213], v[198:199], 0, s[24:25]
	s_mov_b32 m0, s58
	v_lshl_add_u64 v[198:199], v[198:199], 0, s[26:27]
	global_load_lds_dwordx4 v[212:213], off
	s_add_i32 m0, s58, 0x2000
	s_nop 0
	global_load_lds_dwordx4 v[198:199], off
	v_lshl_add_u64 v[198:199], v[210:211], 0, s[20:21]
	s_mov_b32 m0, s46
	s_nop 0
	global_load_lds_dwordx4 v[198:199], off
	v_lshl_add_u64 v[198:199], v[210:211], 0, s[22:23]
	s_mov_b32 m0, s47
	s_nop 0
	global_load_lds_dwordx4 v[198:199], off
	s_waitcnt vmcnt(8)
	s_waitcnt lgkmcnt(0)
	s_barrier
	s_setprio 1
	s_waitcnt lgkmcnt(0)
	v_mfma_f32_16x16x32_bf16 v[60:63], v[136:139], v[174:177], v[60:63]
	v_mfma_f32_16x16x32_bf16 v[56:59], v[150:153], v[174:177], v[56:59]
	v_mfma_f32_16x16x32_bf16 v[44:47], v[136:139], v[182:185], v[44:47]
	v_mfma_f32_16x16x32_bf16 v[40:43], v[150:153], v[182:185], v[40:43]
	v_mfma_f32_16x16x32_bf16 v[28:31], v[136:139], v[190:193], v[28:31]
	v_mfma_f32_16x16x32_bf16 v[24:27], v[150:153], v[190:193], v[24:27]
	v_mfma_f32_16x16x32_bf16 v[12:15], v[136:139], v[202:205], v[12:15]
	v_mfma_f32_16x16x32_bf16 v[8:11], v[150:153], v[202:205], v[8:11]
	v_mfma_f32_16x16x32_bf16 v[60:63], v[146:149], v[178:181], v[60:63]
	v_mfma_f32_16x16x32_bf16 v[56:59], v[154:157], v[178:181], v[56:59]
	v_mfma_f32_16x16x32_bf16 v[44:47], v[146:149], v[186:189], v[44:47]
	v_mfma_f32_16x16x32_bf16 v[40:43], v[154:157], v[186:189], v[40:43]
	v_mfma_f32_16x16x32_bf16 v[28:31], v[146:149], v[194:197], v[28:31]
	v_mfma_f32_16x16x32_bf16 v[24:27], v[154:157], v[194:197], v[24:27]
	v_mfma_f32_16x16x32_bf16 v[12:15], v[146:149], v[206:209], v[12:15]
	v_mfma_f32_16x16x32_bf16 v[8:11], v[154:157], v[206:209], v[8:11]
	v_mfma_f32_16x16x32_bf16 v[52:55], v[158:161], v[174:177], v[52:55]
	v_mfma_f32_16x16x32_bf16 v[48:51], v[166:169], v[174:177], v[48:51]
	v_mfma_f32_16x16x32_bf16 v[36:39], v[158:161], v[182:185], v[36:39]
	v_mfma_f32_16x16x32_bf16 v[32:35], v[166:169], v[182:185], v[32:35]
	v_mfma_f32_16x16x32_bf16 v[20:23], v[158:161], v[190:193], v[20:23]
	v_mfma_f32_16x16x32_bf16 v[16:19], v[166:169], v[190:193], v[16:19]
	v_mfma_f32_16x16x32_bf16 v[4:7], v[158:161], v[202:205], v[4:7]
	v_mfma_f32_16x16x32_bf16 v[0:3], v[166:169], v[202:205], v[0:3]
	v_mfma_f32_16x16x32_bf16 v[52:55], v[162:165], v[178:181], v[52:55]
	v_mfma_f32_16x16x32_bf16 v[48:51], v[170:173], v[178:181], v[48:51]
	v_mfma_f32_16x16x32_bf16 v[36:39], v[162:165], v[186:189], v[36:39]
	v_mfma_f32_16x16x32_bf16 v[32:35], v[170:173], v[186:189], v[32:35]
	v_mfma_f32_16x16x32_bf16 v[20:23], v[162:165], v[194:197], v[20:23]
	v_mfma_f32_16x16x32_bf16 v[16:19], v[170:173], v[194:197], v[16:19]
	v_mfma_f32_16x16x32_bf16 v[4:7], v[162:165], v[206:209], v[4:7]
	v_mfma_f32_16x16x32_bf16 v[0:3], v[170:173], v[206:209], v[0:3]
	s_setprio 0
	s_barrier
	s_add_i32 s57, s57, 2
	s_add_u32 s12, s12, 0x8000
	s_addc_u32 s13, s13, 0
	s_add_u32 s36, s36, 0x8000
	s_addc_u32 s37, s37, 0
	s_cmp_gt_u32 s57, 41
	s_cbranch_scc0 .LBB0_1424
	s_and_b64 vcc, exec, s[28:29]
	s_cbranch_vccz .LBB0_1427
	s_barrier
